# GEMM K-loops: priority flip pair after every 4 MFMAs
# baseline (speedup 1.0000x reference)
; #define PG8_STAGE(bufoff, gbase, voff) do { _Pragma("unroll") for (int _i = 0; _i < 2; ++_i) \
;         __builtin_amdgcn_global_load_lds((const unsigned*)((const char*)(gbase) + (voff)[_i]), (PG8_LAS unsigned*)(lds + (bufoff) + ldsw + _i * 8192), 16, 0, 0); } while (0)
; #define PG8_LDA(dst, b, h) do { _Pragma("unroll") for (int m = 0; m < 4; ++m) _Pragma("unroll") for (int k = 0; k < 2; ++k) dst[m][k] = *(const PG8_LAS bf16x8*)(lds + PG8_SA(b, h) + aoff + m * 2048 + k * 1024); } while (0)
; #define PG8_LDB(dst, b, h) do { _Pragma("unroll") for (int n = 0; n < 2; ++n) _Pragma("unroll") for (int k = 0; k < 2; ++k) dst[n][k] = *(const PG8_LAS bf16x8*)(lds + PG8_SB(b, h) + boff + n * 2048 + k * 1024); } while (0)
; #define PG8_MMA(ai, bj, At, Bt) do { __builtin_amdgcn_s_setprio(1); _Pragma("unroll") for (int m = 0; m < 4; ++m) _Pragma("unroll") for (int n = 0; n < 2; ++n) _Pragma("unroll") for (int k = 0; k < 2; ++k) \
;         acc[ai][bj][m][n] = __builtin_amdgcn_mfma_f32_16x16x32_bf16(Bt[n][k], At[m][k], acc[ai][bj][m][n], 0, 0, 0); __builtin_amdgcn_s_setprio(0); } while (0)
; #define PG8_WAIT_V(n) asm volatile("s_waitcnt vmcnt(" #n ")" ::: "memory")
; #define PG8_BAR __builtin_amdgcn_s_barrier()
; template <class Epi, class Sched, bool ALIGN_EPI = false, bool SP2 = false>
; __device__ __forceinline__ void gemm_phase(PG8_LAS unsigned char* lds, const Gemm g, const Sched& S, const Epi& E, const int wave0) {
;     ...
;         for (int t = 0; t < nt; t += 2) {
;             const bool last = (t == nt - 2);
;             const char* a1 = cA + (size_t)(t + 1) * kstep;
;             const char* a2 = last ? nA : cA + (size_t)(t + 2) * kstep; const char* b2 = last ? nB : cB + (size_t)(t + 2) * kstep;
;             const char* a3 = a2 + kstep; const char* b3 = b2 + kstep;
;             if (last && has_next) S.a_ready(nxt);
;             if constexpr (SP2) {
;             PG8_LDB(B0, 0, 0); PG8_LDB(B1, 0, 1); PG8_SCHED; PG8_LDA(At, 0, 0); PG8_STAGE(PG8_SA(1, 1), a1 + hstepA, voffA);
;             PG8_WAIT_V(8); PG8_WAIT_L(0); PG8_BAR; PG8_MMA(0, 0, At, B0); PG8_MMA(0, 1, At, B1); PG8_BAR; PG8_SCHED;
;             PG8_LDA(At, 0, 1); PG8_STAGE(PG8_SB(0, 0), b2, voffB); PG8_STAGE(PG8_SB(0, 1), b2 + hstepB, voffB); PG8_STAGE(PG8_SA(0, 0), a2, voffA);
;             PG8_WAIT_V(8); PG8_WAIT_L(0); PG8_BAR; PG8_MMA(1, 0, At, B0); PG8_MMA(1, 1, At, B1); PG8_BAR; PG8_SCHED;
.LBB0_316:
	s_add_u32 s16, s0, 0xfff80080
	s_addc_u32 s17, s1, -1
	s_add_i32 s38, 0, 0x10000
	s_cmp_eq_u32 s37, 28
	s_cselect_b32 s19, s11, s17
	s_cselect_b32 s18, s33, s16
	s_cselect_b32 s17, s9, s36
	s_cselect_b32 s16, s34, s35
	s_add_i32 s40, 0, 0x14000
	ds_read_b128 v[144:147], v252
	ds_read_b128 v[148:151], v252 offset:1024
	ds_read_b128 v[152:155], v252 offset:2048
	ds_read_b128 v[156:159], v252 offset:3072
	ds_read_b128 v[178:181], v253
	ds_read_b128 v[182:185], v253 offset:1024
	ds_read_b128 v[186:189], v253 offset:2048
	ds_read_b128 v[190:193], v253 offset:3072
	s_add_i32 m0, s23, 0xc000
	ds_read_b128 v[194:197], v143
	ds_read_b128 v[208:211], v143 offset:1024
	ds_read_b128 v[212:215], v143 offset:2048
	ds_read_b128 v[216:219], v143 offset:3072
	ds_read_b128 v[220:223], v143 offset:4096
	ds_read_b128 v[224:227], v143 offset:5120
	ds_read_b128 v[228:231], v143 offset:6144
	ds_read_b128 v[232:235], v143 offset:7168
	global_load_lds_dwordx4 v136, s[0:1]
	s_add_i32 m0, s23, 0xe000
	s_nop 0
	global_load_lds_dwordx4 v138, s[0:1]
	s_waitcnt vmcnt(8)
	s_waitcnt lgkmcnt(0)
	s_barrier
	s_setprio 1
	s_waitcnt lgkmcnt(0)
	v_mfma_f32_16x16x32_bf16 v[126:129], v[144:147], v[194:197], v[126:129]
	v_mfma_f32_16x16x32_bf16 v[122:125], v[152:155], v[194:197], v[122:125]
	v_mfma_f32_16x16x32_bf16 v[118:121], v[144:147], v[212:215], v[118:121]
	v_mfma_f32_16x16x32_bf16 v[114:117], v[152:155], v[212:215], v[114:117]
	s_setprio 0
	s_setprio 1
	v_mfma_f32_16x16x32_bf16 v[102:105], v[144:147], v[220:223], v[102:105]
	v_mfma_f32_16x16x32_bf16 v[98:101], v[152:155], v[220:223], v[98:101]
	v_mfma_f32_16x16x32_bf16 v[86:89], v[144:147], v[228:231], v[86:89]
	v_mfma_f32_16x16x32_bf16 v[82:85], v[152:155], v[228:231], v[82:85]
	s_setprio 0
	s_setprio 1
	v_mfma_f32_16x16x32_bf16 v[126:129], v[148:151], v[208:211], v[126:129]
	v_mfma_f32_16x16x32_bf16 v[122:125], v[156:159], v[208:211], v[122:125]
	v_mfma_f32_16x16x32_bf16 v[118:121], v[148:151], v[216:219], v[118:121]
	v_mfma_f32_16x16x32_bf16 v[114:117], v[156:159], v[216:219], v[114:117]
	s_setprio 0
	s_setprio 1
	v_mfma_f32_16x16x32_bf16 v[102:105], v[148:151], v[224:227], v[102:105]
	v_mfma_f32_16x16x32_bf16 v[98:101], v[156:159], v[224:227], v[98:101]
	v_mfma_f32_16x16x32_bf16 v[86:89], v[148:151], v[232:235], v[86:89]
	v_mfma_f32_16x16x32_bf16 v[82:85], v[156:159], v[232:235], v[82:85]
	s_setprio 0
	s_setprio 1
	v_mfma_f32_16x16x32_bf16 v[110:113], v[178:181], v[194:197], v[110:113]
	v_mfma_f32_16x16x32_bf16 v[106:109], v[186:189], v[194:197], v[106:109]
	v_mfma_f32_16x16x32_bf16 v[94:97], v[178:181], v[212:215], v[94:97]
	v_mfma_f32_16x16x32_bf16 v[90:93], v[186:189], v[212:215], v[90:93]
	s_setprio 0
	s_setprio 1
	v_mfma_f32_16x16x32_bf16 v[78:81], v[178:181], v[220:223], v[78:81]
	v_mfma_f32_16x16x32_bf16 v[74:77], v[186:189], v[220:223], v[74:77]
	v_mfma_f32_16x16x32_bf16 v[70:73], v[178:181], v[228:231], v[70:73]
	v_mfma_f32_16x16x32_bf16 v[66:69], v[186:189], v[228:231], v[66:69]
	s_setprio 0
	s_setprio 1
	v_mfma_f32_16x16x32_bf16 v[110:113], v[182:185], v[208:211], v[110:113]
	v_mfma_f32_16x16x32_bf16 v[106:109], v[190:193], v[208:211], v[106:109]
	v_mfma_f32_16x16x32_bf16 v[94:97], v[182:185], v[216:219], v[94:97]
	v_mfma_f32_16x16x32_bf16 v[90:93], v[190:193], v[216:219], v[90:93]
	s_setprio 0
	s_setprio 1
	v_mfma_f32_16x16x32_bf16 v[78:81], v[182:185], v[224:227], v[78:81]
	v_mfma_f32_16x16x32_bf16 v[74:77], v[190:193], v[224:227], v[74:77]
	v_mfma_f32_16x16x32_bf16 v[70:73], v[182:185], v[232:235], v[70:73]
	v_mfma_f32_16x16x32_bf16 v[66:69], v[190:193], v[232:235], v[66:69]
	s_setprio 0
	s_barrier
	s_add_i32 s38, s38, s22
	s_mov_b32 m0, s38
	ds_read_b128 v[194:197], v143 offset:16384
	ds_read_b128 v[208:211], v143 offset:17408
	ds_read_b128 v[212:215], v143 offset:18432
	ds_read_b128 v[216:219], v143 offset:19456
	ds_read_b128 v[220:223], v143 offset:20480
	ds_read_b128 v[224:227], v143 offset:21504
	ds_read_b128 v[228:231], v143 offset:22528
	ds_read_b128 v[232:235], v143 offset:23552
	global_load_lds_dwordx4 v64, s[16:17]
	s_add_i32 m0, s38, 0x2000
	s_add_u32 s38, s16, 0x80000
	s_addc_u32 s39, s17, 0
	s_add_i32 s40, s40, s22
	global_load_lds_dwordx4 v130, s[16:17]
	s_mov_b32 m0, s40
	s_mov_b64 s[100:101], s[18:19]
	global_load_lds_dwordx4 v64, s[38:39]
	s_add_i32 m0, s40, 0x2000
	s_nop 0
	global_load_lds_dwordx4 v130, s[38:39]
	s_mov_b32 m0, s23
	s_nop 0
	global_load_lds_dwordx4 v134, s[18:19]
	s_mov_b32 m0, s24
	s_nop 0
	global_load_lds_dwordx4 v132, s[18:19]
	s_waitcnt vmcnt(8)
	s_waitcnt lgkmcnt(0)
	s_barrier
; #define PG8_STAGE(bufoff, gbase, voff) do { _Pragma("unroll") for (int _i = 0; _i < 2; ++_i) \
;         __builtin_amdgcn_global_load_lds((const unsigned*)((const char*)(gbase) + (voff)[_i]), (PG8_LAS unsigned*)(lds + (bufoff) + ldsw + _i * 8192), 16, 0, 0); } while (0)
; #define PG8_LDA(dst, b, h) do { _Pragma("unroll") for (int m = 0; m < 4; ++m) _Pragma("unroll") for (int k = 0; k < 2; ++k) dst[m][k] = *(const PG8_LAS bf16x8*)(lds + PG8_SA(b, h) + aoff + m * 2048 + k * 1024); } while (0)
; #define PG8_LDB(dst, b, h) do { _Pragma("unroll") for (int n = 0; n < 2; ++n) _Pragma("unroll") for (int k = 0; k < 2; ++k) dst[n][k] = *(const PG8_LAS bf16x8*)(lds + PG8_SB(b, h) + boff + n * 2048 + k * 1024); } while (0)
; #define PG8_MMA(ai, bj, At, Bt) do { __builtin_amdgcn_s_setprio(1); _Pragma("unroll") for (int m = 0; m < 4; ++m) _Pragma("unroll") for (int n = 0; n < 2; ++n) _Pragma("unroll") for (int k = 0; k < 2; ++k) \
;         acc[ai][bj][m][n] = __builtin_amdgcn_mfma_f32_16x16x32_bf16(Bt[n][k], At[m][k], acc[ai][bj][m][n], 0, 0, 0); __builtin_amdgcn_s_setprio(0); } while (0)
; #define PG8_WAIT_V(n) asm volatile("s_waitcnt vmcnt(" #n ")" ::: "memory")
; #define PG8_WAIT_L(n) asm volatile("s_waitcnt lgkmcnt(" #n ")" ::: "memory")
; #define PG8_BAR __builtin_amdgcn_s_barrier()
; #define PG8_SCHED __builtin_amdgcn_sched_barrier(0)
; template <class Epi, class Sched, bool ALIGN_EPI = false, bool SP2 = false>
; __device__ __forceinline__ void gemm_phase(PG8_LAS unsigned char* lds, const Gemm g, const Sched& S, const Epi& E, const int wave0) {
;     ...
;             PG8_WAIT_V(8); PG8_WAIT_L(0); PG8_BAR; PG8_MMA(1, 0, At, B0); PG8_MMA(1, 1, At, B1); PG8_BAR; PG8_SCHED;
;             PG8_LDB(B0, 1, 0); PG8_LDB(B1, 1, 1); PG8_SCHED; PG8_LDA(At, 1, 0); PG8_STAGE(PG8_SA(0, 1), a2 + hstepA, voffA);
;             PG8_WAIT_V(8); PG8_WAIT_L(0); PG8_BAR; PG8_MMA(0, 0, At, B0); PG8_MMA(0, 1, At, B1); PG8_BAR; PG8_SCHED;
	s_setprio 1
	s_waitcnt lgkmcnt(0)
	v_mfma_f32_16x16x32_bf16 v[60:63], v[144:147], v[194:197], v[60:63]
	v_mfma_f32_16x16x32_bf16 v[56:59], v[152:155], v[194:197], v[56:59]
	v_mfma_f32_16x16x32_bf16 v[52:55], v[144:147], v[212:215], v[52:55]
	v_mfma_f32_16x16x32_bf16 v[48:51], v[152:155], v[212:215], v[48:51]
	s_setprio 0
	s_setprio 1
	v_mfma_f32_16x16x32_bf16 v[36:39], v[144:147], v[220:223], v[36:39]
	v_mfma_f32_16x16x32_bf16 v[32:35], v[152:155], v[220:223], v[32:35]
	v_mfma_f32_16x16x32_bf16 v[20:23], v[144:147], v[228:231], v[20:23]
	v_mfma_f32_16x16x32_bf16 v[16:19], v[152:155], v[228:231], v[16:19]
	s_setprio 0
	s_setprio 1
	v_mfma_f32_16x16x32_bf16 v[60:63], v[148:151], v[208:211], v[60:63]
	v_mfma_f32_16x16x32_bf16 v[56:59], v[156:159], v[208:211], v[56:59]
	v_mfma_f32_16x16x32_bf16 v[52:55], v[148:151], v[216:219], v[52:55]
	v_mfma_f32_16x16x32_bf16 v[48:51], v[156:159], v[216:219], v[48:51]
	s_setprio 0
	s_setprio 1
	v_mfma_f32_16x16x32_bf16 v[36:39], v[148:151], v[224:227], v[36:39]
	v_mfma_f32_16x16x32_bf16 v[32:35], v[156:159], v[224:227], v[32:35]
	v_mfma_f32_16x16x32_bf16 v[20:23], v[148:151], v[232:235], v[20:23]
	v_mfma_f32_16x16x32_bf16 v[16:19], v[156:159], v[232:235], v[16:19]
	s_setprio 0
	s_setprio 1
	v_mfma_f32_16x16x32_bf16 v[44:47], v[178:181], v[194:197], v[44:47]
	v_mfma_f32_16x16x32_bf16 v[40:43], v[186:189], v[194:197], v[40:43]
	v_mfma_f32_16x16x32_bf16 v[28:31], v[178:181], v[212:215], v[28:31]
	v_mfma_f32_16x16x32_bf16 v[24:27], v[186:189], v[212:215], v[24:27]
	s_setprio 0
	s_setprio 1
	v_mfma_f32_16x16x32_bf16 v[12:15], v[178:181], v[220:223], v[12:15]
	v_mfma_f32_16x16x32_bf16 v[8:11], v[186:189], v[220:223], v[8:11]
	v_mfma_f32_16x16x32_bf16 v[4:7], v[178:181], v[228:231], v[4:7]
	v_mfma_f32_16x16x32_bf16 v[0:3], v[186:189], v[228:231], v[0:3]
	s_setprio 0
	s_setprio 1
	v_mfma_f32_16x16x32_bf16 v[44:47], v[182:185], v[208:211], v[44:47]
	v_mfma_f32_16x16x32_bf16 v[40:43], v[190:193], v[208:211], v[40:43]
	v_mfma_f32_16x16x32_bf16 v[28:31], v[182:185], v[216:219], v[28:31]
	v_mfma_f32_16x16x32_bf16 v[24:27], v[190:193], v[216:219], v[24:27]
	s_setprio 0
	s_setprio 1
	v_mfma_f32_16x16x32_bf16 v[12:15], v[182:185], v[224:227], v[12:15]
	v_mfma_f32_16x16x32_bf16 v[8:11], v[190:193], v[224:227], v[8:11]
	v_mfma_f32_16x16x32_bf16 v[4:7], v[182:185], v[232:235], v[4:7]
	v_mfma_f32_16x16x32_bf16 v[0:3], v[190:193], v[232:235], v[0:3]
	s_setprio 0
	s_barrier
	s_add_i32 s38, 0, 0x18000
	s_add_i32 s39, 0, 0x1c000
	ds_read_b128 v[144:147], v254
	ds_read_b128 v[148:151], v254 offset:1024
	ds_read_b128 v[152:155], v254 offset:2048
	ds_read_b128 v[156:159], v254 offset:3072
	ds_read_b128 v[178:181], v255
	ds_read_b128 v[182:185], v255 offset:1024
	ds_read_b128 v[186:189], v255 offset:2048
	ds_read_b128 v[190:193], v255 offset:3072
	s_add_u32 s18, s18, 0x80000
	s_addc_u32 s19, s19, 0
	s_mov_b32 m0, s25
	ds_read_b128 v[194:197], v143 offset:32768
	ds_read_b128 v[208:211], v143 offset:33792
	ds_read_b128 v[212:215], v143 offset:34816
	ds_read_b128 v[216:219], v143 offset:35840
	ds_read_b128 v[220:223], v143 offset:36864
	ds_read_b128 v[224:227], v143 offset:37888
	ds_read_b128 v[228:231], v143 offset:38912
	ds_read_b128 v[232:235], v143 offset:39936
	global_load_lds_dwordx4 v134, s[18:19]
	s_mov_b32 m0, s26
	s_nop 0
	global_load_lds_dwordx4 v132, s[18:19]
	s_waitcnt vmcnt(8)
	s_waitcnt lgkmcnt(0)
	s_barrier
	s_setprio 1
	s_waitcnt lgkmcnt(0)
	v_mfma_f32_16x16x32_bf16 v[126:129], v[144:147], v[194:197], v[126:129]
	v_mfma_f32_16x16x32_bf16 v[122:125], v[152:155], v[194:197], v[122:125]
	v_mfma_f32_16x16x32_bf16 v[118:121], v[144:147], v[212:215], v[118:121]
	v_mfma_f32_16x16x32_bf16 v[114:117], v[152:155], v[212:215], v[114:117]
	s_setprio 0
	s_setprio 1
	v_mfma_f32_16x16x32_bf16 v[102:105], v[144:147], v[220:223], v[102:105]
	v_mfma_f32_16x16x32_bf16 v[98:101], v[152:155], v[220:223], v[98:101]
	v_mfma_f32_16x16x32_bf16 v[86:89], v[144:147], v[228:231], v[86:89]
	v_mfma_f32_16x16x32_bf16 v[82:85], v[152:155], v[228:231], v[82:85]
	s_setprio 0
	s_setprio 1
	v_mfma_f32_16x16x32_bf16 v[126:129], v[148:151], v[208:211], v[126:129]
	v_mfma_f32_16x16x32_bf16 v[122:125], v[156:159], v[208:211], v[122:125]
	v_mfma_f32_16x16x32_bf16 v[118:121], v[148:151], v[216:219], v[118:121]
	v_mfma_f32_16x16x32_bf16 v[114:117], v[156:159], v[216:219], v[114:117]
	s_setprio 0
	s_setprio 1
	v_mfma_f32_16x16x32_bf16 v[102:105], v[148:151], v[224:227], v[102:105]
	v_mfma_f32_16x16x32_bf16 v[98:101], v[156:159], v[224:227], v[98:101]
	v_mfma_f32_16x16x32_bf16 v[86:89], v[148:151], v[232:235], v[86:89]
	v_mfma_f32_16x16x32_bf16 v[82:85], v[156:159], v[232:235], v[82:85]
	s_setprio 0
	s_setprio 1
	v_mfma_f32_16x16x32_bf16 v[110:113], v[178:181], v[194:197], v[110:113]
	v_mfma_f32_16x16x32_bf16 v[106:109], v[186:189], v[194:197], v[106:109]
	v_mfma_f32_16x16x32_bf16 v[94:97], v[178:181], v[212:215], v[94:97]
	v_mfma_f32_16x16x32_bf16 v[90:93], v[186:189], v[212:215], v[90:93]
	s_setprio 0
	s_setprio 1
	v_mfma_f32_16x16x32_bf16 v[78:81], v[178:181], v[220:223], v[78:81]
	v_mfma_f32_16x16x32_bf16 v[74:77], v[186:189], v[220:223], v[74:77]
	v_mfma_f32_16x16x32_bf16 v[70:73], v[178:181], v[228:231], v[70:73]
	v_mfma_f32_16x16x32_bf16 v[66:69], v[186:189], v[228:231], v[66:69]
	s_setprio 0
	s_setprio 1
	v_mfma_f32_16x16x32_bf16 v[110:113], v[182:185], v[208:211], v[110:113]
	v_mfma_f32_16x16x32_bf16 v[106:109], v[190:193], v[208:211], v[106:109]
	v_mfma_f32_16x16x32_bf16 v[94:97], v[182:185], v[216:219], v[94:97]
	v_mfma_f32_16x16x32_bf16 v[90:93], v[190:193], v[216:219], v[90:93]
	s_setprio 0
	s_setprio 1
	v_mfma_f32_16x16x32_bf16 v[78:81], v[182:185], v[224:227], v[78:81]
	v_mfma_f32_16x16x32_bf16 v[74:77], v[190:193], v[224:227], v[74:77]
	v_mfma_f32_16x16x32_bf16 v[70:73], v[182:185], v[232:235], v[70:73]
	v_mfma_f32_16x16x32_bf16 v[66:69], v[190:193], v[232:235], v[66:69]
	s_setprio 0
	s_barrier
; #define PG8_STAGE(bufoff, gbase, voff) do { _Pragma("unroll") for (int _i = 0; _i < 2; ++_i) \
;         __builtin_amdgcn_global_load_lds((const unsigned*)((const char*)(gbase) + (voff)[_i]), (PG8_LAS unsigned*)(lds + (bufoff) + ldsw + _i * 8192), 16, 0, 0); } while (0)
; #define PG8_LDA(dst, b, h) do { _Pragma("unroll") for (int m = 0; m < 4; ++m) _Pragma("unroll") for (int k = 0; k < 2; ++k) dst[m][k] = *(const PG8_LAS bf16x8*)(lds + PG8_SA(b, h) + aoff + m * 2048 + k * 1024); } while (0)
; #define PG8_MMA(ai, bj, At, Bt) do { __builtin_amdgcn_s_setprio(1); _Pragma("unroll") for (int m = 0; m < 4; ++m) _Pragma("unroll") for (int n = 0; n < 2; ++n) _Pragma("unroll") for (int k = 0; k < 2; ++k) \
;         acc[ai][bj][m][n] = __builtin_amdgcn_mfma_f32_16x16x32_bf16(Bt[n][k], At[m][k], acc[ai][bj][m][n], 0, 0, 0); __builtin_amdgcn_s_setprio(0); } while (0)
; #define PG8_WAIT_V(n) asm volatile("s_waitcnt vmcnt(" #n ")" ::: "memory")
; #define PG8_WAIT_L(n) asm volatile("s_waitcnt lgkmcnt(" #n ")" ::: "memory")
; #define PG8_BAR __builtin_amdgcn_s_barrier()
; #define PG8_SCHED __builtin_amdgcn_sched_barrier(0)
; template <class Epi, class Sched, bool ALIGN_EPI = false, bool SP2 = false>
; __device__ __forceinline__ void gemm_phase(PG8_LAS unsigned char* lds, const Gemm g, const Sched& S, const Epi& E, const int wave0) {
;     ...
;             PG8_LDA(At, 1, 1); PG8_STAGE(PG8_SB(1, 0), b3, voffB); PG8_STAGE(PG8_SB(1, 1), b3 + hstepB, voffB); PG8_STAGE(PG8_SA(1, 0), a3, voffA);
;             PG8_WAIT_V(8); PG8_WAIT_L(0); PG8_BAR; PG8_MMA(1, 0, At, B0); PG8_MMA(1, 1, At, B1); PG8_BAR; PG8_SCHED;
;     ...
;         if constexpr (ALIGN_EPI) { if (wr == 0) PG8_BAR; }
	s_add_i32 s18, s38, s22
	s_add_u32 s42, s16, 0x80
	s_addc_u32 s43, s17, 0
	s_mov_b32 m0, s18
	ds_read_b128 v[194:197], v143 offset:49152
	ds_read_b128 v[208:211], v143 offset:50176
	ds_read_b128 v[212:215], v143 offset:51200
	ds_read_b128 v[216:219], v143 offset:52224
	ds_read_b128 v[220:223], v143 offset:53248
	ds_read_b128 v[224:227], v143 offset:54272
	ds_read_b128 v[228:231], v143 offset:55296
	ds_read_b128 v[232:235], v143 offset:56320
	global_load_lds_dwordx4 v64, s[42:43]
	s_add_i32 m0, s18, 0x2000
	s_add_u32 s16, s16, 0x80080
	s_addc_u32 s17, s17, 0
	s_add_i32 s18, s39, s22
	global_load_lds_dwordx4 v130, s[42:43]
	s_mov_b32 m0, s18
	s_nop 0
	global_load_lds_dwordx4 v64, s[16:17]
	s_add_i32 m0, s18, 0x2000
	s_nop 0
	global_load_lds_dwordx4 v130, s[16:17]
	s_add_u32 s100, s100, 0x80
	s_addc_u32 s101, s101, 0
	s_mov_b32 m0, s27
	s_nop 0
	global_load_lds_dwordx4 v134, s[100:101]
	s_mov_b32 m0, s28
	s_nop 0
	global_load_lds_dwordx4 v132, s[100:101]
	s_waitcnt vmcnt(8)
	s_waitcnt lgkmcnt(0)
	s_barrier
	s_setprio 1
	s_waitcnt lgkmcnt(0)
	v_mfma_f32_16x16x32_bf16 v[60:63], v[144:147], v[194:197], v[60:63]
	v_mfma_f32_16x16x32_bf16 v[56:59], v[152:155], v[194:197], v[56:59]
	v_mfma_f32_16x16x32_bf16 v[52:55], v[144:147], v[212:215], v[52:55]
	v_mfma_f32_16x16x32_bf16 v[48:51], v[152:155], v[212:215], v[48:51]
	s_setprio 0
	s_setprio 1
	v_mfma_f32_16x16x32_bf16 v[36:39], v[144:147], v[220:223], v[36:39]
	v_mfma_f32_16x16x32_bf16 v[32:35], v[152:155], v[220:223], v[32:35]
	v_mfma_f32_16x16x32_bf16 v[20:23], v[144:147], v[228:231], v[20:23]
	v_mfma_f32_16x16x32_bf16 v[16:19], v[152:155], v[228:231], v[16:19]
	s_setprio 0
	s_setprio 1
	v_mfma_f32_16x16x32_bf16 v[60:63], v[148:151], v[208:211], v[60:63]
	v_mfma_f32_16x16x32_bf16 v[56:59], v[156:159], v[208:211], v[56:59]
	v_mfma_f32_16x16x32_bf16 v[52:55], v[148:151], v[216:219], v[52:55]
	v_mfma_f32_16x16x32_bf16 v[48:51], v[156:159], v[216:219], v[48:51]
	s_setprio 0
	s_setprio 1
	v_mfma_f32_16x16x32_bf16 v[36:39], v[148:151], v[224:227], v[36:39]
	v_mfma_f32_16x16x32_bf16 v[32:35], v[156:159], v[224:227], v[32:35]
	v_mfma_f32_16x16x32_bf16 v[20:23], v[148:151], v[232:235], v[20:23]
	v_mfma_f32_16x16x32_bf16 v[16:19], v[156:159], v[232:235], v[16:19]
	s_setprio 0
	s_setprio 1
	v_mfma_f32_16x16x32_bf16 v[44:47], v[178:181], v[194:197], v[44:47]
	v_mfma_f32_16x16x32_bf16 v[40:43], v[186:189], v[194:197], v[40:43]
	v_mfma_f32_16x16x32_bf16 v[28:31], v[178:181], v[212:215], v[28:31]
	v_mfma_f32_16x16x32_bf16 v[24:27], v[186:189], v[212:215], v[24:27]
	s_setprio 0
	s_setprio 1
	v_mfma_f32_16x16x32_bf16 v[12:15], v[178:181], v[220:223], v[12:15]
	v_mfma_f32_16x16x32_bf16 v[8:11], v[186:189], v[220:223], v[8:11]
	v_mfma_f32_16x16x32_bf16 v[4:7], v[178:181], v[228:231], v[4:7]
	v_mfma_f32_16x16x32_bf16 v[0:3], v[186:189], v[228:231], v[0:3]
	s_setprio 0
	s_setprio 1
	v_mfma_f32_16x16x32_bf16 v[44:47], v[182:185], v[208:211], v[44:47]
	v_mfma_f32_16x16x32_bf16 v[40:43], v[190:193], v[208:211], v[40:43]
	v_mfma_f32_16x16x32_bf16 v[28:31], v[182:185], v[216:219], v[28:31]
	v_mfma_f32_16x16x32_bf16 v[24:27], v[190:193], v[216:219], v[24:27]
	s_setprio 0
	s_setprio 1
	v_mfma_f32_16x16x32_bf16 v[12:15], v[182:185], v[224:227], v[12:15]
	v_mfma_f32_16x16x32_bf16 v[8:11], v[190:193], v[224:227], v[8:11]
	v_mfma_f32_16x16x32_bf16 v[4:7], v[182:185], v[232:235], v[4:7]
	v_mfma_f32_16x16x32_bf16 v[0:3], v[190:193], v[232:235], v[0:3]
	s_setprio 0
	s_barrier
	s_add_i32 s37, s37, 2
	s_add_u32 s0, s0, 0x100
	s_addc_u32 s1, s1, 0
	s_add_u32 s35, s35, 0x100
	s_addc_u32 s36, s36, 0
	s_cmp_gt_u32 s37, 29
	s_cbranch_scc0 .LBB0_316
	s_mov_b64 s[42:43], 0x80
	s_and_b64 vcc, exec, s[6:7]
	s_mov_b64 s[34:35], 0x45000
	s_cbranch_vccz .LBB0_319
	s_barrier

; #define PG8_STAGE(bufoff, gbase, voff) do { _Pragma("unroll") for (int _i = 0; _i < 2; ++_i) \
;         __builtin_amdgcn_global_load_lds((const unsigned*)((const char*)(gbase) + (voff)[_i]), (PG8_LAS unsigned*)(lds + (bufoff) + ldsw + _i * 8192), 16, 0, 0); } while (0)
; #define PG8_LDA(dst, b, h) do { _Pragma("unroll") for (int m = 0; m < 4; ++m) _Pragma("unroll") for (int k = 0; k < 2; ++k) dst[m][k] = *(const PG8_LAS bf16x8*)(lds + PG8_SA(b, h) + aoff + m * 2048 + k * 1024); } while (0)
; #define PG8_LDB(dst, b, h) do { _Pragma("unroll") for (int n = 0; n < 2; ++n) _Pragma("unroll") for (int k = 0; k < 2; ++k) dst[n][k] = *(const PG8_LAS bf16x8*)(lds + PG8_SB(b, h) + boff + n * 2048 + k * 1024); } while (0)
; #define PG8_MMA(ai, bj, At, Bt) do { __builtin_amdgcn_s_setprio(1); _Pragma("unroll") for (int m = 0; m < 4; ++m) _Pragma("unroll") for (int n = 0; n < 2; ++n) _Pragma("unroll") for (int k = 0; k < 2; ++k) \
;         acc[ai][bj][m][n] = __builtin_amdgcn_mfma_f32_16x16x32_bf16(Bt[n][k], At[m][k], acc[ai][bj][m][n], 0, 0, 0); __builtin_amdgcn_s_setprio(0); } while (0)
; #define PG8_WAIT_V(n) asm volatile("s_waitcnt vmcnt(" #n ")" ::: "memory")
; #define PG8_BAR __builtin_amdgcn_s_barrier()
; template <class Epi, class Sched, bool ALIGN_EPI = false, bool SP2 = false>
; __device__ __forceinline__ void gemm_phase(PG8_LAS unsigned char* lds, const Gemm g, const Sched& S, const Epi& E, const int wave0) {
;     ...
;         for (int t = 0; t < nt; t += 2) {
;             const bool last = (t == nt - 2);
;             const char* a1 = cA + (size_t)(t + 1) * kstep;
;             const char* a2 = last ? nA : cA + (size_t)(t + 2) * kstep; const char* b2 = last ? nB : cB + (size_t)(t + 2) * kstep;
;             const char* a3 = a2 + kstep; const char* b3 = b2 + kstep;
;             if (last && has_next) S.a_ready(nxt);
;             if constexpr (SP2) {
;             PG8_LDB(B0, 0, 0); PG8_LDB(B1, 0, 1); PG8_SCHED; PG8_LDA(At, 0, 0); PG8_STAGE(PG8_SA(1, 1), a1 + hstepA, voffA);
;             PG8_WAIT_V(8); PG8_WAIT_L(0); PG8_BAR; PG8_MMA(0, 0, At, B0); PG8_MMA(0, 1, At, B1); PG8_BAR; PG8_SCHED;
;             PG8_LDA(At, 0, 1); PG8_STAGE(PG8_SB(0, 0), b2, voffB); PG8_STAGE(PG8_SB(0, 1), b2 + hstepB, voffB); PG8_STAGE(PG8_SA(0, 0), a2, voffA);
;             PG8_WAIT_V(8); PG8_WAIT_L(0); PG8_BAR; PG8_MMA(1, 0, At, B0); PG8_MMA(1, 1, At, B1); PG8_BAR; PG8_SCHED;
.LBB0_1178:
	s_add_u32 s2, s0, 0xfffc0080
	s_addc_u32 s3, s1, -1
	s_add_i32 s31, 0, 0x10000
	s_cmp_eq_u32 s19, 12
	s_cselect_b32 s17, s45, s3
	s_cselect_b32 s16, s44, s2
	s_cselect_b32 s3, s9, s18
	s_cselect_b32 s2, s11, s13
	s_add_i32 s33, 0, 0x14000
	ds_read_b128 v[130:133], v252
	ds_read_b128 v[134:137], v252 offset:1024
	ds_read_b128 v[148:151], v252 offset:2048
	ds_read_b128 v[152:155], v252 offset:3072
	ds_read_b128 v[178:181], v253
	ds_read_b128 v[182:185], v253 offset:1024
	ds_read_b128 v[186:189], v253 offset:2048
	ds_read_b128 v[190:193], v253 offset:3072
	s_add_i32 m0, s23, 0xc000
	ds_read_b128 v[194:197], v159
	ds_read_b128 v[208:211], v159 offset:1024
	ds_read_b128 v[212:215], v159 offset:2048
	ds_read_b128 v[216:219], v159 offset:3072
	ds_read_b128 v[220:223], v159 offset:4096
	ds_read_b128 v[224:227], v159 offset:5120
	ds_read_b128 v[228:231], v159 offset:6144
	ds_read_b128 v[232:235], v159 offset:7168
	global_load_lds_dwordx4 v144, s[0:1]
	s_add_i32 m0, s23, 0xe000
	s_nop 0
	global_load_lds_dwordx4 v146, s[0:1]
	s_waitcnt vmcnt(8)
	s_waitcnt lgkmcnt(0)
	s_barrier
	s_setprio 1
	s_waitcnt lgkmcnt(0)
	v_mfma_f32_16x16x32_bf16 v[126:129], v[130:133], v[194:197], v[126:129]
	v_mfma_f32_16x16x32_bf16 v[122:125], v[148:151], v[194:197], v[122:125]
	v_mfma_f32_16x16x32_bf16 v[110:113], v[130:133], v[212:215], v[110:113]
	v_mfma_f32_16x16x32_bf16 v[106:109], v[148:151], v[212:215], v[106:109]
	s_setprio 0
	s_setprio 1
	v_mfma_f32_16x16x32_bf16 v[94:97], v[130:133], v[220:223], v[94:97]
	v_mfma_f32_16x16x32_bf16 v[90:93], v[148:151], v[220:223], v[90:93]
	v_mfma_f32_16x16x32_bf16 v[78:81], v[130:133], v[228:231], v[78:81]
	v_mfma_f32_16x16x32_bf16 v[74:77], v[148:151], v[228:231], v[74:77]
	s_setprio 0
	s_setprio 1
	v_mfma_f32_16x16x32_bf16 v[126:129], v[134:137], v[208:211], v[126:129]
	v_mfma_f32_16x16x32_bf16 v[122:125], v[152:155], v[208:211], v[122:125]
	v_mfma_f32_16x16x32_bf16 v[110:113], v[134:137], v[216:219], v[110:113]
	v_mfma_f32_16x16x32_bf16 v[106:109], v[152:155], v[216:219], v[106:109]
	s_setprio 0
	s_setprio 1
	v_mfma_f32_16x16x32_bf16 v[94:97], v[134:137], v[224:227], v[94:97]
	v_mfma_f32_16x16x32_bf16 v[90:93], v[152:155], v[224:227], v[90:93]
	v_mfma_f32_16x16x32_bf16 v[78:81], v[134:137], v[232:235], v[78:81]
	v_mfma_f32_16x16x32_bf16 v[74:77], v[152:155], v[232:235], v[74:77]
	s_setprio 0
	s_setprio 1
	v_mfma_f32_16x16x32_bf16 v[118:121], v[178:181], v[194:197], v[118:121]
	v_mfma_f32_16x16x32_bf16 v[114:117], v[186:189], v[194:197], v[114:117]
	v_mfma_f32_16x16x32_bf16 v[102:105], v[178:181], v[212:215], v[102:105]
	v_mfma_f32_16x16x32_bf16 v[98:101], v[186:189], v[212:215], v[98:101]
	s_setprio 0
	s_setprio 1
	v_mfma_f32_16x16x32_bf16 v[86:89], v[178:181], v[220:223], v[86:89]
	v_mfma_f32_16x16x32_bf16 v[82:85], v[186:189], v[220:223], v[82:85]
	v_mfma_f32_16x16x32_bf16 v[70:73], v[178:181], v[228:231], v[70:73]
	v_mfma_f32_16x16x32_bf16 v[66:69], v[186:189], v[228:231], v[66:69]
	s_setprio 0
	s_setprio 1
	v_mfma_f32_16x16x32_bf16 v[118:121], v[182:185], v[208:211], v[118:121]
	v_mfma_f32_16x16x32_bf16 v[114:117], v[190:193], v[208:211], v[114:117]
	v_mfma_f32_16x16x32_bf16 v[102:105], v[182:185], v[216:219], v[102:105]
	v_mfma_f32_16x16x32_bf16 v[98:101], v[190:193], v[216:219], v[98:101]
	s_setprio 0
	s_setprio 1
	v_mfma_f32_16x16x32_bf16 v[86:89], v[182:185], v[224:227], v[86:89]
	v_mfma_f32_16x16x32_bf16 v[82:85], v[190:193], v[224:227], v[82:85]
	v_mfma_f32_16x16x32_bf16 v[70:73], v[182:185], v[232:235], v[70:73]
	v_mfma_f32_16x16x32_bf16 v[66:69], v[190:193], v[232:235], v[66:69]
	s_setprio 0
	s_barrier
	s_add_i32 s31, s31, s22
	s_mov_b32 m0, s31
	ds_read_b128 v[194:197], v159 offset:16384
	ds_read_b128 v[208:211], v159 offset:17408
	ds_read_b128 v[212:215], v159 offset:18432
	ds_read_b128 v[216:219], v159 offset:19456
	ds_read_b128 v[220:223], v159 offset:20480
	ds_read_b128 v[224:227], v159 offset:21504
	ds_read_b128 v[228:231], v159 offset:22528
	ds_read_b128 v[232:235], v159 offset:23552
	global_load_lds_dwordx4 v64, s[2:3]
	s_add_i32 m0, s31, 0x2000
	s_add_u32 s34, s2, 0x40000
	s_addc_u32 s35, s3, 0
	s_add_i32 s31, s33, s22
	global_load_lds_dwordx4 v138, s[2:3]
	s_mov_b32 m0, s31
	s_mov_b64 s[100:101], s[16:17]
	global_load_lds_dwordx4 v64, s[34:35]
	s_add_i32 m0, s31, 0x2000
	s_nop 0
	global_load_lds_dwordx4 v138, s[34:35]
	s_mov_b32 m0, s23
	s_nop 0
	global_load_lds_dwordx4 v142, s[16:17]
	s_mov_b32 m0, s24
	s_nop 0
	global_load_lds_dwordx4 v140, s[16:17]
	s_waitcnt vmcnt(8)
	s_waitcnt lgkmcnt(0)
	s_barrier
; #define PG8_STAGE(bufoff, gbase, voff) do { _Pragma("unroll") for (int _i = 0; _i < 2; ++_i) \
;         __builtin_amdgcn_global_load_lds((const unsigned*)((const char*)(gbase) + (voff)[_i]), (PG8_LAS unsigned*)(lds + (bufoff) + ldsw + _i * 8192), 16, 0, 0); } while (0)
; #define PG8_LDA(dst, b, h) do { _Pragma("unroll") for (int m = 0; m < 4; ++m) _Pragma("unroll") for (int k = 0; k < 2; ++k) dst[m][k] = *(const PG8_LAS bf16x8*)(lds + PG8_SA(b, h) + aoff + m * 2048 + k * 1024); } while (0)
; #define PG8_LDB(dst, b, h) do { _Pragma("unroll") for (int n = 0; n < 2; ++n) _Pragma("unroll") for (int k = 0; k < 2; ++k) dst[n][k] = *(const PG8_LAS bf16x8*)(lds + PG8_SB(b, h) + boff + n * 2048 + k * 1024); } while (0)
; #define PG8_MMA(ai, bj, At, Bt) do { __builtin_amdgcn_s_setprio(1); _Pragma("unroll") for (int m = 0; m < 4; ++m) _Pragma("unroll") for (int n = 0; n < 2; ++n) _Pragma("unroll") for (int k = 0; k < 2; ++k) \
;         acc[ai][bj][m][n] = __builtin_amdgcn_mfma_f32_16x16x32_bf16(Bt[n][k], At[m][k], acc[ai][bj][m][n], 0, 0, 0); __builtin_amdgcn_s_setprio(0); } while (0)
; #define PG8_WAIT_V(n) asm volatile("s_waitcnt vmcnt(" #n ")" ::: "memory")
; #define PG8_WAIT_L(n) asm volatile("s_waitcnt lgkmcnt(" #n ")" ::: "memory")
; #define PG8_BAR __builtin_amdgcn_s_barrier()
; #define PG8_SCHED __builtin_amdgcn_sched_barrier(0)
; template <class Epi, class Sched, bool ALIGN_EPI = false, bool SP2 = false>
; __device__ __forceinline__ void gemm_phase(PG8_LAS unsigned char* lds, const Gemm g, const Sched& S, const Epi& E, const int wave0) {
;     ...
;             PG8_WAIT_V(8); PG8_WAIT_L(0); PG8_BAR; PG8_MMA(1, 0, At, B0); PG8_MMA(1, 1, At, B1); PG8_BAR; PG8_SCHED;
;             PG8_LDB(B0, 1, 0); PG8_LDB(B1, 1, 1); PG8_SCHED; PG8_LDA(At, 1, 0); PG8_STAGE(PG8_SA(0, 1), a2 + hstepA, voffA);
;             PG8_WAIT_V(8); PG8_WAIT_L(0); PG8_BAR; PG8_MMA(0, 0, At, B0); PG8_MMA(0, 1, At, B1); PG8_BAR; PG8_SCHED;
	s_setprio 1
	s_waitcnt lgkmcnt(0)
	v_mfma_f32_16x16x32_bf16 v[60:63], v[130:133], v[194:197], v[60:63]
	v_mfma_f32_16x16x32_bf16 v[56:59], v[148:151], v[194:197], v[56:59]
	v_mfma_f32_16x16x32_bf16 v[44:47], v[130:133], v[212:215], v[44:47]
	v_mfma_f32_16x16x32_bf16 v[40:43], v[148:151], v[212:215], v[40:43]
	s_setprio 0
	s_setprio 1
	v_mfma_f32_16x16x32_bf16 v[28:31], v[130:133], v[220:223], v[28:31]
	v_mfma_f32_16x16x32_bf16 v[24:27], v[148:151], v[220:223], v[24:27]
	v_mfma_f32_16x16x32_bf16 v[12:15], v[130:133], v[228:231], v[12:15]
	v_mfma_f32_16x16x32_bf16 v[8:11], v[148:151], v[228:231], v[8:11]
	s_setprio 0
	s_setprio 1
	v_mfma_f32_16x16x32_bf16 v[60:63], v[134:137], v[208:211], v[60:63]
	v_mfma_f32_16x16x32_bf16 v[56:59], v[152:155], v[208:211], v[56:59]
	v_mfma_f32_16x16x32_bf16 v[44:47], v[134:137], v[216:219], v[44:47]
	v_mfma_f32_16x16x32_bf16 v[40:43], v[152:155], v[216:219], v[40:43]
	s_setprio 0
	s_setprio 1
	v_mfma_f32_16x16x32_bf16 v[28:31], v[134:137], v[224:227], v[28:31]
	v_mfma_f32_16x16x32_bf16 v[24:27], v[152:155], v[224:227], v[24:27]
	v_mfma_f32_16x16x32_bf16 v[12:15], v[134:137], v[232:235], v[12:15]
	v_mfma_f32_16x16x32_bf16 v[8:11], v[152:155], v[232:235], v[8:11]
	s_setprio 0
	s_setprio 1
	v_mfma_f32_16x16x32_bf16 v[52:55], v[178:181], v[194:197], v[52:55]
	v_mfma_f32_16x16x32_bf16 v[48:51], v[186:189], v[194:197], v[48:51]
	v_mfma_f32_16x16x32_bf16 v[36:39], v[178:181], v[212:215], v[36:39]
	v_mfma_f32_16x16x32_bf16 v[32:35], v[186:189], v[212:215], v[32:35]
	s_setprio 0
	s_setprio 1
	v_mfma_f32_16x16x32_bf16 v[20:23], v[178:181], v[220:223], v[20:23]
	v_mfma_f32_16x16x32_bf16 v[16:19], v[186:189], v[220:223], v[16:19]
	v_mfma_f32_16x16x32_bf16 v[4:7], v[178:181], v[228:231], v[4:7]
	v_mfma_f32_16x16x32_bf16 v[0:3], v[186:189], v[228:231], v[0:3]
	s_setprio 0
	s_setprio 1
	v_mfma_f32_16x16x32_bf16 v[52:55], v[182:185], v[208:211], v[52:55]
	v_mfma_f32_16x16x32_bf16 v[48:51], v[190:193], v[208:211], v[48:51]
	v_mfma_f32_16x16x32_bf16 v[36:39], v[182:185], v[216:219], v[36:39]
	v_mfma_f32_16x16x32_bf16 v[32:35], v[190:193], v[216:219], v[32:35]
	s_setprio 0
	s_setprio 1
	v_mfma_f32_16x16x32_bf16 v[20:23], v[182:185], v[224:227], v[20:23]
	v_mfma_f32_16x16x32_bf16 v[16:19], v[190:193], v[224:227], v[16:19]
	v_mfma_f32_16x16x32_bf16 v[4:7], v[182:185], v[232:235], v[4:7]
	v_mfma_f32_16x16x32_bf16 v[0:3], v[190:193], v[232:235], v[0:3]
	s_setprio 0
	s_barrier
	s_add_i32 s31, 0, 0x18000
	s_add_i32 s33, 0, 0x1c000
	ds_read_b128 v[130:133], v254
	ds_read_b128 v[134:137], v254 offset:1024
	ds_read_b128 v[148:151], v254 offset:2048
	ds_read_b128 v[152:155], v254 offset:3072
	ds_read_b128 v[178:181], v255
	ds_read_b128 v[182:185], v255 offset:1024
	ds_read_b128 v[186:189], v255 offset:2048
	ds_read_b128 v[190:193], v255 offset:3072
	s_add_u32 s16, s16, 0x40000
	s_addc_u32 s17, s17, 0
	s_mov_b32 m0, s25
	ds_read_b128 v[194:197], v159 offset:32768
	ds_read_b128 v[208:211], v159 offset:33792
	ds_read_b128 v[212:215], v159 offset:34816
	ds_read_b128 v[216:219], v159 offset:35840
	ds_read_b128 v[220:223], v159 offset:36864
	ds_read_b128 v[224:227], v159 offset:37888
	ds_read_b128 v[228:231], v159 offset:38912
	ds_read_b128 v[232:235], v159 offset:39936
	global_load_lds_dwordx4 v142, s[16:17]
	s_mov_b32 m0, s26
	s_nop 0
	global_load_lds_dwordx4 v140, s[16:17]
	s_waitcnt vmcnt(8)
	s_waitcnt lgkmcnt(0)
	s_barrier
	s_setprio 1
	s_waitcnt lgkmcnt(0)
	v_mfma_f32_16x16x32_bf16 v[126:129], v[130:133], v[194:197], v[126:129]
	v_mfma_f32_16x16x32_bf16 v[122:125], v[148:151], v[194:197], v[122:125]
	v_mfma_f32_16x16x32_bf16 v[110:113], v[130:133], v[212:215], v[110:113]
	v_mfma_f32_16x16x32_bf16 v[106:109], v[148:151], v[212:215], v[106:109]
	s_setprio 0
	s_setprio 1
	v_mfma_f32_16x16x32_bf16 v[94:97], v[130:133], v[220:223], v[94:97]
	v_mfma_f32_16x16x32_bf16 v[90:93], v[148:151], v[220:223], v[90:93]
	v_mfma_f32_16x16x32_bf16 v[78:81], v[130:133], v[228:231], v[78:81]
	v_mfma_f32_16x16x32_bf16 v[74:77], v[148:151], v[228:231], v[74:77]
	s_setprio 0
	s_setprio 1
	v_mfma_f32_16x16x32_bf16 v[126:129], v[134:137], v[208:211], v[126:129]
	v_mfma_f32_16x16x32_bf16 v[122:125], v[152:155], v[208:211], v[122:125]
	v_mfma_f32_16x16x32_bf16 v[110:113], v[134:137], v[216:219], v[110:113]
	v_mfma_f32_16x16x32_bf16 v[106:109], v[152:155], v[216:219], v[106:109]
	s_setprio 0
	s_setprio 1
	v_mfma_f32_16x16x32_bf16 v[94:97], v[134:137], v[224:227], v[94:97]
	v_mfma_f32_16x16x32_bf16 v[90:93], v[152:155], v[224:227], v[90:93]
	v_mfma_f32_16x16x32_bf16 v[78:81], v[134:137], v[232:235], v[78:81]
	v_mfma_f32_16x16x32_bf16 v[74:77], v[152:155], v[232:235], v[74:77]
	s_setprio 0
	s_setprio 1
	v_mfma_f32_16x16x32_bf16 v[118:121], v[178:181], v[194:197], v[118:121]
	v_mfma_f32_16x16x32_bf16 v[114:117], v[186:189], v[194:197], v[114:117]
	v_mfma_f32_16x16x32_bf16 v[102:105], v[178:181], v[212:215], v[102:105]
	v_mfma_f32_16x16x32_bf16 v[98:101], v[186:189], v[212:215], v[98:101]
	s_setprio 0
	s_setprio 1
	v_mfma_f32_16x16x32_bf16 v[86:89], v[178:181], v[220:223], v[86:89]
	v_mfma_f32_16x16x32_bf16 v[82:85], v[186:189], v[220:223], v[82:85]
	v_mfma_f32_16x16x32_bf16 v[70:73], v[178:181], v[228:231], v[70:73]
	v_mfma_f32_16x16x32_bf16 v[66:69], v[186:189], v[228:231], v[66:69]
	s_setprio 0
	s_setprio 1
	v_mfma_f32_16x16x32_bf16 v[118:121], v[182:185], v[208:211], v[118:121]
	v_mfma_f32_16x16x32_bf16 v[114:117], v[190:193], v[208:211], v[114:117]
	v_mfma_f32_16x16x32_bf16 v[102:105], v[182:185], v[216:219], v[102:105]
	v_mfma_f32_16x16x32_bf16 v[98:101], v[190:193], v[216:219], v[98:101]
	s_setprio 0
	s_setprio 1
	v_mfma_f32_16x16x32_bf16 v[86:89], v[182:185], v[224:227], v[86:89]
	v_mfma_f32_16x16x32_bf16 v[82:85], v[190:193], v[224:227], v[82:85]
	v_mfma_f32_16x16x32_bf16 v[70:73], v[182:185], v[232:235], v[70:73]
	v_mfma_f32_16x16x32_bf16 v[66:69], v[190:193], v[232:235], v[66:69]
	s_setprio 0
	s_barrier
; #define PG8_STAGE(bufoff, gbase, voff) do { _Pragma("unroll") for (int _i = 0; _i < 2; ++_i) \
;         __builtin_amdgcn_global_load_lds((const unsigned*)((const char*)(gbase) + (voff)[_i]), (PG8_LAS unsigned*)(lds + (bufoff) + ldsw + _i * 8192), 16, 0, 0); } while (0)
; #define PG8_LDA(dst, b, h) do { _Pragma("unroll") for (int m = 0; m < 4; ++m) _Pragma("unroll") for (int k = 0; k < 2; ++k) dst[m][k] = *(const PG8_LAS bf16x8*)(lds + PG8_SA(b, h) + aoff + m * 2048 + k * 1024); } while (0)
; #define PG8_MMA(ai, bj, At, Bt) do { __builtin_amdgcn_s_setprio(1); _Pragma("unroll") for (int m = 0; m < 4; ++m) _Pragma("unroll") for (int n = 0; n < 2; ++n) _Pragma("unroll") for (int k = 0; k < 2; ++k) \
;         acc[ai][bj][m][n] = __builtin_amdgcn_mfma_f32_16x16x32_bf16(Bt[n][k], At[m][k], acc[ai][bj][m][n], 0, 0, 0); __builtin_amdgcn_s_setprio(0); } while (0)
; #define PG8_WAIT_V(n) asm volatile("s_waitcnt vmcnt(" #n ")" ::: "memory")
; #define PG8_WAIT_L(n) asm volatile("s_waitcnt lgkmcnt(" #n ")" ::: "memory")
; #define PG8_BAR __builtin_amdgcn_s_barrier()
; #define PG8_SCHED __builtin_amdgcn_sched_barrier(0)
; template <class Epi, class Sched, bool ALIGN_EPI = false, bool SP2 = false>
; __device__ __forceinline__ void gemm_phase(PG8_LAS unsigned char* lds, const Gemm g, const Sched& S, const Epi& E, const int wave0) {
;     ...
;             PG8_LDA(At, 1, 1); PG8_STAGE(PG8_SB(1, 0), b3, voffB); PG8_STAGE(PG8_SB(1, 1), b3 + hstepB, voffB); PG8_STAGE(PG8_SA(1, 0), a3, voffA);
;             PG8_WAIT_V(8); PG8_WAIT_L(0); PG8_BAR; PG8_MMA(1, 0, At, B0); PG8_MMA(1, 1, At, B1); PG8_BAR; PG8_SCHED;
;     ...
;         if constexpr (ALIGN_EPI) { if (wr == 0) PG8_BAR; }
	s_add_i32 s16, s31, s22
	s_add_u32 s36, s2, 0x80
	s_addc_u32 s37, s3, 0
	s_mov_b32 m0, s16
	ds_read_b128 v[194:197], v159 offset:49152
	ds_read_b128 v[208:211], v159 offset:50176
	ds_read_b128 v[212:215], v159 offset:51200
	ds_read_b128 v[216:219], v159 offset:52224
	ds_read_b128 v[220:223], v159 offset:53248
	ds_read_b128 v[224:227], v159 offset:54272
	ds_read_b128 v[228:231], v159 offset:55296
	ds_read_b128 v[232:235], v159 offset:56320
	global_load_lds_dwordx4 v64, s[36:37]
	s_add_i32 m0, s16, 0x2000
	s_add_u32 s2, s2, 0x40080
	s_addc_u32 s3, s3, 0
	s_add_i32 s16, s33, s22
	global_load_lds_dwordx4 v138, s[36:37]
	s_mov_b32 m0, s16
	s_nop 0
	global_load_lds_dwordx4 v64, s[2:3]
	s_add_i32 m0, s16, 0x2000
	s_nop 0
	global_load_lds_dwordx4 v138, s[2:3]
	s_add_u32 s100, s100, 0x80
	s_addc_u32 s101, s101, 0
	s_mov_b32 m0, s27
	s_nop 0
	global_load_lds_dwordx4 v142, s[100:101]
	s_mov_b32 m0, s28
	s_nop 0
	global_load_lds_dwordx4 v140, s[100:101]
	s_waitcnt vmcnt(8)
	s_waitcnt lgkmcnt(0)
	s_barrier
	s_setprio 1
	s_waitcnt lgkmcnt(0)
	v_mfma_f32_16x16x32_bf16 v[60:63], v[130:133], v[194:197], v[60:63]
	v_mfma_f32_16x16x32_bf16 v[56:59], v[148:151], v[194:197], v[56:59]
	v_mfma_f32_16x16x32_bf16 v[44:47], v[130:133], v[212:215], v[44:47]
	v_mfma_f32_16x16x32_bf16 v[40:43], v[148:151], v[212:215], v[40:43]
	s_setprio 0
	s_setprio 1
	v_mfma_f32_16x16x32_bf16 v[28:31], v[130:133], v[220:223], v[28:31]
	v_mfma_f32_16x16x32_bf16 v[24:27], v[148:151], v[220:223], v[24:27]
	v_mfma_f32_16x16x32_bf16 v[12:15], v[130:133], v[228:231], v[12:15]
	v_mfma_f32_16x16x32_bf16 v[8:11], v[148:151], v[228:231], v[8:11]
	s_setprio 0
	s_setprio 1
	v_mfma_f32_16x16x32_bf16 v[60:63], v[134:137], v[208:211], v[60:63]
	v_mfma_f32_16x16x32_bf16 v[56:59], v[152:155], v[208:211], v[56:59]
	v_mfma_f32_16x16x32_bf16 v[44:47], v[134:137], v[216:219], v[44:47]
	v_mfma_f32_16x16x32_bf16 v[40:43], v[152:155], v[216:219], v[40:43]
	s_setprio 0
	s_setprio 1
	v_mfma_f32_16x16x32_bf16 v[28:31], v[134:137], v[224:227], v[28:31]
	v_mfma_f32_16x16x32_bf16 v[24:27], v[152:155], v[224:227], v[24:27]
	v_mfma_f32_16x16x32_bf16 v[12:15], v[134:137], v[232:235], v[12:15]
	v_mfma_f32_16x16x32_bf16 v[8:11], v[152:155], v[232:235], v[8:11]
	s_setprio 0
	s_setprio 1
	v_mfma_f32_16x16x32_bf16 v[52:55], v[178:181], v[194:197], v[52:55]
	v_mfma_f32_16x16x32_bf16 v[48:51], v[186:189], v[194:197], v[48:51]
	v_mfma_f32_16x16x32_bf16 v[36:39], v[178:181], v[212:215], v[36:39]
	v_mfma_f32_16x16x32_bf16 v[32:35], v[186:189], v[212:215], v[32:35]
	s_setprio 0
	s_setprio 1
	v_mfma_f32_16x16x32_bf16 v[20:23], v[178:181], v[220:223], v[20:23]
	v_mfma_f32_16x16x32_bf16 v[16:19], v[186:189], v[220:223], v[16:19]
	v_mfma_f32_16x16x32_bf16 v[4:7], v[178:181], v[228:231], v[4:7]
	v_mfma_f32_16x16x32_bf16 v[0:3], v[186:189], v[228:231], v[0:3]
	s_setprio 0
	s_setprio 1
	v_mfma_f32_16x16x32_bf16 v[52:55], v[182:185], v[208:211], v[52:55]
	v_mfma_f32_16x16x32_bf16 v[48:51], v[190:193], v[208:211], v[48:51]
	v_mfma_f32_16x16x32_bf16 v[36:39], v[182:185], v[216:219], v[36:39]
	v_mfma_f32_16x16x32_bf16 v[32:35], v[190:193], v[216:219], v[32:35]
	s_setprio 0
	s_setprio 1
	v_mfma_f32_16x16x32_bf16 v[20:23], v[182:185], v[224:227], v[20:23]
	v_mfma_f32_16x16x32_bf16 v[16:19], v[190:193], v[224:227], v[16:19]
	v_mfma_f32_16x16x32_bf16 v[4:7], v[182:185], v[232:235], v[4:7]
	v_mfma_f32_16x16x32_bf16 v[0:3], v[190:193], v[232:235], v[0:3]
	s_setprio 0
	s_barrier
	s_add_i32 s19, s19, 2
	s_add_u32 s0, s0, 0x100
	s_addc_u32 s1, s1, 0
	s_add_u32 s13, s13, 0x100
	s_addc_u32 s18, s18, 0
	s_cmp_gt_u32 s19, 13
	s_cbranch_scc0 .LBB0_1178
	s_mov_b64 s[36:37], 0x80
	s_and_b64 vcc, exec, s[6:7]
	s_cbranch_vccz .LBB0_1181
	s_barrier

; #define PG8_STAGE(bufoff, gbase, voff) do { _Pragma("unroll") for (int _i = 0; _i < 2; ++_i) \
;         __builtin_amdgcn_global_load_lds((const unsigned*)((const char*)(gbase) + (voff)[_i]), (PG8_LAS unsigned*)(lds + (bufoff) + ldsw + _i * 8192), 16, 0, 0); } while (0)
; #define PG8_LDA(dst, b, h) do { _Pragma("unroll") for (int m = 0; m < 4; ++m) _Pragma("unroll") for (int k = 0; k < 2; ++k) dst[m][k] = *(const PG8_LAS bf16x8*)(lds + PG8_SA(b, h) + aoff + m * 2048 + k * 1024); } while (0)
; #define PG8_LDB(dst, b, h) do { _Pragma("unroll") for (int n = 0; n < 2; ++n) _Pragma("unroll") for (int k = 0; k < 2; ++k) dst[n][k] = *(const PG8_LAS bf16x8*)(lds + PG8_SB(b, h) + boff + n * 2048 + k * 1024); } while (0)
; #define PG8_MMA(ai, bj, At, Bt) do { __builtin_amdgcn_s_setprio(1); _Pragma("unroll") for (int m = 0; m < 4; ++m) _Pragma("unroll") for (int n = 0; n < 2; ++n) _Pragma("unroll") for (int k = 0; k < 2; ++k) \
;         acc[ai][bj][m][n] = __builtin_amdgcn_mfma_f32_16x16x32_bf16(Bt[n][k], At[m][k], acc[ai][bj][m][n], 0, 0, 0); __builtin_amdgcn_s_setprio(0); } while (0)
; #define PG8_WAIT_V(n) asm volatile("s_waitcnt vmcnt(" #n ")" ::: "memory")
; #define PG8_BAR __builtin_amdgcn_s_barrier()
; template <class Epi, class Sched, bool ALIGN_EPI = false, bool SP2 = false>
; __device__ __forceinline__ void gemm_phase(PG8_LAS unsigned char* lds, const Gemm g, const Sched& S, const Epi& E, const int wave0) {
;     ...
;         for (int t = 0; t < nt; t += 2) {
;             const bool last = (t == nt - 2);
;             const char* a1 = cA + (size_t)(t + 1) * kstep;
;             const char* a2 = last ? nA : cA + (size_t)(t + 2) * kstep; const char* b2 = last ? nB : cB + (size_t)(t + 2) * kstep;
;             const char* a3 = a2 + kstep; const char* b3 = b2 + kstep;
;             if (last && has_next) S.a_ready(nxt);
;             if constexpr (SP2) {
;             PG8_LDB(B0, 0, 0); PG8_LDB(B1, 0, 1); PG8_SCHED; PG8_LDA(At, 0, 0); PG8_STAGE(PG8_SA(1, 1), a1 + hstepA, voffA);
;             PG8_WAIT_V(8); PG8_WAIT_L(0); PG8_BAR; PG8_MMA(0, 0, At, B0); PG8_MMA(0, 1, At, B1); PG8_BAR; PG8_SCHED;
;             PG8_LDA(At, 0, 1); PG8_STAGE(PG8_SB(0, 0), b2, voffB); PG8_STAGE(PG8_SB(0, 1), b2 + hstepB, voffB); PG8_STAGE(PG8_SA(0, 0), a2, voffA);
;             PG8_WAIT_V(8); PG8_WAIT_L(0); PG8_BAR; PG8_MMA(1, 0, At, B0); PG8_MMA(1, 1, At, B1); PG8_BAR; PG8_SCHED;
.LBB0_1231:
	s_add_u32 s2, s0, 0xfffc0080
	s_addc_u32 s3, s1, -1
	s_add_i32 s31, 0, 0x10000
	s_cmp_eq_u32 s19, 12
	s_cselect_b32 s17, s43, s3
	s_cselect_b32 s16, s42, s2
	s_cselect_b32 s3, s9, s18
	s_cselect_b32 s2, s11, s13
	s_add_i32 s33, 0, 0x14000
	ds_read_b128 v[140:143], v252
	ds_read_b128 v[144:147], v252 offset:1024
	ds_read_b128 v[154:157], v252 offset:2048
	ds_read_b128 v[158:161], v252 offset:3072
	ds_read_b128 v[178:181], v253
	ds_read_b128 v[182:185], v253 offset:1024
	ds_read_b128 v[186:189], v253 offset:2048
	ds_read_b128 v[190:193], v253 offset:3072
	s_add_i32 m0, s23, 0xc000
	ds_read_b128 v[194:197], v153
	ds_read_b128 v[208:211], v153 offset:1024
	ds_read_b128 v[212:215], v153 offset:2048
	ds_read_b128 v[216:219], v153 offset:3072
	ds_read_b128 v[220:223], v153 offset:4096
	ds_read_b128 v[224:227], v153 offset:5120
	ds_read_b128 v[228:231], v153 offset:6144
	ds_read_b128 v[232:235], v153 offset:7168
	global_load_lds_dwordx4 v136, s[0:1]
	s_add_i32 m0, s23, 0xe000
	s_nop 0
	global_load_lds_dwordx4 v138, s[0:1]
	s_waitcnt vmcnt(8)
	s_waitcnt lgkmcnt(0)
	s_barrier
	s_setprio 1
	s_waitcnt lgkmcnt(0)
	v_mfma_f32_16x16x32_bf16 v[126:129], v[140:143], v[194:197], v[126:129]
	v_mfma_f32_16x16x32_bf16 v[122:125], v[154:157], v[194:197], v[122:125]
	v_mfma_f32_16x16x32_bf16 v[110:113], v[140:143], v[212:215], v[110:113]
	v_mfma_f32_16x16x32_bf16 v[106:109], v[154:157], v[212:215], v[106:109]
	s_setprio 0
	s_setprio 1
	v_mfma_f32_16x16x32_bf16 v[94:97], v[140:143], v[220:223], v[94:97]
	v_mfma_f32_16x16x32_bf16 v[90:93], v[154:157], v[220:223], v[90:93]
	v_mfma_f32_16x16x32_bf16 v[78:81], v[140:143], v[228:231], v[78:81]
	v_mfma_f32_16x16x32_bf16 v[74:77], v[154:157], v[228:231], v[74:77]
	s_setprio 0
	s_setprio 1
	v_mfma_f32_16x16x32_bf16 v[126:129], v[144:147], v[208:211], v[126:129]
	v_mfma_f32_16x16x32_bf16 v[122:125], v[158:161], v[208:211], v[122:125]
	v_mfma_f32_16x16x32_bf16 v[110:113], v[144:147], v[216:219], v[110:113]
	v_mfma_f32_16x16x32_bf16 v[106:109], v[158:161], v[216:219], v[106:109]
	s_setprio 0
	s_setprio 1
	v_mfma_f32_16x16x32_bf16 v[94:97], v[144:147], v[224:227], v[94:97]
	v_mfma_f32_16x16x32_bf16 v[90:93], v[158:161], v[224:227], v[90:93]
	v_mfma_f32_16x16x32_bf16 v[78:81], v[144:147], v[232:235], v[78:81]
	v_mfma_f32_16x16x32_bf16 v[74:77], v[158:161], v[232:235], v[74:77]
	s_setprio 0
	s_setprio 1
	v_mfma_f32_16x16x32_bf16 v[118:121], v[178:181], v[194:197], v[118:121]
	v_mfma_f32_16x16x32_bf16 v[114:117], v[186:189], v[194:197], v[114:117]
	v_mfma_f32_16x16x32_bf16 v[102:105], v[178:181], v[212:215], v[102:105]
	v_mfma_f32_16x16x32_bf16 v[98:101], v[186:189], v[212:215], v[98:101]
	s_setprio 0
	s_setprio 1
	v_mfma_f32_16x16x32_bf16 v[86:89], v[178:181], v[220:223], v[86:89]
	v_mfma_f32_16x16x32_bf16 v[82:85], v[186:189], v[220:223], v[82:85]
	v_mfma_f32_16x16x32_bf16 v[70:73], v[178:181], v[228:231], v[70:73]
	v_mfma_f32_16x16x32_bf16 v[66:69], v[186:189], v[228:231], v[66:69]
	s_setprio 0
	s_setprio 1
	v_mfma_f32_16x16x32_bf16 v[118:121], v[182:185], v[208:211], v[118:121]
	v_mfma_f32_16x16x32_bf16 v[114:117], v[190:193], v[208:211], v[114:117]
	v_mfma_f32_16x16x32_bf16 v[102:105], v[182:185], v[216:219], v[102:105]
	v_mfma_f32_16x16x32_bf16 v[98:101], v[190:193], v[216:219], v[98:101]
	s_setprio 0
	s_setprio 1
	v_mfma_f32_16x16x32_bf16 v[86:89], v[182:185], v[224:227], v[86:89]
	v_mfma_f32_16x16x32_bf16 v[82:85], v[190:193], v[224:227], v[82:85]
	v_mfma_f32_16x16x32_bf16 v[70:73], v[182:185], v[232:235], v[70:73]
	v_mfma_f32_16x16x32_bf16 v[66:69], v[190:193], v[232:235], v[66:69]
	s_setprio 0
	s_barrier
	s_add_i32 s31, s31, s22
	s_mov_b32 m0, s31
	ds_read_b128 v[194:197], v153 offset:16384
	ds_read_b128 v[208:211], v153 offset:17408
	ds_read_b128 v[212:215], v153 offset:18432
	ds_read_b128 v[216:219], v153 offset:19456
	ds_read_b128 v[220:223], v153 offset:20480
	ds_read_b128 v[224:227], v153 offset:21504
	ds_read_b128 v[228:231], v153 offset:22528
	ds_read_b128 v[232:235], v153 offset:23552
	global_load_lds_dwordx4 v64, s[2:3]
	s_add_i32 m0, s31, 0x2000
	s_add_u32 s34, s2, 0x40000
	s_addc_u32 s35, s3, 0
	s_add_i32 s31, s33, s22
	global_load_lds_dwordx4 v130, s[2:3]
	s_mov_b32 m0, s31
	s_mov_b64 s[100:101], s[16:17]
	global_load_lds_dwordx4 v64, s[34:35]
	s_add_i32 m0, s31, 0x2000
	s_nop 0
	global_load_lds_dwordx4 v130, s[34:35]
	s_mov_b32 m0, s23
	s_nop 0
	global_load_lds_dwordx4 v134, s[16:17]
	s_mov_b32 m0, s24
	s_nop 0
	global_load_lds_dwordx4 v132, s[16:17]
	s_waitcnt vmcnt(8)
	s_waitcnt lgkmcnt(0)
	s_barrier
; #define PG8_STAGE(bufoff, gbase, voff) do { _Pragma("unroll") for (int _i = 0; _i < 2; ++_i) \
;         __builtin_amdgcn_global_load_lds((const unsigned*)((const char*)(gbase) + (voff)[_i]), (PG8_LAS unsigned*)(lds + (bufoff) + ldsw + _i * 8192), 16, 0, 0); } while (0)
; #define PG8_LDA(dst, b, h) do { _Pragma("unroll") for (int m = 0; m < 4; ++m) _Pragma("unroll") for (int k = 0; k < 2; ++k) dst[m][k] = *(const PG8_LAS bf16x8*)(lds + PG8_SA(b, h) + aoff + m * 2048 + k * 1024); } while (0)
; #define PG8_LDB(dst, b, h) do { _Pragma("unroll") for (int n = 0; n < 2; ++n) _Pragma("unroll") for (int k = 0; k < 2; ++k) dst[n][k] = *(const PG8_LAS bf16x8*)(lds + PG8_SB(b, h) + boff + n * 2048 + k * 1024); } while (0)
; #define PG8_MMA(ai, bj, At, Bt) do { __builtin_amdgcn_s_setprio(1); _Pragma("unroll") for (int m = 0; m < 4; ++m) _Pragma("unroll") for (int n = 0; n < 2; ++n) _Pragma("unroll") for (int k = 0; k < 2; ++k) \
;         acc[ai][bj][m][n] = __builtin_amdgcn_mfma_f32_16x16x32_bf16(Bt[n][k], At[m][k], acc[ai][bj][m][n], 0, 0, 0); __builtin_amdgcn_s_setprio(0); } while (0)
; #define PG8_WAIT_V(n) asm volatile("s_waitcnt vmcnt(" #n ")" ::: "memory")
; #define PG8_WAIT_L(n) asm volatile("s_waitcnt lgkmcnt(" #n ")" ::: "memory")
; #define PG8_BAR __builtin_amdgcn_s_barrier()
; #define PG8_SCHED __builtin_amdgcn_sched_barrier(0)
; template <class Epi, class Sched, bool ALIGN_EPI = false, bool SP2 = false>
; __device__ __forceinline__ void gemm_phase(PG8_LAS unsigned char* lds, const Gemm g, const Sched& S, const Epi& E, const int wave0) {
;     ...
;             PG8_WAIT_V(8); PG8_WAIT_L(0); PG8_BAR; PG8_MMA(0, 0, At, B0); PG8_MMA(0, 1, At, B1); PG8_BAR; PG8_SCHED;
;             PG8_LDA(At, 0, 1); PG8_STAGE(PG8_SB(0, 0), b2, voffB); PG8_STAGE(PG8_SB(0, 1), b2 + hstepB, voffB); PG8_STAGE(PG8_SA(0, 0), a2, voffA);
;             PG8_WAIT_V(8); PG8_WAIT_L(0); PG8_BAR; PG8_MMA(1, 0, At, B0); PG8_MMA(1, 1, At, B1); PG8_BAR; PG8_SCHED;
;             PG8_LDB(B0, 1, 0); PG8_LDB(B1, 1, 1); PG8_SCHED; PG8_LDA(At, 1, 0); PG8_STAGE(PG8_SA(0, 1), a2 + hstepA, voffA);
;             PG8_WAIT_V(8); PG8_WAIT_L(0); PG8_BAR; PG8_MMA(0, 0, At, B0); PG8_MMA(0, 1, At, B1); PG8_BAR; PG8_SCHED;
	s_setprio 1
	s_waitcnt lgkmcnt(0)
	v_mfma_f32_16x16x32_bf16 v[60:63], v[140:143], v[194:197], v[60:63]
	v_mfma_f32_16x16x32_bf16 v[56:59], v[154:157], v[194:197], v[56:59]
	v_mfma_f32_16x16x32_bf16 v[44:47], v[140:143], v[212:215], v[44:47]
	v_mfma_f32_16x16x32_bf16 v[40:43], v[154:157], v[212:215], v[40:43]
	s_setprio 0
	s_setprio 1
	v_mfma_f32_16x16x32_bf16 v[28:31], v[140:143], v[220:223], v[28:31]
	v_mfma_f32_16x16x32_bf16 v[24:27], v[154:157], v[220:223], v[24:27]
	v_mfma_f32_16x16x32_bf16 v[12:15], v[140:143], v[228:231], v[12:15]
	v_mfma_f32_16x16x32_bf16 v[8:11], v[154:157], v[228:231], v[8:11]
	s_setprio 0
	s_setprio 1
	v_mfma_f32_16x16x32_bf16 v[60:63], v[144:147], v[208:211], v[60:63]
	v_mfma_f32_16x16x32_bf16 v[56:59], v[158:161], v[208:211], v[56:59]
	v_mfma_f32_16x16x32_bf16 v[44:47], v[144:147], v[216:219], v[44:47]
	v_mfma_f32_16x16x32_bf16 v[40:43], v[158:161], v[216:219], v[40:43]
	s_setprio 0
	s_setprio 1
	v_mfma_f32_16x16x32_bf16 v[28:31], v[144:147], v[224:227], v[28:31]
	v_mfma_f32_16x16x32_bf16 v[24:27], v[158:161], v[224:227], v[24:27]
	v_mfma_f32_16x16x32_bf16 v[12:15], v[144:147], v[232:235], v[12:15]
	v_mfma_f32_16x16x32_bf16 v[8:11], v[158:161], v[232:235], v[8:11]
	s_setprio 0
	s_setprio 1
	v_mfma_f32_16x16x32_bf16 v[52:55], v[178:181], v[194:197], v[52:55]
	v_mfma_f32_16x16x32_bf16 v[48:51], v[186:189], v[194:197], v[48:51]
	v_mfma_f32_16x16x32_bf16 v[36:39], v[178:181], v[212:215], v[36:39]
	v_mfma_f32_16x16x32_bf16 v[32:35], v[186:189], v[212:215], v[32:35]
	s_setprio 0
	s_setprio 1
	v_mfma_f32_16x16x32_bf16 v[20:23], v[178:181], v[220:223], v[20:23]
	v_mfma_f32_16x16x32_bf16 v[16:19], v[186:189], v[220:223], v[16:19]
	v_mfma_f32_16x16x32_bf16 v[4:7], v[178:181], v[228:231], v[4:7]
	v_mfma_f32_16x16x32_bf16 v[0:3], v[186:189], v[228:231], v[0:3]
	s_setprio 0
	s_setprio 1
	v_mfma_f32_16x16x32_bf16 v[52:55], v[182:185], v[208:211], v[52:55]
	v_mfma_f32_16x16x32_bf16 v[48:51], v[190:193], v[208:211], v[48:51]
	v_mfma_f32_16x16x32_bf16 v[36:39], v[182:185], v[216:219], v[36:39]
	v_mfma_f32_16x16x32_bf16 v[32:35], v[190:193], v[216:219], v[32:35]
	s_setprio 0
	s_setprio 1
	v_mfma_f32_16x16x32_bf16 v[20:23], v[182:185], v[224:227], v[20:23]
	v_mfma_f32_16x16x32_bf16 v[16:19], v[190:193], v[224:227], v[16:19]
	v_mfma_f32_16x16x32_bf16 v[4:7], v[182:185], v[232:235], v[4:7]
	v_mfma_f32_16x16x32_bf16 v[0:3], v[190:193], v[232:235], v[0:3]
	s_setprio 0
	s_barrier
	s_add_i32 s31, 0, 0x18000
	s_add_i32 s33, 0, 0x1c000
	ds_read_b128 v[140:143], v254
	ds_read_b128 v[144:147], v254 offset:1024
	ds_read_b128 v[154:157], v254 offset:2048
	ds_read_b128 v[158:161], v254 offset:3072
	ds_read_b128 v[178:181], v255
	ds_read_b128 v[182:185], v255 offset:1024
	ds_read_b128 v[186:189], v255 offset:2048
	ds_read_b128 v[190:193], v255 offset:3072
	s_add_u32 s16, s16, 0x40000
	s_addc_u32 s17, s17, 0
	s_mov_b32 m0, s25
	ds_read_b128 v[194:197], v153 offset:32768
	ds_read_b128 v[208:211], v153 offset:33792
	ds_read_b128 v[212:215], v153 offset:34816
	ds_read_b128 v[216:219], v153 offset:35840
	ds_read_b128 v[220:223], v153 offset:36864
	ds_read_b128 v[224:227], v153 offset:37888
	ds_read_b128 v[228:231], v153 offset:38912
	ds_read_b128 v[232:235], v153 offset:39936
	global_load_lds_dwordx4 v134, s[16:17]
	s_mov_b32 m0, s26
	s_nop 0
	global_load_lds_dwordx4 v132, s[16:17]
	s_waitcnt vmcnt(8)
	s_waitcnt lgkmcnt(0)
	s_barrier
	s_setprio 1
	s_waitcnt lgkmcnt(0)
	v_mfma_f32_16x16x32_bf16 v[126:129], v[140:143], v[194:197], v[126:129]
	v_mfma_f32_16x16x32_bf16 v[122:125], v[154:157], v[194:197], v[122:125]
	v_mfma_f32_16x16x32_bf16 v[110:113], v[140:143], v[212:215], v[110:113]
	v_mfma_f32_16x16x32_bf16 v[106:109], v[154:157], v[212:215], v[106:109]
	s_setprio 0
	s_setprio 1
	v_mfma_f32_16x16x32_bf16 v[94:97], v[140:143], v[220:223], v[94:97]
	v_mfma_f32_16x16x32_bf16 v[90:93], v[154:157], v[220:223], v[90:93]
	v_mfma_f32_16x16x32_bf16 v[78:81], v[140:143], v[228:231], v[78:81]
	v_mfma_f32_16x16x32_bf16 v[74:77], v[154:157], v[228:231], v[74:77]
	s_setprio 0
	s_setprio 1
	v_mfma_f32_16x16x32_bf16 v[126:129], v[144:147], v[208:211], v[126:129]
	v_mfma_f32_16x16x32_bf16 v[122:125], v[158:161], v[208:211], v[122:125]
	v_mfma_f32_16x16x32_bf16 v[110:113], v[144:147], v[216:219], v[110:113]
	v_mfma_f32_16x16x32_bf16 v[106:109], v[158:161], v[216:219], v[106:109]
	s_setprio 0
	s_setprio 1
	v_mfma_f32_16x16x32_bf16 v[94:97], v[144:147], v[224:227], v[94:97]
	v_mfma_f32_16x16x32_bf16 v[90:93], v[158:161], v[224:227], v[90:93]
	v_mfma_f32_16x16x32_bf16 v[78:81], v[144:147], v[232:235], v[78:81]
	v_mfma_f32_16x16x32_bf16 v[74:77], v[158:161], v[232:235], v[74:77]
	s_setprio 0
	s_setprio 1
	v_mfma_f32_16x16x32_bf16 v[118:121], v[178:181], v[194:197], v[118:121]
	v_mfma_f32_16x16x32_bf16 v[114:117], v[186:189], v[194:197], v[114:117]
	v_mfma_f32_16x16x32_bf16 v[102:105], v[178:181], v[212:215], v[102:105]
	v_mfma_f32_16x16x32_bf16 v[98:101], v[186:189], v[212:215], v[98:101]
	s_setprio 0
	s_setprio 1
	v_mfma_f32_16x16x32_bf16 v[86:89], v[178:181], v[220:223], v[86:89]
	v_mfma_f32_16x16x32_bf16 v[82:85], v[186:189], v[220:223], v[82:85]
	v_mfma_f32_16x16x32_bf16 v[70:73], v[178:181], v[228:231], v[70:73]
	v_mfma_f32_16x16x32_bf16 v[66:69], v[186:189], v[228:231], v[66:69]
	s_setprio 0
	s_setprio 1
	v_mfma_f32_16x16x32_bf16 v[118:121], v[182:185], v[208:211], v[118:121]
	v_mfma_f32_16x16x32_bf16 v[114:117], v[190:193], v[208:211], v[114:117]
	v_mfma_f32_16x16x32_bf16 v[102:105], v[182:185], v[216:219], v[102:105]
	v_mfma_f32_16x16x32_bf16 v[98:101], v[190:193], v[216:219], v[98:101]
	s_setprio 0
	s_setprio 1
	v_mfma_f32_16x16x32_bf16 v[86:89], v[182:185], v[224:227], v[86:89]
	v_mfma_f32_16x16x32_bf16 v[82:85], v[190:193], v[224:227], v[82:85]
	v_mfma_f32_16x16x32_bf16 v[70:73], v[182:185], v[232:235], v[70:73]
	v_mfma_f32_16x16x32_bf16 v[66:69], v[190:193], v[232:235], v[66:69]
	s_setprio 0
	s_barrier
; #define PG8_STAGE(bufoff, gbase, voff) do { _Pragma("unroll") for (int _i = 0; _i < 2; ++_i) \
;         __builtin_amdgcn_global_load_lds((const unsigned*)((const char*)(gbase) + (voff)[_i]), (PG8_LAS unsigned*)(lds + (bufoff) + ldsw + _i * 8192), 16, 0, 0); } while (0)
; #define PG8_LDA(dst, b, h) do { _Pragma("unroll") for (int m = 0; m < 4; ++m) _Pragma("unroll") for (int k = 0; k < 2; ++k) dst[m][k] = *(const PG8_LAS bf16x8*)(lds + PG8_SA(b, h) + aoff + m * 2048 + k * 1024); } while (0)
; #define PG8_MMA(ai, bj, At, Bt) do { __builtin_amdgcn_s_setprio(1); _Pragma("unroll") for (int m = 0; m < 4; ++m) _Pragma("unroll") for (int n = 0; n < 2; ++n) _Pragma("unroll") for (int k = 0; k < 2; ++k) \
;         acc[ai][bj][m][n] = __builtin_amdgcn_mfma_f32_16x16x32_bf16(Bt[n][k], At[m][k], acc[ai][bj][m][n], 0, 0, 0); __builtin_amdgcn_s_setprio(0); } while (0)
; #define PG8_WAIT_V(n) asm volatile("s_waitcnt vmcnt(" #n ")" ::: "memory")
; #define PG8_WAIT_L(n) asm volatile("s_waitcnt lgkmcnt(" #n ")" ::: "memory")
; #define PG8_BAR __builtin_amdgcn_s_barrier()
; #define PG8_SCHED __builtin_amdgcn_sched_barrier(0)
; template <class Epi, class Sched, bool ALIGN_EPI = false, bool SP2 = false>
; __device__ __forceinline__ void gemm_phase(PG8_LAS unsigned char* lds, const Gemm g, const Sched& S, const Epi& E, const int wave0) {
;     ...
;         for (int t = 0; t < nt; t += 2) {
;             const bool last = (t == nt - 2);
;     ...
;             PG8_LDA(At, 1, 1); PG8_STAGE(PG8_SB(1, 0), b3, voffB); PG8_STAGE(PG8_SB(1, 1), b3 + hstepB, voffB); PG8_STAGE(PG8_SA(1, 0), a3, voffA);
;             PG8_WAIT_V(8); PG8_WAIT_L(0); PG8_BAR; PG8_MMA(1, 0, At, B0); PG8_MMA(1, 1, At, B1); PG8_BAR; PG8_SCHED;
	s_add_i32 s16, s31, s22
	s_add_u32 s36, s2, 0x80
	s_addc_u32 s37, s3, 0
	s_mov_b32 m0, s16
	ds_read_b128 v[194:197], v153 offset:49152
	ds_read_b128 v[208:211], v153 offset:50176
	ds_read_b128 v[212:215], v153 offset:51200
	ds_read_b128 v[216:219], v153 offset:52224
	ds_read_b128 v[220:223], v153 offset:53248
	ds_read_b128 v[224:227], v153 offset:54272
	ds_read_b128 v[228:231], v153 offset:55296
	ds_read_b128 v[232:235], v153 offset:56320
	global_load_lds_dwordx4 v64, s[36:37]
	s_add_i32 m0, s16, 0x2000
	s_add_u32 s2, s2, 0x40080
	s_addc_u32 s3, s3, 0
	s_add_i32 s16, s33, s22
	global_load_lds_dwordx4 v130, s[36:37]
	s_mov_b32 m0, s16
	s_nop 0
	global_load_lds_dwordx4 v64, s[2:3]
	s_add_i32 m0, s16, 0x2000
	s_nop 0
	global_load_lds_dwordx4 v130, s[2:3]
	s_add_u32 s100, s100, 0x80
	s_addc_u32 s101, s101, 0
	s_mov_b32 m0, s27
	s_nop 0
	global_load_lds_dwordx4 v134, s[100:101]
	s_mov_b32 m0, s28
	s_nop 0
	global_load_lds_dwordx4 v132, s[100:101]
	s_waitcnt vmcnt(8)
	s_waitcnt lgkmcnt(0)
	s_barrier
	s_setprio 1
	s_waitcnt lgkmcnt(0)
	v_mfma_f32_16x16x32_bf16 v[60:63], v[140:143], v[194:197], v[60:63]
	v_mfma_f32_16x16x32_bf16 v[56:59], v[154:157], v[194:197], v[56:59]
	v_mfma_f32_16x16x32_bf16 v[44:47], v[140:143], v[212:215], v[44:47]
	v_mfma_f32_16x16x32_bf16 v[40:43], v[154:157], v[212:215], v[40:43]
	s_setprio 0
	s_setprio 1
	v_mfma_f32_16x16x32_bf16 v[28:31], v[140:143], v[220:223], v[28:31]
	v_mfma_f32_16x16x32_bf16 v[24:27], v[154:157], v[220:223], v[24:27]
	v_mfma_f32_16x16x32_bf16 v[12:15], v[140:143], v[228:231], v[12:15]
	v_mfma_f32_16x16x32_bf16 v[8:11], v[154:157], v[228:231], v[8:11]
	s_setprio 0
	s_setprio 1
	v_mfma_f32_16x16x32_bf16 v[60:63], v[144:147], v[208:211], v[60:63]
	v_mfma_f32_16x16x32_bf16 v[56:59], v[158:161], v[208:211], v[56:59]
	v_mfma_f32_16x16x32_bf16 v[44:47], v[144:147], v[216:219], v[44:47]
	v_mfma_f32_16x16x32_bf16 v[40:43], v[158:161], v[216:219], v[40:43]
	s_setprio 0
	s_setprio 1
	v_mfma_f32_16x16x32_bf16 v[28:31], v[144:147], v[224:227], v[28:31]
	v_mfma_f32_16x16x32_bf16 v[24:27], v[158:161], v[224:227], v[24:27]
	v_mfma_f32_16x16x32_bf16 v[12:15], v[144:147], v[232:235], v[12:15]
	v_mfma_f32_16x16x32_bf16 v[8:11], v[158:161], v[232:235], v[8:11]
	s_setprio 0
	s_setprio 1
	v_mfma_f32_16x16x32_bf16 v[52:55], v[178:181], v[194:197], v[52:55]
	v_mfma_f32_16x16x32_bf16 v[48:51], v[186:189], v[194:197], v[48:51]
	v_mfma_f32_16x16x32_bf16 v[36:39], v[178:181], v[212:215], v[36:39]
	v_mfma_f32_16x16x32_bf16 v[32:35], v[186:189], v[212:215], v[32:35]
	s_setprio 0
	s_setprio 1
	v_mfma_f32_16x16x32_bf16 v[20:23], v[178:181], v[220:223], v[20:23]
	v_mfma_f32_16x16x32_bf16 v[16:19], v[186:189], v[220:223], v[16:19]
	v_mfma_f32_16x16x32_bf16 v[4:7], v[178:181], v[228:231], v[4:7]
	v_mfma_f32_16x16x32_bf16 v[0:3], v[186:189], v[228:231], v[0:3]
	s_setprio 0
	s_setprio 1
	v_mfma_f32_16x16x32_bf16 v[52:55], v[182:185], v[208:211], v[52:55]
	v_mfma_f32_16x16x32_bf16 v[48:51], v[190:193], v[208:211], v[48:51]
	v_mfma_f32_16x16x32_bf16 v[36:39], v[182:185], v[216:219], v[36:39]
	v_mfma_f32_16x16x32_bf16 v[32:35], v[190:193], v[216:219], v[32:35]
	s_setprio 0
	s_setprio 1
	v_mfma_f32_16x16x32_bf16 v[20:23], v[182:185], v[224:227], v[20:23]
	v_mfma_f32_16x16x32_bf16 v[16:19], v[190:193], v[224:227], v[16:19]
	v_mfma_f32_16x16x32_bf16 v[4:7], v[182:185], v[232:235], v[4:7]
	v_mfma_f32_16x16x32_bf16 v[0:3], v[190:193], v[232:235], v[0:3]
	s_setprio 0
	s_barrier
	s_add_i32 s19, s19, 2
	s_add_u32 s0, s0, 0x100
	s_addc_u32 s1, s1, 0
	s_add_u32 s13, s13, 0x100
	s_addc_u32 s18, s18, 0
	s_cmp_gt_u32 s19, 13
	s_cbranch_scc0 .LBB0_1231
	s_mov_b64 s[36:37], 0x80
	s_and_b64 vcc, exec, s[6:7]
	s_cbranch_vccz .LBB0_1234
	s_barrier

; #define PG8_STAGE(bufoff, gbase, voff) do { _Pragma("unroll") for (int _i = 0; _i < 2; ++_i) \
;         __builtin_amdgcn_global_load_lds((const unsigned*)((const char*)(gbase) + (voff)[_i]), (PG8_LAS unsigned*)(lds + (bufoff) + ldsw + _i * 8192), 16, 0, 0); } while (0)
; #define PG8_LDA(dst, b, h) do { _Pragma("unroll") for (int m = 0; m < 4; ++m) _Pragma("unroll") for (int k = 0; k < 2; ++k) dst[m][k] = *(const PG8_LAS bf16x8*)(lds + PG8_SA(b, h) + aoff + m * 2048 + k * 1024); } while (0)
; #define PG8_LDB(dst, b, h) do { _Pragma("unroll") for (int n = 0; n < 2; ++n) _Pragma("unroll") for (int k = 0; k < 2; ++k) dst[n][k] = *(const PG8_LAS bf16x8*)(lds + PG8_SB(b, h) + boff + n * 2048 + k * 1024); } while (0)
; #define PG8_MMA(ai, bj, At, Bt) do { __builtin_amdgcn_s_setprio(1); _Pragma("unroll") for (int m = 0; m < 4; ++m) _Pragma("unroll") for (int n = 0; n < 2; ++n) _Pragma("unroll") for (int k = 0; k < 2; ++k) \
;         acc[ai][bj][m][n] = __builtin_amdgcn_mfma_f32_16x16x32_bf16(Bt[n][k], At[m][k], acc[ai][bj][m][n], 0, 0, 0); __builtin_amdgcn_s_setprio(0); } while (0)
; #define PG8_WAIT_V(n) asm volatile("s_waitcnt vmcnt(" #n ")" ::: "memory")
; #define PG8_BAR __builtin_amdgcn_s_barrier()
; template <class Epi, class Sched, bool ALIGN_EPI = false, bool SP2 = false>
; __device__ __forceinline__ void gemm_phase(PG8_LAS unsigned char* lds, const Gemm g, const Sched& S, const Epi& E, const int wave0) {
;     ...
;         for (int t = 0; t < nt; t += 2) {
;             const bool last = (t == nt - 2);
;             const char* a1 = cA + (size_t)(t + 1) * kstep;
;             const char* a2 = last ? nA : cA + (size_t)(t + 2) * kstep; const char* b2 = last ? nB : cB + (size_t)(t + 2) * kstep;
;             const char* a3 = a2 + kstep; const char* b3 = b2 + kstep;
;             if (last && has_next) S.a_ready(nxt);
;             if constexpr (SP2) {
;             PG8_LDB(B0, 0, 0); PG8_LDB(B1, 0, 1); PG8_SCHED; PG8_LDA(At, 0, 0); PG8_STAGE(PG8_SA(1, 1), a1 + hstepA, voffA);
;             PG8_WAIT_V(8); PG8_WAIT_L(0); PG8_BAR; PG8_MMA(0, 0, At, B0); PG8_MMA(0, 1, At, B1); PG8_BAR; PG8_SCHED;
;             PG8_LDA(At, 0, 1); PG8_STAGE(PG8_SB(0, 0), b2, voffB); PG8_STAGE(PG8_SB(0, 1), b2 + hstepB, voffB); PG8_STAGE(PG8_SA(0, 0), a2, voffA);
;             PG8_WAIT_V(8); PG8_WAIT_L(0); PG8_BAR; PG8_MMA(1, 0, At, B0); PG8_MMA(1, 1, At, B1); PG8_BAR; PG8_SCHED;
.LBB0_1341:
	s_add_u32 s16, s0, 0xfff80080
	s_addc_u32 s17, s1, -1
	s_add_i32 s40, 0, 0x10000
	s_cmp_eq_u32 s37, 28
	s_cselect_b32 s19, s11, s17
	s_cselect_b32 s18, s33, s16
	s_cselect_b32 s17, s9, s36
	s_cselect_b32 s16, s34, s35
	s_add_i32 s42, 0, 0x14000
	ds_read_b128 v[144:147], v252
	ds_read_b128 v[148:151], v252 offset:1024
	ds_read_b128 v[152:155], v252 offset:2048
	ds_read_b128 v[156:159], v252 offset:3072
	ds_read_b128 v[178:181], v253
	ds_read_b128 v[182:185], v253 offset:1024
	ds_read_b128 v[186:189], v253 offset:2048
	ds_read_b128 v[190:193], v253 offset:3072
	s_add_i32 m0, s23, 0xc000
	ds_read_b128 v[194:197], v143
	ds_read_b128 v[208:211], v143 offset:1024
	ds_read_b128 v[212:215], v143 offset:2048
	ds_read_b128 v[216:219], v143 offset:3072
	ds_read_b128 v[220:223], v143 offset:4096
	ds_read_b128 v[224:227], v143 offset:5120
	ds_read_b128 v[228:231], v143 offset:6144
	ds_read_b128 v[232:235], v143 offset:7168
	global_load_lds_dwordx4 v136, s[0:1]
	s_add_i32 m0, s23, 0xe000
	s_nop 0
	global_load_lds_dwordx4 v138, s[0:1]
	s_waitcnt vmcnt(8)
	s_waitcnt lgkmcnt(0)
	s_barrier
	s_setprio 1
	s_waitcnt lgkmcnt(0)
	v_mfma_f32_16x16x32_bf16 v[126:129], v[144:147], v[194:197], v[126:129]
	v_mfma_f32_16x16x32_bf16 v[122:125], v[152:155], v[194:197], v[122:125]
	v_mfma_f32_16x16x32_bf16 v[118:121], v[144:147], v[212:215], v[118:121]
	v_mfma_f32_16x16x32_bf16 v[114:117], v[152:155], v[212:215], v[114:117]
	s_setprio 0
	s_setprio 1
	v_mfma_f32_16x16x32_bf16 v[102:105], v[144:147], v[220:223], v[102:105]
	v_mfma_f32_16x16x32_bf16 v[98:101], v[152:155], v[220:223], v[98:101]
	v_mfma_f32_16x16x32_bf16 v[86:89], v[144:147], v[228:231], v[86:89]
	v_mfma_f32_16x16x32_bf16 v[82:85], v[152:155], v[228:231], v[82:85]
	s_setprio 0
	s_setprio 1
	v_mfma_f32_16x16x32_bf16 v[126:129], v[148:151], v[208:211], v[126:129]
	v_mfma_f32_16x16x32_bf16 v[122:125], v[156:159], v[208:211], v[122:125]
	v_mfma_f32_16x16x32_bf16 v[118:121], v[148:151], v[216:219], v[118:121]
	v_mfma_f32_16x16x32_bf16 v[114:117], v[156:159], v[216:219], v[114:117]
	s_setprio 0
	s_setprio 1
	v_mfma_f32_16x16x32_bf16 v[102:105], v[148:151], v[224:227], v[102:105]
	v_mfma_f32_16x16x32_bf16 v[98:101], v[156:159], v[224:227], v[98:101]
	v_mfma_f32_16x16x32_bf16 v[86:89], v[148:151], v[232:235], v[86:89]
	v_mfma_f32_16x16x32_bf16 v[82:85], v[156:159], v[232:235], v[82:85]
	s_setprio 0
	s_setprio 1
	v_mfma_f32_16x16x32_bf16 v[110:113], v[178:181], v[194:197], v[110:113]
	v_mfma_f32_16x16x32_bf16 v[106:109], v[186:189], v[194:197], v[106:109]
	v_mfma_f32_16x16x32_bf16 v[94:97], v[178:181], v[212:215], v[94:97]
	v_mfma_f32_16x16x32_bf16 v[90:93], v[186:189], v[212:215], v[90:93]
	s_setprio 0
	s_setprio 1
	v_mfma_f32_16x16x32_bf16 v[78:81], v[178:181], v[220:223], v[78:81]
	v_mfma_f32_16x16x32_bf16 v[74:77], v[186:189], v[220:223], v[74:77]
	v_mfma_f32_16x16x32_bf16 v[70:73], v[178:181], v[228:231], v[70:73]
	v_mfma_f32_16x16x32_bf16 v[66:69], v[186:189], v[228:231], v[66:69]
	s_setprio 0
	s_setprio 1
	v_mfma_f32_16x16x32_bf16 v[110:113], v[182:185], v[208:211], v[110:113]
	v_mfma_f32_16x16x32_bf16 v[106:109], v[190:193], v[208:211], v[106:109]
	v_mfma_f32_16x16x32_bf16 v[94:97], v[182:185], v[216:219], v[94:97]
	v_mfma_f32_16x16x32_bf16 v[90:93], v[190:193], v[216:219], v[90:93]
	s_setprio 0
	s_setprio 1
	v_mfma_f32_16x16x32_bf16 v[78:81], v[182:185], v[224:227], v[78:81]
	v_mfma_f32_16x16x32_bf16 v[74:77], v[190:193], v[224:227], v[74:77]
	v_mfma_f32_16x16x32_bf16 v[70:73], v[182:185], v[232:235], v[70:73]
	v_mfma_f32_16x16x32_bf16 v[66:69], v[190:193], v[232:235], v[66:69]
	s_setprio 0
	s_barrier
	s_add_i32 s40, s40, s22
	s_mov_b32 m0, s40
	ds_read_b128 v[194:197], v143 offset:16384
	ds_read_b128 v[208:211], v143 offset:17408
	ds_read_b128 v[212:215], v143 offset:18432
	ds_read_b128 v[216:219], v143 offset:19456
	ds_read_b128 v[220:223], v143 offset:20480
	ds_read_b128 v[224:227], v143 offset:21504
	ds_read_b128 v[228:231], v143 offset:22528
	ds_read_b128 v[232:235], v143 offset:23552
	global_load_lds_dwordx4 v64, s[16:17]
	s_add_i32 m0, s40, 0x2000
	s_add_u32 s40, s16, 0x80000
	s_addc_u32 s41, s17, 0
	s_add_i32 s42, s42, s22
	global_load_lds_dwordx4 v130, s[16:17]
	s_mov_b32 m0, s42
	s_mov_b64 s[100:101], s[18:19]
	global_load_lds_dwordx4 v64, s[40:41]
	s_add_i32 m0, s42, 0x2000
	s_nop 0
	global_load_lds_dwordx4 v130, s[40:41]
	s_mov_b32 m0, s23
	s_nop 0
	global_load_lds_dwordx4 v134, s[18:19]
	s_mov_b32 m0, s24
	s_nop 0
	global_load_lds_dwordx4 v132, s[18:19]
	s_waitcnt vmcnt(8)
	s_waitcnt lgkmcnt(0)
	s_barrier
; #define PG8_STAGE(bufoff, gbase, voff) do { _Pragma("unroll") for (int _i = 0; _i < 2; ++_i) \
;         __builtin_amdgcn_global_load_lds((const unsigned*)((const char*)(gbase) + (voff)[_i]), (PG8_LAS unsigned*)(lds + (bufoff) + ldsw + _i * 8192), 16, 0, 0); } while (0)
; #define PG8_LDA(dst, b, h) do { _Pragma("unroll") for (int m = 0; m < 4; ++m) _Pragma("unroll") for (int k = 0; k < 2; ++k) dst[m][k] = *(const PG8_LAS bf16x8*)(lds + PG8_SA(b, h) + aoff + m * 2048 + k * 1024); } while (0)
; #define PG8_LDB(dst, b, h) do { _Pragma("unroll") for (int n = 0; n < 2; ++n) _Pragma("unroll") for (int k = 0; k < 2; ++k) dst[n][k] = *(const PG8_LAS bf16x8*)(lds + PG8_SB(b, h) + boff + n * 2048 + k * 1024); } while (0)
; #define PG8_MMA(ai, bj, At, Bt) do { __builtin_amdgcn_s_setprio(1); _Pragma("unroll") for (int m = 0; m < 4; ++m) _Pragma("unroll") for (int n = 0; n < 2; ++n) _Pragma("unroll") for (int k = 0; k < 2; ++k) \
;         acc[ai][bj][m][n] = __builtin_amdgcn_mfma_f32_16x16x32_bf16(Bt[n][k], At[m][k], acc[ai][bj][m][n], 0, 0, 0); __builtin_amdgcn_s_setprio(0); } while (0)
; #define PG8_WAIT_V(n) asm volatile("s_waitcnt vmcnt(" #n ")" ::: "memory")
; #define PG8_WAIT_L(n) asm volatile("s_waitcnt lgkmcnt(" #n ")" ::: "memory")
; #define PG8_BAR __builtin_amdgcn_s_barrier()
; #define PG8_SCHED __builtin_amdgcn_sched_barrier(0)
; template <class Epi, class Sched, bool ALIGN_EPI = false, bool SP2 = false>
; __device__ __forceinline__ void gemm_phase(PG8_LAS unsigned char* lds, const Gemm g, const Sched& S, const Epi& E, const int wave0) {
;     ...
;             PG8_WAIT_V(8); PG8_WAIT_L(0); PG8_BAR; PG8_MMA(0, 0, At, B0); PG8_MMA(0, 1, At, B1); PG8_BAR; PG8_SCHED;
;             PG8_LDA(At, 0, 1); PG8_STAGE(PG8_SB(0, 0), b2, voffB); PG8_STAGE(PG8_SB(0, 1), b2 + hstepB, voffB); PG8_STAGE(PG8_SA(0, 0), a2, voffA);
;             PG8_WAIT_V(8); PG8_WAIT_L(0); PG8_BAR; PG8_MMA(1, 0, At, B0); PG8_MMA(1, 1, At, B1); PG8_BAR; PG8_SCHED;
;             PG8_LDB(B0, 1, 0); PG8_LDB(B1, 1, 1); PG8_SCHED; PG8_LDA(At, 1, 0); PG8_STAGE(PG8_SA(0, 1), a2 + hstepA, voffA);
;             PG8_WAIT_V(8); PG8_WAIT_L(0); PG8_BAR; PG8_MMA(0, 0, At, B0); PG8_MMA(0, 1, At, B1); PG8_BAR; PG8_SCHED;
	s_setprio 1
	s_waitcnt lgkmcnt(0)
	v_mfma_f32_16x16x32_bf16 v[60:63], v[144:147], v[194:197], v[60:63]
	v_mfma_f32_16x16x32_bf16 v[56:59], v[152:155], v[194:197], v[56:59]
	v_mfma_f32_16x16x32_bf16 v[52:55], v[144:147], v[212:215], v[52:55]
	v_mfma_f32_16x16x32_bf16 v[48:51], v[152:155], v[212:215], v[48:51]
	s_setprio 0
	s_setprio 1
	v_mfma_f32_16x16x32_bf16 v[36:39], v[144:147], v[220:223], v[36:39]
	v_mfma_f32_16x16x32_bf16 v[32:35], v[152:155], v[220:223], v[32:35]
	v_mfma_f32_16x16x32_bf16 v[20:23], v[144:147], v[228:231], v[20:23]
	v_mfma_f32_16x16x32_bf16 v[16:19], v[152:155], v[228:231], v[16:19]
	s_setprio 0
	s_setprio 1
	v_mfma_f32_16x16x32_bf16 v[60:63], v[148:151], v[208:211], v[60:63]
	v_mfma_f32_16x16x32_bf16 v[56:59], v[156:159], v[208:211], v[56:59]
	v_mfma_f32_16x16x32_bf16 v[52:55], v[148:151], v[216:219], v[52:55]
	v_mfma_f32_16x16x32_bf16 v[48:51], v[156:159], v[216:219], v[48:51]
	s_setprio 0
	s_setprio 1
	v_mfma_f32_16x16x32_bf16 v[36:39], v[148:151], v[224:227], v[36:39]
	v_mfma_f32_16x16x32_bf16 v[32:35], v[156:159], v[224:227], v[32:35]
	v_mfma_f32_16x16x32_bf16 v[20:23], v[148:151], v[232:235], v[20:23]
	v_mfma_f32_16x16x32_bf16 v[16:19], v[156:159], v[232:235], v[16:19]
	s_setprio 0
	s_setprio 1
	v_mfma_f32_16x16x32_bf16 v[44:47], v[178:181], v[194:197], v[44:47]
	v_mfma_f32_16x16x32_bf16 v[40:43], v[186:189], v[194:197], v[40:43]
	v_mfma_f32_16x16x32_bf16 v[28:31], v[178:181], v[212:215], v[28:31]
	v_mfma_f32_16x16x32_bf16 v[24:27], v[186:189], v[212:215], v[24:27]
	s_setprio 0
	s_setprio 1
	v_mfma_f32_16x16x32_bf16 v[12:15], v[178:181], v[220:223], v[12:15]
	v_mfma_f32_16x16x32_bf16 v[8:11], v[186:189], v[220:223], v[8:11]
	v_mfma_f32_16x16x32_bf16 v[4:7], v[178:181], v[228:231], v[4:7]
	v_mfma_f32_16x16x32_bf16 v[0:3], v[186:189], v[228:231], v[0:3]
	s_setprio 0
	s_setprio 1
	v_mfma_f32_16x16x32_bf16 v[44:47], v[182:185], v[208:211], v[44:47]
	v_mfma_f32_16x16x32_bf16 v[40:43], v[190:193], v[208:211], v[40:43]
	v_mfma_f32_16x16x32_bf16 v[28:31], v[182:185], v[216:219], v[28:31]
	v_mfma_f32_16x16x32_bf16 v[24:27], v[190:193], v[216:219], v[24:27]
	s_setprio 0
	s_setprio 1
	v_mfma_f32_16x16x32_bf16 v[12:15], v[182:185], v[224:227], v[12:15]
	v_mfma_f32_16x16x32_bf16 v[8:11], v[190:193], v[224:227], v[8:11]
	v_mfma_f32_16x16x32_bf16 v[4:7], v[182:185], v[232:235], v[4:7]
	v_mfma_f32_16x16x32_bf16 v[0:3], v[190:193], v[232:235], v[0:3]
	s_setprio 0
	s_barrier
	s_add_i32 s40, 0, 0x18000
	s_add_i32 s41, 0, 0x1c000
	ds_read_b128 v[144:147], v254
	ds_read_b128 v[148:151], v254 offset:1024
	ds_read_b128 v[152:155], v254 offset:2048
	ds_read_b128 v[156:159], v254 offset:3072
	ds_read_b128 v[178:181], v255
	ds_read_b128 v[182:185], v255 offset:1024
	ds_read_b128 v[186:189], v255 offset:2048
	ds_read_b128 v[190:193], v255 offset:3072
	s_add_u32 s18, s18, 0x80000
	s_addc_u32 s19, s19, 0
	s_mov_b32 m0, s25
	ds_read_b128 v[194:197], v143 offset:32768
	ds_read_b128 v[208:211], v143 offset:33792
	ds_read_b128 v[212:215], v143 offset:34816
	ds_read_b128 v[216:219], v143 offset:35840
	ds_read_b128 v[220:223], v143 offset:36864
	ds_read_b128 v[224:227], v143 offset:37888
	ds_read_b128 v[228:231], v143 offset:38912
	ds_read_b128 v[232:235], v143 offset:39936
	global_load_lds_dwordx4 v134, s[18:19]
	s_mov_b32 m0, s26
	s_nop 0
	global_load_lds_dwordx4 v132, s[18:19]
	s_waitcnt vmcnt(8)
	s_waitcnt lgkmcnt(0)
	s_barrier
	s_setprio 1
	s_waitcnt lgkmcnt(0)
	v_mfma_f32_16x16x32_bf16 v[126:129], v[144:147], v[194:197], v[126:129]
	v_mfma_f32_16x16x32_bf16 v[122:125], v[152:155], v[194:197], v[122:125]
	v_mfma_f32_16x16x32_bf16 v[118:121], v[144:147], v[212:215], v[118:121]
	v_mfma_f32_16x16x32_bf16 v[114:117], v[152:155], v[212:215], v[114:117]
	s_setprio 0
	s_setprio 1
	v_mfma_f32_16x16x32_bf16 v[102:105], v[144:147], v[220:223], v[102:105]
	v_mfma_f32_16x16x32_bf16 v[98:101], v[152:155], v[220:223], v[98:101]
	v_mfma_f32_16x16x32_bf16 v[86:89], v[144:147], v[228:231], v[86:89]
	v_mfma_f32_16x16x32_bf16 v[82:85], v[152:155], v[228:231], v[82:85]
	s_setprio 0
	s_setprio 1
	v_mfma_f32_16x16x32_bf16 v[126:129], v[148:151], v[208:211], v[126:129]
	v_mfma_f32_16x16x32_bf16 v[122:125], v[156:159], v[208:211], v[122:125]
	v_mfma_f32_16x16x32_bf16 v[118:121], v[148:151], v[216:219], v[118:121]
	v_mfma_f32_16x16x32_bf16 v[114:117], v[156:159], v[216:219], v[114:117]
	s_setprio 0
	s_setprio 1
	v_mfma_f32_16x16x32_bf16 v[102:105], v[148:151], v[224:227], v[102:105]
	v_mfma_f32_16x16x32_bf16 v[98:101], v[156:159], v[224:227], v[98:101]
	v_mfma_f32_16x16x32_bf16 v[86:89], v[148:151], v[232:235], v[86:89]
	v_mfma_f32_16x16x32_bf16 v[82:85], v[156:159], v[232:235], v[82:85]
	s_setprio 0
	s_setprio 1
	v_mfma_f32_16x16x32_bf16 v[110:113], v[178:181], v[194:197], v[110:113]
	v_mfma_f32_16x16x32_bf16 v[106:109], v[186:189], v[194:197], v[106:109]
	v_mfma_f32_16x16x32_bf16 v[94:97], v[178:181], v[212:215], v[94:97]
	v_mfma_f32_16x16x32_bf16 v[90:93], v[186:189], v[212:215], v[90:93]
	s_setprio 0
	s_setprio 1
	v_mfma_f32_16x16x32_bf16 v[78:81], v[178:181], v[220:223], v[78:81]
	v_mfma_f32_16x16x32_bf16 v[74:77], v[186:189], v[220:223], v[74:77]
	v_mfma_f32_16x16x32_bf16 v[70:73], v[178:181], v[228:231], v[70:73]
	v_mfma_f32_16x16x32_bf16 v[66:69], v[186:189], v[228:231], v[66:69]
	s_setprio 0
	s_setprio 1
	v_mfma_f32_16x16x32_bf16 v[110:113], v[182:185], v[208:211], v[110:113]
	v_mfma_f32_16x16x32_bf16 v[106:109], v[190:193], v[208:211], v[106:109]
	v_mfma_f32_16x16x32_bf16 v[94:97], v[182:185], v[216:219], v[94:97]
	v_mfma_f32_16x16x32_bf16 v[90:93], v[190:193], v[216:219], v[90:93]
	s_setprio 0
	s_setprio 1
	v_mfma_f32_16x16x32_bf16 v[78:81], v[182:185], v[224:227], v[78:81]
	v_mfma_f32_16x16x32_bf16 v[74:77], v[190:193], v[224:227], v[74:77]
	v_mfma_f32_16x16x32_bf16 v[70:73], v[182:185], v[232:235], v[70:73]
	v_mfma_f32_16x16x32_bf16 v[66:69], v[190:193], v[232:235], v[66:69]
	s_setprio 0
	s_barrier
; #define PG8_STAGE(bufoff, gbase, voff) do { _Pragma("unroll") for (int _i = 0; _i < 2; ++_i) \
;         __builtin_amdgcn_global_load_lds((const unsigned*)((const char*)(gbase) + (voff)[_i]), (PG8_LAS unsigned*)(lds + (bufoff) + ldsw + _i * 8192), 16, 0, 0); } while (0)
; #define PG8_LDA(dst, b, h) do { _Pragma("unroll") for (int m = 0; m < 4; ++m) _Pragma("unroll") for (int k = 0; k < 2; ++k) dst[m][k] = *(const PG8_LAS bf16x8*)(lds + PG8_SA(b, h) + aoff + m * 2048 + k * 1024); } while (0)
; #define PG8_MMA(ai, bj, At, Bt) do { __builtin_amdgcn_s_setprio(1); _Pragma("unroll") for (int m = 0; m < 4; ++m) _Pragma("unroll") for (int n = 0; n < 2; ++n) _Pragma("unroll") for (int k = 0; k < 2; ++k) \
;         acc[ai][bj][m][n] = __builtin_amdgcn_mfma_f32_16x16x32_bf16(Bt[n][k], At[m][k], acc[ai][bj][m][n], 0, 0, 0); __builtin_amdgcn_s_setprio(0); } while (0)
; #define PG8_WAIT_V(n) asm volatile("s_waitcnt vmcnt(" #n ")" ::: "memory")
; #define PG8_WAIT_L(n) asm volatile("s_waitcnt lgkmcnt(" #n ")" ::: "memory")
; #define PG8_BAR __builtin_amdgcn_s_barrier()
; #define PG8_SCHED __builtin_amdgcn_sched_barrier(0)
; template <class Epi, class Sched, bool ALIGN_EPI = false, bool SP2 = false>
; __device__ __forceinline__ void gemm_phase(PG8_LAS unsigned char* lds, const Gemm g, const Sched& S, const Epi& E, const int wave0) {
;     ...
;         for (int t = 0; t < nt; t += 2) {
;             const bool last = (t == nt - 2);
;     ...
;             PG8_LDA(At, 1, 1); PG8_STAGE(PG8_SB(1, 0), b3, voffB); PG8_STAGE(PG8_SB(1, 1), b3 + hstepB, voffB); PG8_STAGE(PG8_SA(1, 0), a3, voffA);
;             PG8_WAIT_V(8); PG8_WAIT_L(0); PG8_BAR; PG8_MMA(1, 0, At, B0); PG8_MMA(1, 1, At, B1); PG8_BAR; PG8_SCHED;
	s_add_i32 s18, s40, s22
	s_add_u32 s44, s16, 0x80
	s_addc_u32 s45, s17, 0
	s_mov_b32 m0, s18
	ds_read_b128 v[194:197], v143 offset:49152
	ds_read_b128 v[208:211], v143 offset:50176
	ds_read_b128 v[212:215], v143 offset:51200
	ds_read_b128 v[216:219], v143 offset:52224
	ds_read_b128 v[220:223], v143 offset:53248
	ds_read_b128 v[224:227], v143 offset:54272
	ds_read_b128 v[228:231], v143 offset:55296
	ds_read_b128 v[232:235], v143 offset:56320
	global_load_lds_dwordx4 v64, s[44:45]
	s_add_i32 m0, s18, 0x2000
	s_add_u32 s16, s16, 0x80080
	s_addc_u32 s17, s17, 0
	s_add_i32 s18, s41, s22
	global_load_lds_dwordx4 v130, s[44:45]
	s_mov_b32 m0, s18
	s_nop 0
	global_load_lds_dwordx4 v64, s[16:17]
	s_add_i32 m0, s18, 0x2000
	s_nop 0
	global_load_lds_dwordx4 v130, s[16:17]
	s_add_u32 s100, s100, 0x80
	s_addc_u32 s101, s101, 0
	s_mov_b32 m0, s27
	s_nop 0
	global_load_lds_dwordx4 v134, s[100:101]
	s_mov_b32 m0, s28
	s_nop 0
	global_load_lds_dwordx4 v132, s[100:101]
	s_waitcnt vmcnt(8)
	s_waitcnt lgkmcnt(0)
	s_barrier
	s_setprio 1
	s_waitcnt lgkmcnt(0)
	v_mfma_f32_16x16x32_bf16 v[60:63], v[144:147], v[194:197], v[60:63]
	v_mfma_f32_16x16x32_bf16 v[56:59], v[152:155], v[194:197], v[56:59]
	v_mfma_f32_16x16x32_bf16 v[52:55], v[144:147], v[212:215], v[52:55]
	v_mfma_f32_16x16x32_bf16 v[48:51], v[152:155], v[212:215], v[48:51]
	s_setprio 0
	s_setprio 1
	v_mfma_f32_16x16x32_bf16 v[36:39], v[144:147], v[220:223], v[36:39]
	v_mfma_f32_16x16x32_bf16 v[32:35], v[152:155], v[220:223], v[32:35]
	v_mfma_f32_16x16x32_bf16 v[20:23], v[144:147], v[228:231], v[20:23]
	v_mfma_f32_16x16x32_bf16 v[16:19], v[152:155], v[228:231], v[16:19]
	s_setprio 0
	s_setprio 1
	v_mfma_f32_16x16x32_bf16 v[60:63], v[148:151], v[208:211], v[60:63]
	v_mfma_f32_16x16x32_bf16 v[56:59], v[156:159], v[208:211], v[56:59]
	v_mfma_f32_16x16x32_bf16 v[52:55], v[148:151], v[216:219], v[52:55]
	v_mfma_f32_16x16x32_bf16 v[48:51], v[156:159], v[216:219], v[48:51]
	s_setprio 0
	s_setprio 1
	v_mfma_f32_16x16x32_bf16 v[36:39], v[148:151], v[224:227], v[36:39]
	v_mfma_f32_16x16x32_bf16 v[32:35], v[156:159], v[224:227], v[32:35]
	v_mfma_f32_16x16x32_bf16 v[20:23], v[148:151], v[232:235], v[20:23]
	v_mfma_f32_16x16x32_bf16 v[16:19], v[156:159], v[232:235], v[16:19]
	s_setprio 0
	s_setprio 1
	v_mfma_f32_16x16x32_bf16 v[44:47], v[178:181], v[194:197], v[44:47]
	v_mfma_f32_16x16x32_bf16 v[40:43], v[186:189], v[194:197], v[40:43]
	v_mfma_f32_16x16x32_bf16 v[28:31], v[178:181], v[212:215], v[28:31]
	v_mfma_f32_16x16x32_bf16 v[24:27], v[186:189], v[212:215], v[24:27]
	s_setprio 0
	s_setprio 1
	v_mfma_f32_16x16x32_bf16 v[12:15], v[178:181], v[220:223], v[12:15]
	v_mfma_f32_16x16x32_bf16 v[8:11], v[186:189], v[220:223], v[8:11]
	v_mfma_f32_16x16x32_bf16 v[4:7], v[178:181], v[228:231], v[4:7]
	v_mfma_f32_16x16x32_bf16 v[0:3], v[186:189], v[228:231], v[0:3]
	s_setprio 0
	s_setprio 1
	v_mfma_f32_16x16x32_bf16 v[44:47], v[182:185], v[208:211], v[44:47]
	v_mfma_f32_16x16x32_bf16 v[40:43], v[190:193], v[208:211], v[40:43]
	v_mfma_f32_16x16x32_bf16 v[28:31], v[182:185], v[216:219], v[28:31]
	v_mfma_f32_16x16x32_bf16 v[24:27], v[190:193], v[216:219], v[24:27]
	s_setprio 0
	s_setprio 1
	v_mfma_f32_16x16x32_bf16 v[12:15], v[182:185], v[224:227], v[12:15]
	v_mfma_f32_16x16x32_bf16 v[8:11], v[190:193], v[224:227], v[8:11]
	v_mfma_f32_16x16x32_bf16 v[4:7], v[182:185], v[232:235], v[4:7]
	v_mfma_f32_16x16x32_bf16 v[0:3], v[190:193], v[232:235], v[0:3]
	s_setprio 0
	s_barrier
	s_add_i32 s37, s37, 2
	s_add_u32 s0, s0, 0x100
	s_addc_u32 s1, s1, 0
	s_add_u32 s35, s35, 0x100
	s_addc_u32 s36, s36, 0
	s_cmp_gt_u32 s37, 29
	s_cbranch_scc0 .LBB0_1341
	s_mov_b64 s[44:45], 0x80
	s_and_b64 vcc, exec, s[6:7]
	s_mov_b64 s[34:35], 0x45000
	s_cbranch_vccz .LBB0_1344
	s_barrier

; #define PG8_STAGE(bufoff, gbase, voff) do { _Pragma("unroll") for (int _i = 0; _i < 2; ++_i) \
;         __builtin_amdgcn_global_load_lds((const unsigned*)((const char*)(gbase) + (voff)[_i]), (PG8_LAS unsigned*)(lds + (bufoff) + ldsw + _i * 8192), 16, 0, 0); } while (0)
; #define PG8_LDA(dst, b, h) do { _Pragma("unroll") for (int m = 0; m < 4; ++m) _Pragma("unroll") for (int k = 0; k < 2; ++k) dst[m][k] = *(const PG8_LAS bf16x8*)(lds + PG8_SA(b, h) + aoff + m * 2048 + k * 1024); } while (0)
; #define PG8_LDB(dst, b, h) do { _Pragma("unroll") for (int n = 0; n < 2; ++n) _Pragma("unroll") for (int k = 0; k < 2; ++k) dst[n][k] = *(const PG8_LAS bf16x8*)(lds + PG8_SB(b, h) + boff + n * 2048 + k * 1024); } while (0)
; #define PG8_MMA(ai, bj, At, Bt) do { __builtin_amdgcn_s_setprio(1); _Pragma("unroll") for (int m = 0; m < 4; ++m) _Pragma("unroll") for (int n = 0; n < 2; ++n) _Pragma("unroll") for (int k = 0; k < 2; ++k) \
;         acc[ai][bj][m][n] = __builtin_amdgcn_mfma_f32_16x16x32_bf16(Bt[n][k], At[m][k], acc[ai][bj][m][n], 0, 0, 0); __builtin_amdgcn_s_setprio(0); } while (0)
; #define PG8_WAIT_V(n) asm volatile("s_waitcnt vmcnt(" #n ")" ::: "memory")
; #define PG8_BAR __builtin_amdgcn_s_barrier()
; template <class Epi, class Sched, bool ALIGN_EPI = false, bool SP2 = false>
; __device__ __forceinline__ void gemm_phase(PG8_LAS unsigned char* lds, const Gemm g, const Sched& S, const Epi& E, const int wave0) {
;     ...
;         for (int t = 0; t < nt; t += 2) {
;             const bool last = (t == nt - 2);
;             const char* a1 = cA + (size_t)(t + 1) * kstep;
;             const char* a2 = last ? nA : cA + (size_t)(t + 2) * kstep; const char* b2 = last ? nB : cB + (size_t)(t + 2) * kstep;
;             const char* a3 = a2 + kstep; const char* b3 = b2 + kstep;
;             if (last && has_next) S.a_ready(nxt);
;             if constexpr (SP2) {
;             PG8_LDB(B0, 0, 0); PG8_LDB(B1, 0, 1); PG8_SCHED; PG8_LDA(At, 0, 0); PG8_STAGE(PG8_SA(1, 1), a1 + hstepA, voffA);
;             PG8_WAIT_V(8); PG8_WAIT_L(0); PG8_BAR; PG8_MMA(0, 0, At, B0); PG8_MMA(0, 1, At, B1); PG8_BAR; PG8_SCHED;
;             PG8_LDA(At, 0, 1); PG8_STAGE(PG8_SB(0, 0), b2, voffB); PG8_STAGE(PG8_SB(0, 1), b2 + hstepB, voffB); PG8_STAGE(PG8_SA(0, 0), a2, voffA);
;             PG8_WAIT_V(8); PG8_WAIT_L(0); PG8_BAR; PG8_MMA(1, 0, At, B0); PG8_MMA(1, 1, At, B1); PG8_BAR; PG8_SCHED;
.LBB0_1360:
	s_add_u32 s16, s0, 0xfff80080
	s_addc_u32 s17, s1, -1
	s_add_i32 s42, 0, 0x10000
	s_cmp_eq_u32 s41, 12
	s_cselect_b32 s19, s5, s17
	s_cselect_b32 s18, s4, s16
	s_cselect_b32 s17, s11, s27
	s_cselect_b32 s16, s13, s15
	s_add_i32 s44, 0, 0x14000
	ds_read_b128 v[144:147], v252
	ds_read_b128 v[148:151], v252 offset:1024
	ds_read_b128 v[152:155], v252 offset:2048
	ds_read_b128 v[156:159], v252 offset:3072
	ds_read_b128 v[178:181], v253
	ds_read_b128 v[182:185], v253 offset:1024
	ds_read_b128 v[186:189], v253 offset:2048
	ds_read_b128 v[190:193], v253 offset:3072
	s_add_i32 m0, s23, 0xc000
	ds_read_b128 v[194:197], v143
	ds_read_b128 v[208:211], v143 offset:1024
	ds_read_b128 v[212:215], v143 offset:2048
	ds_read_b128 v[216:219], v143 offset:3072
	ds_read_b128 v[220:223], v143 offset:4096
	ds_read_b128 v[224:227], v143 offset:5120
	ds_read_b128 v[228:231], v143 offset:6144
	ds_read_b128 v[232:235], v143 offset:7168
	global_load_lds_dwordx4 v136, s[0:1]
	s_add_i32 m0, s23, 0xe000
	s_nop 0
	global_load_lds_dwordx4 v138, s[0:1]
	s_waitcnt vmcnt(8)
	s_waitcnt lgkmcnt(0)
	s_barrier
	s_setprio 1
	s_waitcnt lgkmcnt(0)
	v_mfma_f32_16x16x32_bf16 v[126:129], v[144:147], v[194:197], v[126:129]
	v_mfma_f32_16x16x32_bf16 v[122:125], v[152:155], v[194:197], v[122:125]
	v_mfma_f32_16x16x32_bf16 v[118:121], v[144:147], v[212:215], v[118:121]
	v_mfma_f32_16x16x32_bf16 v[114:117], v[152:155], v[212:215], v[114:117]
	s_setprio 0
	s_setprio 1
	v_mfma_f32_16x16x32_bf16 v[102:105], v[144:147], v[220:223], v[102:105]
	v_mfma_f32_16x16x32_bf16 v[98:101], v[152:155], v[220:223], v[98:101]
	v_mfma_f32_16x16x32_bf16 v[86:89], v[144:147], v[228:231], v[86:89]
	v_mfma_f32_16x16x32_bf16 v[82:85], v[152:155], v[228:231], v[82:85]
	s_setprio 0
	s_setprio 1
	v_mfma_f32_16x16x32_bf16 v[126:129], v[148:151], v[208:211], v[126:129]
	v_mfma_f32_16x16x32_bf16 v[122:125], v[156:159], v[208:211], v[122:125]
	v_mfma_f32_16x16x32_bf16 v[118:121], v[148:151], v[216:219], v[118:121]
	v_mfma_f32_16x16x32_bf16 v[114:117], v[156:159], v[216:219], v[114:117]
	s_setprio 0
	s_setprio 1
	v_mfma_f32_16x16x32_bf16 v[102:105], v[148:151], v[224:227], v[102:105]
	v_mfma_f32_16x16x32_bf16 v[98:101], v[156:159], v[224:227], v[98:101]
	v_mfma_f32_16x16x32_bf16 v[86:89], v[148:151], v[232:235], v[86:89]
	v_mfma_f32_16x16x32_bf16 v[82:85], v[156:159], v[232:235], v[82:85]
	s_setprio 0
	s_setprio 1
	v_mfma_f32_16x16x32_bf16 v[110:113], v[178:181], v[194:197], v[110:113]
	v_mfma_f32_16x16x32_bf16 v[106:109], v[186:189], v[194:197], v[106:109]
	v_mfma_f32_16x16x32_bf16 v[94:97], v[178:181], v[212:215], v[94:97]
	v_mfma_f32_16x16x32_bf16 v[90:93], v[186:189], v[212:215], v[90:93]
	s_setprio 0
	s_setprio 1
	v_mfma_f32_16x16x32_bf16 v[78:81], v[178:181], v[220:223], v[78:81]
	v_mfma_f32_16x16x32_bf16 v[74:77], v[186:189], v[220:223], v[74:77]
	v_mfma_f32_16x16x32_bf16 v[70:73], v[178:181], v[228:231], v[70:73]
	v_mfma_f32_16x16x32_bf16 v[66:69], v[186:189], v[228:231], v[66:69]
	s_setprio 0
	s_setprio 1
	v_mfma_f32_16x16x32_bf16 v[110:113], v[182:185], v[208:211], v[110:113]
	v_mfma_f32_16x16x32_bf16 v[106:109], v[190:193], v[208:211], v[106:109]
	v_mfma_f32_16x16x32_bf16 v[94:97], v[182:185], v[216:219], v[94:97]
	v_mfma_f32_16x16x32_bf16 v[90:93], v[190:193], v[216:219], v[90:93]
	s_setprio 0
	s_setprio 1
	v_mfma_f32_16x16x32_bf16 v[78:81], v[182:185], v[224:227], v[78:81]
	v_mfma_f32_16x16x32_bf16 v[74:77], v[190:193], v[224:227], v[74:77]
	v_mfma_f32_16x16x32_bf16 v[70:73], v[182:185], v[232:235], v[70:73]
	v_mfma_f32_16x16x32_bf16 v[66:69], v[190:193], v[232:235], v[66:69]
	s_setprio 0
	s_barrier
	s_add_i32 s42, s42, s22
	s_mov_b32 m0, s42
	ds_read_b128 v[194:197], v143 offset:16384
	ds_read_b128 v[208:211], v143 offset:17408
	ds_read_b128 v[212:215], v143 offset:18432
	ds_read_b128 v[216:219], v143 offset:19456
	ds_read_b128 v[220:223], v143 offset:20480
	ds_read_b128 v[224:227], v143 offset:21504
	ds_read_b128 v[228:231], v143 offset:22528
	ds_read_b128 v[232:235], v143 offset:23552
	global_load_lds_dwordx4 v64, s[16:17]
	s_add_i32 m0, s42, 0x2000
	s_add_u32 s42, s16, 0x80000
	s_addc_u32 s43, s17, 0
	s_add_i32 s44, s44, s22
	global_load_lds_dwordx4 v130, s[16:17]
	s_mov_b32 m0, s44
	s_mov_b64 s[100:101], s[18:19]
	global_load_lds_dwordx4 v64, s[42:43]
	s_add_i32 m0, s44, 0x2000
	s_nop 0
	global_load_lds_dwordx4 v130, s[42:43]
	s_mov_b32 m0, s23
	s_nop 0
	global_load_lds_dwordx4 v134, s[18:19]
	s_mov_b32 m0, s24
	s_nop 0
	global_load_lds_dwordx4 v132, s[18:19]
	s_waitcnt vmcnt(8)
	s_waitcnt lgkmcnt(0)
	s_barrier
; #define PG8_STAGE(bufoff, gbase, voff) do { _Pragma("unroll") for (int _i = 0; _i < 2; ++_i) \
;         __builtin_amdgcn_global_load_lds((const unsigned*)((const char*)(gbase) + (voff)[_i]), (PG8_LAS unsigned*)(lds + (bufoff) + ldsw + _i * 8192), 16, 0, 0); } while (0)
; #define PG8_LDA(dst, b, h) do { _Pragma("unroll") for (int m = 0; m < 4; ++m) _Pragma("unroll") for (int k = 0; k < 2; ++k) dst[m][k] = *(const PG8_LAS bf16x8*)(lds + PG8_SA(b, h) + aoff + m * 2048 + k * 1024); } while (0)
; #define PG8_LDB(dst, b, h) do { _Pragma("unroll") for (int n = 0; n < 2; ++n) _Pragma("unroll") for (int k = 0; k < 2; ++k) dst[n][k] = *(const PG8_LAS bf16x8*)(lds + PG8_SB(b, h) + boff + n * 2048 + k * 1024); } while (0)
; #define PG8_MMA(ai, bj, At, Bt) do { __builtin_amdgcn_s_setprio(1); _Pragma("unroll") for (int m = 0; m < 4; ++m) _Pragma("unroll") for (int n = 0; n < 2; ++n) _Pragma("unroll") for (int k = 0; k < 2; ++k) \
;         acc[ai][bj][m][n] = __builtin_amdgcn_mfma_f32_16x16x32_bf16(Bt[n][k], At[m][k], acc[ai][bj][m][n], 0, 0, 0); __builtin_amdgcn_s_setprio(0); } while (0)
; #define PG8_WAIT_V(n) asm volatile("s_waitcnt vmcnt(" #n ")" ::: "memory")
; #define PG8_WAIT_L(n) asm volatile("s_waitcnt lgkmcnt(" #n ")" ::: "memory")
; #define PG8_BAR __builtin_amdgcn_s_barrier()
; #define PG8_SCHED __builtin_amdgcn_sched_barrier(0)
; template <class Epi, class Sched, bool ALIGN_EPI = false, bool SP2 = false>
; __device__ __forceinline__ void gemm_phase(PG8_LAS unsigned char* lds, const Gemm g, const Sched& S, const Epi& E, const int wave0) {
;     ...
;             PG8_WAIT_V(8); PG8_WAIT_L(0); PG8_BAR; PG8_MMA(0, 0, At, B0); PG8_MMA(0, 1, At, B1); PG8_BAR; PG8_SCHED;
;             PG8_LDA(At, 0, 1); PG8_STAGE(PG8_SB(0, 0), b2, voffB); PG8_STAGE(PG8_SB(0, 1), b2 + hstepB, voffB); PG8_STAGE(PG8_SA(0, 0), a2, voffA);
;             PG8_WAIT_V(8); PG8_WAIT_L(0); PG8_BAR; PG8_MMA(1, 0, At, B0); PG8_MMA(1, 1, At, B1); PG8_BAR; PG8_SCHED;
;             PG8_LDB(B0, 1, 0); PG8_LDB(B1, 1, 1); PG8_SCHED; PG8_LDA(At, 1, 0); PG8_STAGE(PG8_SA(0, 1), a2 + hstepA, voffA);
;             PG8_WAIT_V(8); PG8_WAIT_L(0); PG8_BAR; PG8_MMA(0, 0, At, B0); PG8_MMA(0, 1, At, B1); PG8_BAR; PG8_SCHED;
	s_setprio 1
	s_waitcnt lgkmcnt(0)
	v_mfma_f32_16x16x32_bf16 v[60:63], v[144:147], v[194:197], v[60:63]
	v_mfma_f32_16x16x32_bf16 v[56:59], v[152:155], v[194:197], v[56:59]
	v_mfma_f32_16x16x32_bf16 v[52:55], v[144:147], v[212:215], v[52:55]
	v_mfma_f32_16x16x32_bf16 v[48:51], v[152:155], v[212:215], v[48:51]
	s_setprio 0
	s_setprio 1
	v_mfma_f32_16x16x32_bf16 v[36:39], v[144:147], v[220:223], v[36:39]
	v_mfma_f32_16x16x32_bf16 v[32:35], v[152:155], v[220:223], v[32:35]
	v_mfma_f32_16x16x32_bf16 v[20:23], v[144:147], v[228:231], v[20:23]
	v_mfma_f32_16x16x32_bf16 v[16:19], v[152:155], v[228:231], v[16:19]
	s_setprio 0
	s_setprio 1
	v_mfma_f32_16x16x32_bf16 v[60:63], v[148:151], v[208:211], v[60:63]
	v_mfma_f32_16x16x32_bf16 v[56:59], v[156:159], v[208:211], v[56:59]
	v_mfma_f32_16x16x32_bf16 v[52:55], v[148:151], v[216:219], v[52:55]
	v_mfma_f32_16x16x32_bf16 v[48:51], v[156:159], v[216:219], v[48:51]
	s_setprio 0
	s_setprio 1
	v_mfma_f32_16x16x32_bf16 v[36:39], v[148:151], v[224:227], v[36:39]
	v_mfma_f32_16x16x32_bf16 v[32:35], v[156:159], v[224:227], v[32:35]
	v_mfma_f32_16x16x32_bf16 v[20:23], v[148:151], v[232:235], v[20:23]
	v_mfma_f32_16x16x32_bf16 v[16:19], v[156:159], v[232:235], v[16:19]
	s_setprio 0
	s_setprio 1
	v_mfma_f32_16x16x32_bf16 v[44:47], v[178:181], v[194:197], v[44:47]
	v_mfma_f32_16x16x32_bf16 v[40:43], v[186:189], v[194:197], v[40:43]
	v_mfma_f32_16x16x32_bf16 v[28:31], v[178:181], v[212:215], v[28:31]
	v_mfma_f32_16x16x32_bf16 v[24:27], v[186:189], v[212:215], v[24:27]
	s_setprio 0
	s_setprio 1
	v_mfma_f32_16x16x32_bf16 v[12:15], v[178:181], v[220:223], v[12:15]
	v_mfma_f32_16x16x32_bf16 v[8:11], v[186:189], v[220:223], v[8:11]
	v_mfma_f32_16x16x32_bf16 v[4:7], v[178:181], v[228:231], v[4:7]
	v_mfma_f32_16x16x32_bf16 v[0:3], v[186:189], v[228:231], v[0:3]
	s_setprio 0
	s_setprio 1
	v_mfma_f32_16x16x32_bf16 v[44:47], v[182:185], v[208:211], v[44:47]
	v_mfma_f32_16x16x32_bf16 v[40:43], v[190:193], v[208:211], v[40:43]
	v_mfma_f32_16x16x32_bf16 v[28:31], v[182:185], v[216:219], v[28:31]
	v_mfma_f32_16x16x32_bf16 v[24:27], v[190:193], v[216:219], v[24:27]
	s_setprio 0
	s_setprio 1
	v_mfma_f32_16x16x32_bf16 v[12:15], v[182:185], v[224:227], v[12:15]
	v_mfma_f32_16x16x32_bf16 v[8:11], v[190:193], v[224:227], v[8:11]
	v_mfma_f32_16x16x32_bf16 v[4:7], v[182:185], v[232:235], v[4:7]
	v_mfma_f32_16x16x32_bf16 v[0:3], v[190:193], v[232:235], v[0:3]
	s_setprio 0
	s_barrier
	s_add_i32 s42, 0, 0x18000
	s_add_i32 s43, 0, 0x1c000
	ds_read_b128 v[144:147], v254
	ds_read_b128 v[148:151], v254 offset:1024
	ds_read_b128 v[152:155], v254 offset:2048
	ds_read_b128 v[156:159], v254 offset:3072
	ds_read_b128 v[178:181], v255
	ds_read_b128 v[182:185], v255 offset:1024
	ds_read_b128 v[186:189], v255 offset:2048
	ds_read_b128 v[190:193], v255 offset:3072
	s_add_u32 s18, s18, 0x80000
	s_addc_u32 s19, s19, 0
	s_mov_b32 m0, s25
	ds_read_b128 v[194:197], v143 offset:32768
	ds_read_b128 v[208:211], v143 offset:33792
	ds_read_b128 v[212:215], v143 offset:34816
	ds_read_b128 v[216:219], v143 offset:35840
	ds_read_b128 v[220:223], v143 offset:36864
	ds_read_b128 v[224:227], v143 offset:37888
	ds_read_b128 v[228:231], v143 offset:38912
	ds_read_b128 v[232:235], v143 offset:39936
	global_load_lds_dwordx4 v134, s[18:19]
	s_mov_b32 m0, s33
	s_nop 0
	global_load_lds_dwordx4 v132, s[18:19]
	s_waitcnt vmcnt(8)
	s_waitcnt lgkmcnt(0)
	s_barrier
	s_setprio 1
	s_waitcnt lgkmcnt(0)
	v_mfma_f32_16x16x32_bf16 v[126:129], v[144:147], v[194:197], v[126:129]
	v_mfma_f32_16x16x32_bf16 v[122:125], v[152:155], v[194:197], v[122:125]
	v_mfma_f32_16x16x32_bf16 v[118:121], v[144:147], v[212:215], v[118:121]
	v_mfma_f32_16x16x32_bf16 v[114:117], v[152:155], v[212:215], v[114:117]
	s_setprio 0
	s_setprio 1
	v_mfma_f32_16x16x32_bf16 v[102:105], v[144:147], v[220:223], v[102:105]
	v_mfma_f32_16x16x32_bf16 v[98:101], v[152:155], v[220:223], v[98:101]
	v_mfma_f32_16x16x32_bf16 v[86:89], v[144:147], v[228:231], v[86:89]
	v_mfma_f32_16x16x32_bf16 v[82:85], v[152:155], v[228:231], v[82:85]
	s_setprio 0
	s_setprio 1
	v_mfma_f32_16x16x32_bf16 v[126:129], v[148:151], v[208:211], v[126:129]
	v_mfma_f32_16x16x32_bf16 v[122:125], v[156:159], v[208:211], v[122:125]
	v_mfma_f32_16x16x32_bf16 v[118:121], v[148:151], v[216:219], v[118:121]
	v_mfma_f32_16x16x32_bf16 v[114:117], v[156:159], v[216:219], v[114:117]
	s_setprio 0
	s_setprio 1
	v_mfma_f32_16x16x32_bf16 v[102:105], v[148:151], v[224:227], v[102:105]
	v_mfma_f32_16x16x32_bf16 v[98:101], v[156:159], v[224:227], v[98:101]
	v_mfma_f32_16x16x32_bf16 v[86:89], v[148:151], v[232:235], v[86:89]
	v_mfma_f32_16x16x32_bf16 v[82:85], v[156:159], v[232:235], v[82:85]
	s_setprio 0
	s_setprio 1
	v_mfma_f32_16x16x32_bf16 v[110:113], v[178:181], v[194:197], v[110:113]
	v_mfma_f32_16x16x32_bf16 v[106:109], v[186:189], v[194:197], v[106:109]
	v_mfma_f32_16x16x32_bf16 v[94:97], v[178:181], v[212:215], v[94:97]
	v_mfma_f32_16x16x32_bf16 v[90:93], v[186:189], v[212:215], v[90:93]
	s_setprio 0
	s_setprio 1
	v_mfma_f32_16x16x32_bf16 v[78:81], v[178:181], v[220:223], v[78:81]
	v_mfma_f32_16x16x32_bf16 v[74:77], v[186:189], v[220:223], v[74:77]
	v_mfma_f32_16x16x32_bf16 v[70:73], v[178:181], v[228:231], v[70:73]
	v_mfma_f32_16x16x32_bf16 v[66:69], v[186:189], v[228:231], v[66:69]
	s_setprio 0
	s_setprio 1
	v_mfma_f32_16x16x32_bf16 v[110:113], v[182:185], v[208:211], v[110:113]
	v_mfma_f32_16x16x32_bf16 v[106:109], v[190:193], v[208:211], v[106:109]
	v_mfma_f32_16x16x32_bf16 v[94:97], v[182:185], v[216:219], v[94:97]
	v_mfma_f32_16x16x32_bf16 v[90:93], v[190:193], v[216:219], v[90:93]
	s_setprio 0
	s_setprio 1
	v_mfma_f32_16x16x32_bf16 v[78:81], v[182:185], v[224:227], v[78:81]
	v_mfma_f32_16x16x32_bf16 v[74:77], v[190:193], v[224:227], v[74:77]
	v_mfma_f32_16x16x32_bf16 v[70:73], v[182:185], v[232:235], v[70:73]
	v_mfma_f32_16x16x32_bf16 v[66:69], v[190:193], v[232:235], v[66:69]
	s_setprio 0
	s_barrier
; #define PG8_STAGE(bufoff, gbase, voff) do { _Pragma("unroll") for (int _i = 0; _i < 2; ++_i) \
;         __builtin_amdgcn_global_load_lds((const unsigned*)((const char*)(gbase) + (voff)[_i]), (PG8_LAS unsigned*)(lds + (bufoff) + ldsw + _i * 8192), 16, 0, 0); } while (0)
; #define PG8_LDA(dst, b, h) do { _Pragma("unroll") for (int m = 0; m < 4; ++m) _Pragma("unroll") for (int k = 0; k < 2; ++k) dst[m][k] = *(const PG8_LAS bf16x8*)(lds + PG8_SA(b, h) + aoff + m * 2048 + k * 1024); } while (0)
; #define PG8_MMA(ai, bj, At, Bt) do { __builtin_amdgcn_s_setprio(1); _Pragma("unroll") for (int m = 0; m < 4; ++m) _Pragma("unroll") for (int n = 0; n < 2; ++n) _Pragma("unroll") for (int k = 0; k < 2; ++k) \
;         acc[ai][bj][m][n] = __builtin_amdgcn_mfma_f32_16x16x32_bf16(Bt[n][k], At[m][k], acc[ai][bj][m][n], 0, 0, 0); __builtin_amdgcn_s_setprio(0); } while (0)
; #define PG8_WAIT_V(n) asm volatile("s_waitcnt vmcnt(" #n ")" ::: "memory")
; #define PG8_WAIT_L(n) asm volatile("s_waitcnt lgkmcnt(" #n ")" ::: "memory")
; #define PG8_BAR __builtin_amdgcn_s_barrier()
; #define PG8_SCHED __builtin_amdgcn_sched_barrier(0)
; template <class Epi, class Sched, bool ALIGN_EPI = false, bool SP2 = false>
; __device__ __forceinline__ void gemm_phase(PG8_LAS unsigned char* lds, const Gemm g, const Sched& S, const Epi& E, const int wave0) {
;     ...
;         for (int t = 0; t < nt; t += 2) {
;             const bool last = (t == nt - 2);
;     ...
;             PG8_LDA(At, 1, 1); PG8_STAGE(PG8_SB(1, 0), b3, voffB); PG8_STAGE(PG8_SB(1, 1), b3 + hstepB, voffB); PG8_STAGE(PG8_SA(1, 0), a3, voffA);
;             PG8_WAIT_V(8); PG8_WAIT_L(0); PG8_BAR; PG8_MMA(1, 0, At, B0); PG8_MMA(1, 1, At, B1); PG8_BAR; PG8_SCHED;
	s_add_i32 s18, s42, s22
	s_add_u32 s46, s16, 0x80
	s_addc_u32 s47, s17, 0
	s_mov_b32 m0, s18
	ds_read_b128 v[194:197], v143 offset:49152
	ds_read_b128 v[208:211], v143 offset:50176
	ds_read_b128 v[212:215], v143 offset:51200
	ds_read_b128 v[216:219], v143 offset:52224
	ds_read_b128 v[220:223], v143 offset:53248
	ds_read_b128 v[224:227], v143 offset:54272
	ds_read_b128 v[228:231], v143 offset:55296
	ds_read_b128 v[232:235], v143 offset:56320
	global_load_lds_dwordx4 v64, s[46:47]
	s_add_i32 m0, s18, 0x2000
	s_add_u32 s16, s16, 0x80080
	s_addc_u32 s17, s17, 0
	s_add_i32 s18, s43, s22
	global_load_lds_dwordx4 v130, s[46:47]
	s_mov_b32 m0, s18
	s_nop 0
	global_load_lds_dwordx4 v64, s[16:17]
	s_add_i32 m0, s18, 0x2000
	s_nop 0
	global_load_lds_dwordx4 v130, s[16:17]
	s_add_u32 s100, s100, 0x80
	s_addc_u32 s101, s101, 0
	s_mov_b32 m0, s34
	s_nop 0
	global_load_lds_dwordx4 v134, s[100:101]
	s_mov_b32 m0, s35
	s_nop 0
	global_load_lds_dwordx4 v132, s[100:101]
	s_waitcnt vmcnt(8)
	s_waitcnt lgkmcnt(0)
	s_barrier
	s_setprio 1
	s_waitcnt lgkmcnt(0)
	v_mfma_f32_16x16x32_bf16 v[60:63], v[144:147], v[194:197], v[60:63]
	v_mfma_f32_16x16x32_bf16 v[56:59], v[152:155], v[194:197], v[56:59]
	v_mfma_f32_16x16x32_bf16 v[52:55], v[144:147], v[212:215], v[52:55]
	v_mfma_f32_16x16x32_bf16 v[48:51], v[152:155], v[212:215], v[48:51]
	s_setprio 0
	s_setprio 1
	v_mfma_f32_16x16x32_bf16 v[36:39], v[144:147], v[220:223], v[36:39]
	v_mfma_f32_16x16x32_bf16 v[32:35], v[152:155], v[220:223], v[32:35]
	v_mfma_f32_16x16x32_bf16 v[20:23], v[144:147], v[228:231], v[20:23]
	v_mfma_f32_16x16x32_bf16 v[16:19], v[152:155], v[228:231], v[16:19]
	s_setprio 0
	s_setprio 1
	v_mfma_f32_16x16x32_bf16 v[60:63], v[148:151], v[208:211], v[60:63]
	v_mfma_f32_16x16x32_bf16 v[56:59], v[156:159], v[208:211], v[56:59]
	v_mfma_f32_16x16x32_bf16 v[52:55], v[148:151], v[216:219], v[52:55]
	v_mfma_f32_16x16x32_bf16 v[48:51], v[156:159], v[216:219], v[48:51]
	s_setprio 0
	s_setprio 1
	v_mfma_f32_16x16x32_bf16 v[36:39], v[148:151], v[224:227], v[36:39]
	v_mfma_f32_16x16x32_bf16 v[32:35], v[156:159], v[224:227], v[32:35]
	v_mfma_f32_16x16x32_bf16 v[20:23], v[148:151], v[232:235], v[20:23]
	v_mfma_f32_16x16x32_bf16 v[16:19], v[156:159], v[232:235], v[16:19]
	s_setprio 0
	s_setprio 1
	v_mfma_f32_16x16x32_bf16 v[44:47], v[178:181], v[194:197], v[44:47]
	v_mfma_f32_16x16x32_bf16 v[40:43], v[186:189], v[194:197], v[40:43]
	v_mfma_f32_16x16x32_bf16 v[28:31], v[178:181], v[212:215], v[28:31]
	v_mfma_f32_16x16x32_bf16 v[24:27], v[186:189], v[212:215], v[24:27]
	s_setprio 0
	s_setprio 1
	v_mfma_f32_16x16x32_bf16 v[12:15], v[178:181], v[220:223], v[12:15]
	v_mfma_f32_16x16x32_bf16 v[8:11], v[186:189], v[220:223], v[8:11]
	v_mfma_f32_16x16x32_bf16 v[4:7], v[178:181], v[228:231], v[4:7]
	v_mfma_f32_16x16x32_bf16 v[0:3], v[186:189], v[228:231], v[0:3]
	s_setprio 0
	s_setprio 1
	v_mfma_f32_16x16x32_bf16 v[44:47], v[182:185], v[208:211], v[44:47]
	v_mfma_f32_16x16x32_bf16 v[40:43], v[190:193], v[208:211], v[40:43]
	v_mfma_f32_16x16x32_bf16 v[28:31], v[182:185], v[216:219], v[28:31]
	v_mfma_f32_16x16x32_bf16 v[24:27], v[190:193], v[216:219], v[24:27]
	s_setprio 0
	s_setprio 1
	v_mfma_f32_16x16x32_bf16 v[12:15], v[182:185], v[224:227], v[12:15]
	v_mfma_f32_16x16x32_bf16 v[8:11], v[190:193], v[224:227], v[8:11]
	v_mfma_f32_16x16x32_bf16 v[4:7], v[182:185], v[232:235], v[4:7]
	v_mfma_f32_16x16x32_bf16 v[0:3], v[190:193], v[232:235], v[0:3]
	s_setprio 0
	s_barrier
	s_add_i32 s41, s41, 2
	s_add_u32 s0, s0, 0x100
	s_addc_u32 s1, s1, 0
	s_add_u32 s15, s15, 0x100
	s_addc_u32 s27, s27, 0
	s_cmp_gt_u32 s41, 13
	s_cbranch_scc0 .LBB0_1360
	s_mov_b64 s[46:47], 0x80
	s_and_b64 vcc, exec, s[8:9]
	s_cbranch_vccz .LBB0_1363
	s_barrier

; #define PG8_STAGE(bufoff, gbase, voff) do { _Pragma("unroll") for (int _i = 0; _i < 2; ++_i) \
;         __builtin_amdgcn_global_load_lds((const unsigned*)((const char*)(gbase) + (voff)[_i]), (PG8_LAS unsigned*)(lds + (bufoff) + ldsw + _i * 8192), 16, 0, 0); } while (0)
; #define PG8_LDA(dst, b, h) do { _Pragma("unroll") for (int m = 0; m < 4; ++m) _Pragma("unroll") for (int k = 0; k < 2; ++k) dst[m][k] = *(const PG8_LAS bf16x8*)(lds + PG8_SA(b, h) + aoff + m * 2048 + k * 1024); } while (0)
; #define PG8_LDB(dst, b, h) do { _Pragma("unroll") for (int n = 0; n < 2; ++n) _Pragma("unroll") for (int k = 0; k < 2; ++k) dst[n][k] = *(const PG8_LAS bf16x8*)(lds + PG8_SB(b, h) + boff + n * 2048 + k * 1024); } while (0)
; #define PG8_MMA(ai, bj, At, Bt) do { __builtin_amdgcn_s_setprio(1); _Pragma("unroll") for (int m = 0; m < 4; ++m) _Pragma("unroll") for (int n = 0; n < 2; ++n) _Pragma("unroll") for (int k = 0; k < 2; ++k) \
;         acc[ai][bj][m][n] = __builtin_amdgcn_mfma_f32_16x16x32_bf16(Bt[n][k], At[m][k], acc[ai][bj][m][n], 0, 0, 0); __builtin_amdgcn_s_setprio(0); } while (0)
; #define PG8_WAIT_V(n) asm volatile("s_waitcnt vmcnt(" #n ")" ::: "memory")
; #define PG8_BAR __builtin_amdgcn_s_barrier()
; template <class Epi, class Sched, bool ALIGN_EPI = false, bool SP2 = false>
; __device__ __forceinline__ void gemm_phase(PG8_LAS unsigned char* lds, const Gemm g, const Sched& S, const Epi& E, const int wave0) {
;     ...
;         for (int t = 0; t < nt; t += 2) {
;             const bool last = (t == nt - 2);
;             const char* a1 = cA + (size_t)(t + 1) * kstep;
;             const char* a2 = last ? nA : cA + (size_t)(t + 2) * kstep; const char* b2 = last ? nB : cB + (size_t)(t + 2) * kstep;
;             const char* a3 = a2 + kstep; const char* b3 = b2 + kstep;
;             if (last && has_next) S.a_ready(nxt);
;             if constexpr (SP2) {
;             PG8_LDB(B0, 0, 0); PG8_LDB(B1, 0, 1); PG8_SCHED; PG8_LDA(At, 0, 0); PG8_STAGE(PG8_SA(1, 1), a1 + hstepA, voffA);
;             PG8_WAIT_V(8); PG8_WAIT_L(0); PG8_BAR; PG8_MMA(0, 0, At, B0); PG8_MMA(0, 1, At, B1); PG8_BAR; PG8_SCHED;
;             PG8_LDA(At, 0, 1); PG8_STAGE(PG8_SB(0, 0), b2, voffB); PG8_STAGE(PG8_SB(0, 1), b2 + hstepB, voffB); PG8_STAGE(PG8_SA(0, 0), a2, voffA);
;             PG8_WAIT_V(8); PG8_WAIT_L(0); PG8_BAR; PG8_MMA(1, 0, At, B0); PG8_MMA(1, 1, At, B1); PG8_BAR; PG8_SCHED;
.LBB0_1571:
	s_add_u32 s16, s0, 0xfff80080
	s_addc_u32 s17, s1, -1
	s_add_i32 s46, 0, 0x10000
	s_cmp_eq_u32 s45, 28
	s_cselect_b32 s19, s9, s17
	s_cselect_b32 s18, s33, s16
	s_cselect_b32 s17, s7, s44
	s_cselect_b32 s16, s36, s37
	s_add_i32 s48, 0, 0x14000
	ds_read_b128 v[140:143], v252
	ds_read_b128 v[148:151], v252 offset:1024
	ds_read_b128 v[152:155], v252 offset:2048
	ds_read_b128 v[156:159], v252 offset:3072
	ds_read_b128 v[178:181], v253
	ds_read_b128 v[182:185], v253 offset:1024
	ds_read_b128 v[186:189], v253 offset:2048
	ds_read_b128 v[190:193], v253 offset:3072
	s_add_i32 m0, s15, 0xc000
	ds_read_b128 v[194:197], v147
	ds_read_b128 v[208:211], v147 offset:1024
	ds_read_b128 v[212:215], v147 offset:2048
	ds_read_b128 v[216:219], v147 offset:3072
	ds_read_b128 v[220:223], v147 offset:4096
	ds_read_b128 v[224:227], v147 offset:5120
	ds_read_b128 v[228:231], v147 offset:6144
	ds_read_b128 v[232:235], v147 offset:7168
	global_load_lds_dwordx4 v136, s[0:1]
	s_add_i32 m0, s15, 0xe000
	s_nop 0
	global_load_lds_dwordx4 v138, s[0:1]
	s_waitcnt vmcnt(8)
	s_waitcnt lgkmcnt(0)
	s_barrier
	s_setprio 1
	s_waitcnt lgkmcnt(0)
	v_mfma_f32_16x16x32_bf16 v[126:129], v[140:143], v[194:197], v[126:129]
	v_mfma_f32_16x16x32_bf16 v[122:125], v[152:155], v[194:197], v[122:125]
	v_mfma_f32_16x16x32_bf16 v[110:113], v[140:143], v[212:215], v[110:113]
	v_mfma_f32_16x16x32_bf16 v[106:109], v[152:155], v[212:215], v[106:109]
	s_setprio 0
	s_setprio 1
	v_mfma_f32_16x16x32_bf16 v[94:97], v[140:143], v[220:223], v[94:97]
	v_mfma_f32_16x16x32_bf16 v[90:93], v[152:155], v[220:223], v[90:93]
	v_mfma_f32_16x16x32_bf16 v[78:81], v[140:143], v[228:231], v[78:81]
	v_mfma_f32_16x16x32_bf16 v[74:77], v[152:155], v[228:231], v[74:77]
	s_setprio 0
	s_setprio 1
	v_mfma_f32_16x16x32_bf16 v[126:129], v[148:151], v[208:211], v[126:129]
	v_mfma_f32_16x16x32_bf16 v[122:125], v[156:159], v[208:211], v[122:125]
	v_mfma_f32_16x16x32_bf16 v[110:113], v[148:151], v[216:219], v[110:113]
	v_mfma_f32_16x16x32_bf16 v[106:109], v[156:159], v[216:219], v[106:109]
	s_setprio 0
	s_setprio 1
	v_mfma_f32_16x16x32_bf16 v[94:97], v[148:151], v[224:227], v[94:97]
	v_mfma_f32_16x16x32_bf16 v[90:93], v[156:159], v[224:227], v[90:93]
	v_mfma_f32_16x16x32_bf16 v[78:81], v[148:151], v[232:235], v[78:81]
	v_mfma_f32_16x16x32_bf16 v[74:77], v[156:159], v[232:235], v[74:77]
	s_setprio 0
	s_setprio 1
	v_mfma_f32_16x16x32_bf16 v[118:121], v[178:181], v[194:197], v[118:121]
	v_mfma_f32_16x16x32_bf16 v[114:117], v[186:189], v[194:197], v[114:117]
	v_mfma_f32_16x16x32_bf16 v[102:105], v[178:181], v[212:215], v[102:105]
	v_mfma_f32_16x16x32_bf16 v[98:101], v[186:189], v[212:215], v[98:101]
	s_setprio 0
	s_setprio 1
	v_mfma_f32_16x16x32_bf16 v[86:89], v[178:181], v[220:223], v[86:89]
	v_mfma_f32_16x16x32_bf16 v[82:85], v[186:189], v[220:223], v[82:85]
	v_mfma_f32_16x16x32_bf16 v[70:73], v[178:181], v[228:231], v[70:73]
	v_mfma_f32_16x16x32_bf16 v[66:69], v[186:189], v[228:231], v[66:69]
	s_setprio 0
	s_setprio 1
	v_mfma_f32_16x16x32_bf16 v[118:121], v[182:185], v[208:211], v[118:121]
	v_mfma_f32_16x16x32_bf16 v[114:117], v[190:193], v[208:211], v[114:117]
	v_mfma_f32_16x16x32_bf16 v[102:105], v[182:185], v[216:219], v[102:105]
	v_mfma_f32_16x16x32_bf16 v[98:101], v[190:193], v[216:219], v[98:101]
	s_setprio 0
	s_setprio 1
	v_mfma_f32_16x16x32_bf16 v[86:89], v[182:185], v[224:227], v[86:89]
	v_mfma_f32_16x16x32_bf16 v[82:85], v[190:193], v[224:227], v[82:85]
	v_mfma_f32_16x16x32_bf16 v[70:73], v[182:185], v[232:235], v[70:73]
	v_mfma_f32_16x16x32_bf16 v[66:69], v[190:193], v[232:235], v[66:69]
	s_setprio 0
	s_barrier
	s_add_i32 s46, s46, s28
	s_mov_b32 m0, s46
	ds_read_b128 v[194:197], v147 offset:16384
	ds_read_b128 v[208:211], v147 offset:17408
	ds_read_b128 v[212:215], v147 offset:18432
	ds_read_b128 v[216:219], v147 offset:19456
	ds_read_b128 v[220:223], v147 offset:20480
	ds_read_b128 v[224:227], v147 offset:21504
	ds_read_b128 v[228:231], v147 offset:22528
	ds_read_b128 v[232:235], v147 offset:23552
	global_load_lds_dwordx4 v64, s[16:17]
	s_add_i32 m0, s46, 0x2000
	s_add_u32 s46, s16, 0x80000
	s_addc_u32 s47, s17, 0
	s_add_i32 s48, s48, s28
	global_load_lds_dwordx4 v130, s[16:17]
	s_mov_b32 m0, s48
	s_mov_b64 s[100:101], s[18:19]
	global_load_lds_dwordx4 v64, s[46:47]
	s_add_i32 m0, s48, 0x2000
	s_nop 0
	global_load_lds_dwordx4 v130, s[46:47]
	s_mov_b32 m0, s15
	s_nop 0
	global_load_lds_dwordx4 v134, s[18:19]
	s_mov_b32 m0, s27
	s_nop 0
	global_load_lds_dwordx4 v132, s[18:19]
	s_waitcnt vmcnt(8)
	s_waitcnt lgkmcnt(0)
	s_barrier
; #define PG8_STAGE(bufoff, gbase, voff) do { _Pragma("unroll") for (int _i = 0; _i < 2; ++_i) \
;         __builtin_amdgcn_global_load_lds((const unsigned*)((const char*)(gbase) + (voff)[_i]), (PG8_LAS unsigned*)(lds + (bufoff) + ldsw + _i * 8192), 16, 0, 0); } while (0)
; #define PG8_LDA(dst, b, h) do { _Pragma("unroll") for (int m = 0; m < 4; ++m) _Pragma("unroll") for (int k = 0; k < 2; ++k) dst[m][k] = *(const PG8_LAS bf16x8*)(lds + PG8_SA(b, h) + aoff + m * 2048 + k * 1024); } while (0)
; #define PG8_LDB(dst, b, h) do { _Pragma("unroll") for (int n = 0; n < 2; ++n) _Pragma("unroll") for (int k = 0; k < 2; ++k) dst[n][k] = *(const PG8_LAS bf16x8*)(lds + PG8_SB(b, h) + boff + n * 2048 + k * 1024); } while (0)
; #define PG8_MMA(ai, bj, At, Bt) do { __builtin_amdgcn_s_setprio(1); _Pragma("unroll") for (int m = 0; m < 4; ++m) _Pragma("unroll") for (int n = 0; n < 2; ++n) _Pragma("unroll") for (int k = 0; k < 2; ++k) \
;         acc[ai][bj][m][n] = __builtin_amdgcn_mfma_f32_16x16x32_bf16(Bt[n][k], At[m][k], acc[ai][bj][m][n], 0, 0, 0); __builtin_amdgcn_s_setprio(0); } while (0)
; #define PG8_WAIT_V(n) asm volatile("s_waitcnt vmcnt(" #n ")" ::: "memory")
; #define PG8_WAIT_L(n) asm volatile("s_waitcnt lgkmcnt(" #n ")" ::: "memory")
; #define PG8_BAR __builtin_amdgcn_s_barrier()
; #define PG8_SCHED __builtin_amdgcn_sched_barrier(0)
; template <class Epi, class Sched, bool ALIGN_EPI = false, bool SP2 = false>
; __device__ __forceinline__ void gemm_phase(PG8_LAS unsigned char* lds, const Gemm g, const Sched& S, const Epi& E, const int wave0) {
;     ...
;             PG8_WAIT_V(8); PG8_WAIT_L(0); PG8_BAR; PG8_MMA(0, 0, At, B0); PG8_MMA(0, 1, At, B1); PG8_BAR; PG8_SCHED;
;             PG8_LDA(At, 0, 1); PG8_STAGE(PG8_SB(0, 0), b2, voffB); PG8_STAGE(PG8_SB(0, 1), b2 + hstepB, voffB); PG8_STAGE(PG8_SA(0, 0), a2, voffA);
;             PG8_WAIT_V(8); PG8_WAIT_L(0); PG8_BAR; PG8_MMA(1, 0, At, B0); PG8_MMA(1, 1, At, B1); PG8_BAR; PG8_SCHED;
;             PG8_LDB(B0, 1, 0); PG8_LDB(B1, 1, 1); PG8_SCHED; PG8_LDA(At, 1, 0); PG8_STAGE(PG8_SA(0, 1), a2 + hstepA, voffA);
;             PG8_WAIT_V(8); PG8_WAIT_L(0); PG8_BAR; PG8_MMA(0, 0, At, B0); PG8_MMA(0, 1, At, B1); PG8_BAR; PG8_SCHED;
	s_setprio 1
	s_waitcnt lgkmcnt(0)
	v_mfma_f32_16x16x32_bf16 v[60:63], v[140:143], v[194:197], v[60:63]
	v_mfma_f32_16x16x32_bf16 v[56:59], v[152:155], v[194:197], v[56:59]
	v_mfma_f32_16x16x32_bf16 v[44:47], v[140:143], v[212:215], v[44:47]
	v_mfma_f32_16x16x32_bf16 v[40:43], v[152:155], v[212:215], v[40:43]
	s_setprio 0
	s_setprio 1
	v_mfma_f32_16x16x32_bf16 v[28:31], v[140:143], v[220:223], v[28:31]
	v_mfma_f32_16x16x32_bf16 v[24:27], v[152:155], v[220:223], v[24:27]
	v_mfma_f32_16x16x32_bf16 v[12:15], v[140:143], v[228:231], v[12:15]
	v_mfma_f32_16x16x32_bf16 v[8:11], v[152:155], v[228:231], v[8:11]
	s_setprio 0
	s_setprio 1
	v_mfma_f32_16x16x32_bf16 v[60:63], v[148:151], v[208:211], v[60:63]
	v_mfma_f32_16x16x32_bf16 v[56:59], v[156:159], v[208:211], v[56:59]
	v_mfma_f32_16x16x32_bf16 v[44:47], v[148:151], v[216:219], v[44:47]
	v_mfma_f32_16x16x32_bf16 v[40:43], v[156:159], v[216:219], v[40:43]
	s_setprio 0
	s_setprio 1
	v_mfma_f32_16x16x32_bf16 v[28:31], v[148:151], v[224:227], v[28:31]
	v_mfma_f32_16x16x32_bf16 v[24:27], v[156:159], v[224:227], v[24:27]
	v_mfma_f32_16x16x32_bf16 v[12:15], v[148:151], v[232:235], v[12:15]
	v_mfma_f32_16x16x32_bf16 v[8:11], v[156:159], v[232:235], v[8:11]
	s_setprio 0
	s_setprio 1
	v_mfma_f32_16x16x32_bf16 v[52:55], v[178:181], v[194:197], v[52:55]
	v_mfma_f32_16x16x32_bf16 v[48:51], v[186:189], v[194:197], v[48:51]
	v_mfma_f32_16x16x32_bf16 v[36:39], v[178:181], v[212:215], v[36:39]
	v_mfma_f32_16x16x32_bf16 v[32:35], v[186:189], v[212:215], v[32:35]
	s_setprio 0
	s_setprio 1
	v_mfma_f32_16x16x32_bf16 v[20:23], v[178:181], v[220:223], v[20:23]
	v_mfma_f32_16x16x32_bf16 v[16:19], v[186:189], v[220:223], v[16:19]
	v_mfma_f32_16x16x32_bf16 v[4:7], v[178:181], v[228:231], v[4:7]
	v_mfma_f32_16x16x32_bf16 v[0:3], v[186:189], v[228:231], v[0:3]
	s_setprio 0
	s_setprio 1
	v_mfma_f32_16x16x32_bf16 v[52:55], v[182:185], v[208:211], v[52:55]
	v_mfma_f32_16x16x32_bf16 v[48:51], v[190:193], v[208:211], v[48:51]
	v_mfma_f32_16x16x32_bf16 v[36:39], v[182:185], v[216:219], v[36:39]
	v_mfma_f32_16x16x32_bf16 v[32:35], v[190:193], v[216:219], v[32:35]
	s_setprio 0
	s_setprio 1
	v_mfma_f32_16x16x32_bf16 v[20:23], v[182:185], v[224:227], v[20:23]
	v_mfma_f32_16x16x32_bf16 v[16:19], v[190:193], v[224:227], v[16:19]
	v_mfma_f32_16x16x32_bf16 v[4:7], v[182:185], v[232:235], v[4:7]
	v_mfma_f32_16x16x32_bf16 v[0:3], v[190:193], v[232:235], v[0:3]
	s_setprio 0
	s_barrier
	s_add_i32 s46, 0, 0x18000
	s_add_i32 s47, 0, 0x1c000
	ds_read_b128 v[140:143], v254
	ds_read_b128 v[148:151], v254 offset:1024
	ds_read_b128 v[152:155], v254 offset:2048
	ds_read_b128 v[156:159], v254 offset:3072
	ds_read_b128 v[178:181], v255
	ds_read_b128 v[182:185], v255 offset:1024
	ds_read_b128 v[186:189], v255 offset:2048
	ds_read_b128 v[190:193], v255 offset:3072
	s_add_u32 s18, s18, 0x80000
	s_addc_u32 s19, s19, 0
	s_mov_b32 m0, s29
	ds_read_b128 v[194:197], v147 offset:32768
	ds_read_b128 v[208:211], v147 offset:33792
	ds_read_b128 v[212:215], v147 offset:34816
	ds_read_b128 v[216:219], v147 offset:35840
	ds_read_b128 v[220:223], v147 offset:36864
	ds_read_b128 v[224:227], v147 offset:37888
	ds_read_b128 v[228:231], v147 offset:38912
	ds_read_b128 v[232:235], v147 offset:39936
	global_load_lds_dwordx4 v134, s[18:19]
	s_mov_b32 m0, s30
	s_nop 0
	global_load_lds_dwordx4 v132, s[18:19]
	s_waitcnt vmcnt(8)
	s_waitcnt lgkmcnt(0)
	s_barrier
	s_setprio 1
	s_waitcnt lgkmcnt(0)
	v_mfma_f32_16x16x32_bf16 v[126:129], v[140:143], v[194:197], v[126:129]
	v_mfma_f32_16x16x32_bf16 v[122:125], v[152:155], v[194:197], v[122:125]
	v_mfma_f32_16x16x32_bf16 v[110:113], v[140:143], v[212:215], v[110:113]
	v_mfma_f32_16x16x32_bf16 v[106:109], v[152:155], v[212:215], v[106:109]
	s_setprio 0
	s_setprio 1
	v_mfma_f32_16x16x32_bf16 v[94:97], v[140:143], v[220:223], v[94:97]
	v_mfma_f32_16x16x32_bf16 v[90:93], v[152:155], v[220:223], v[90:93]
	v_mfma_f32_16x16x32_bf16 v[78:81], v[140:143], v[228:231], v[78:81]
	v_mfma_f32_16x16x32_bf16 v[74:77], v[152:155], v[228:231], v[74:77]
	s_setprio 0
	s_setprio 1
	v_mfma_f32_16x16x32_bf16 v[126:129], v[148:151], v[208:211], v[126:129]
	v_mfma_f32_16x16x32_bf16 v[122:125], v[156:159], v[208:211], v[122:125]
	v_mfma_f32_16x16x32_bf16 v[110:113], v[148:151], v[216:219], v[110:113]
	v_mfma_f32_16x16x32_bf16 v[106:109], v[156:159], v[216:219], v[106:109]
	s_setprio 0
	s_setprio 1
	v_mfma_f32_16x16x32_bf16 v[94:97], v[148:151], v[224:227], v[94:97]
	v_mfma_f32_16x16x32_bf16 v[90:93], v[156:159], v[224:227], v[90:93]
	v_mfma_f32_16x16x32_bf16 v[78:81], v[148:151], v[232:235], v[78:81]
	v_mfma_f32_16x16x32_bf16 v[74:77], v[156:159], v[232:235], v[74:77]
	s_setprio 0
	s_setprio 1
	v_mfma_f32_16x16x32_bf16 v[118:121], v[178:181], v[194:197], v[118:121]
	v_mfma_f32_16x16x32_bf16 v[114:117], v[186:189], v[194:197], v[114:117]
	v_mfma_f32_16x16x32_bf16 v[102:105], v[178:181], v[212:215], v[102:105]
	v_mfma_f32_16x16x32_bf16 v[98:101], v[186:189], v[212:215], v[98:101]
	s_setprio 0
	s_setprio 1
	v_mfma_f32_16x16x32_bf16 v[86:89], v[178:181], v[220:223], v[86:89]
	v_mfma_f32_16x16x32_bf16 v[82:85], v[186:189], v[220:223], v[82:85]
	v_mfma_f32_16x16x32_bf16 v[70:73], v[178:181], v[228:231], v[70:73]
	v_mfma_f32_16x16x32_bf16 v[66:69], v[186:189], v[228:231], v[66:69]
	s_setprio 0
	s_setprio 1
	v_mfma_f32_16x16x32_bf16 v[118:121], v[182:185], v[208:211], v[118:121]
	v_mfma_f32_16x16x32_bf16 v[114:117], v[190:193], v[208:211], v[114:117]
	v_mfma_f32_16x16x32_bf16 v[102:105], v[182:185], v[216:219], v[102:105]
	v_mfma_f32_16x16x32_bf16 v[98:101], v[190:193], v[216:219], v[98:101]
	s_setprio 0
	s_setprio 1
	v_mfma_f32_16x16x32_bf16 v[86:89], v[182:185], v[224:227], v[86:89]
	v_mfma_f32_16x16x32_bf16 v[82:85], v[190:193], v[224:227], v[82:85]
	v_mfma_f32_16x16x32_bf16 v[70:73], v[182:185], v[232:235], v[70:73]
	v_mfma_f32_16x16x32_bf16 v[66:69], v[190:193], v[232:235], v[66:69]
	s_setprio 0
	s_barrier
; #define PG8_STAGE(bufoff, gbase, voff) do { _Pragma("unroll") for (int _i = 0; _i < 2; ++_i) \
;         __builtin_amdgcn_global_load_lds((const unsigned*)((const char*)(gbase) + (voff)[_i]), (PG8_LAS unsigned*)(lds + (bufoff) + ldsw + _i * 8192), 16, 0, 0); } while (0)
; #define PG8_LDA(dst, b, h) do { _Pragma("unroll") for (int m = 0; m < 4; ++m) _Pragma("unroll") for (int k = 0; k < 2; ++k) dst[m][k] = *(const PG8_LAS bf16x8*)(lds + PG8_SA(b, h) + aoff + m * 2048 + k * 1024); } while (0)
; #define PG8_MMA(ai, bj, At, Bt) do { __builtin_amdgcn_s_setprio(1); _Pragma("unroll") for (int m = 0; m < 4; ++m) _Pragma("unroll") for (int n = 0; n < 2; ++n) _Pragma("unroll") for (int k = 0; k < 2; ++k) \
;         acc[ai][bj][m][n] = __builtin_amdgcn_mfma_f32_16x16x32_bf16(Bt[n][k], At[m][k], acc[ai][bj][m][n], 0, 0, 0); __builtin_amdgcn_s_setprio(0); } while (0)
; #define PG8_WAIT_V(n) asm volatile("s_waitcnt vmcnt(" #n ")" ::: "memory")
; #define PG8_WAIT_L(n) asm volatile("s_waitcnt lgkmcnt(" #n ")" ::: "memory")
; #define PG8_BAR __builtin_amdgcn_s_barrier()
; #define PG8_SCHED __builtin_amdgcn_sched_barrier(0)
; template <class Epi, class Sched, bool ALIGN_EPI = false, bool SP2 = false>
; __device__ __forceinline__ void gemm_phase(PG8_LAS unsigned char* lds, const Gemm g, const Sched& S, const Epi& E, const int wave0) {
;     ...
;         for (int t = 0; t < nt; t += 2) {
;             const bool last = (t == nt - 2);
;     ...
;             PG8_LDA(At, 1, 1); PG8_STAGE(PG8_SB(1, 0), b3, voffB); PG8_STAGE(PG8_SB(1, 1), b3 + hstepB, voffB); PG8_STAGE(PG8_SA(1, 0), a3, voffA);
;             PG8_WAIT_V(8); PG8_WAIT_L(0); PG8_BAR; PG8_MMA(1, 0, At, B0); PG8_MMA(1, 1, At, B1); PG8_BAR; PG8_SCHED;
	s_add_i32 s18, s46, s28
	s_add_u32 s50, s16, 0x80
	s_addc_u32 s51, s17, 0
	s_mov_b32 m0, s18
	ds_read_b128 v[194:197], v147 offset:49152
	ds_read_b128 v[208:211], v147 offset:50176
	ds_read_b128 v[212:215], v147 offset:51200
	ds_read_b128 v[216:219], v147 offset:52224
	ds_read_b128 v[220:223], v147 offset:53248
	ds_read_b128 v[224:227], v147 offset:54272
	ds_read_b128 v[228:231], v147 offset:55296
	ds_read_b128 v[232:235], v147 offset:56320
	global_load_lds_dwordx4 v64, s[50:51]
	s_add_i32 m0, s18, 0x2000
	s_add_u32 s16, s16, 0x80080
	s_addc_u32 s17, s17, 0
	s_add_i32 s18, s47, s28
	global_load_lds_dwordx4 v130, s[50:51]
	s_mov_b32 m0, s18
	s_nop 0
	global_load_lds_dwordx4 v64, s[16:17]
	s_add_i32 m0, s18, 0x2000
	s_nop 0
	global_load_lds_dwordx4 v130, s[16:17]
	s_add_u32 s100, s100, 0x80
	s_addc_u32 s101, s101, 0
	s_mov_b32 m0, s31
	s_nop 0
	global_load_lds_dwordx4 v134, s[100:101]
	s_mov_b32 m0, s34
	s_nop 0
	global_load_lds_dwordx4 v132, s[100:101]
	s_waitcnt vmcnt(8)
	s_waitcnt lgkmcnt(0)
	s_barrier
	s_setprio 1
	s_waitcnt lgkmcnt(0)
	v_mfma_f32_16x16x32_bf16 v[60:63], v[140:143], v[194:197], v[60:63]
	v_mfma_f32_16x16x32_bf16 v[56:59], v[152:155], v[194:197], v[56:59]
	v_mfma_f32_16x16x32_bf16 v[44:47], v[140:143], v[212:215], v[44:47]
	v_mfma_f32_16x16x32_bf16 v[40:43], v[152:155], v[212:215], v[40:43]
	s_setprio 0
	s_setprio 1
	v_mfma_f32_16x16x32_bf16 v[28:31], v[140:143], v[220:223], v[28:31]
	v_mfma_f32_16x16x32_bf16 v[24:27], v[152:155], v[220:223], v[24:27]
	v_mfma_f32_16x16x32_bf16 v[12:15], v[140:143], v[228:231], v[12:15]
	v_mfma_f32_16x16x32_bf16 v[8:11], v[152:155], v[228:231], v[8:11]
	s_setprio 0
	s_setprio 1
	v_mfma_f32_16x16x32_bf16 v[60:63], v[148:151], v[208:211], v[60:63]
	v_mfma_f32_16x16x32_bf16 v[56:59], v[156:159], v[208:211], v[56:59]
	v_mfma_f32_16x16x32_bf16 v[44:47], v[148:151], v[216:219], v[44:47]
	v_mfma_f32_16x16x32_bf16 v[40:43], v[156:159], v[216:219], v[40:43]
	s_setprio 0
	s_setprio 1
	v_mfma_f32_16x16x32_bf16 v[28:31], v[148:151], v[224:227], v[28:31]
	v_mfma_f32_16x16x32_bf16 v[24:27], v[156:159], v[224:227], v[24:27]
	v_mfma_f32_16x16x32_bf16 v[12:15], v[148:151], v[232:235], v[12:15]
	v_mfma_f32_16x16x32_bf16 v[8:11], v[156:159], v[232:235], v[8:11]
	s_setprio 0
	s_setprio 1
	v_mfma_f32_16x16x32_bf16 v[52:55], v[178:181], v[194:197], v[52:55]
	v_mfma_f32_16x16x32_bf16 v[48:51], v[186:189], v[194:197], v[48:51]
	v_mfma_f32_16x16x32_bf16 v[36:39], v[178:181], v[212:215], v[36:39]
	v_mfma_f32_16x16x32_bf16 v[32:35], v[186:189], v[212:215], v[32:35]
	s_setprio 0
	s_setprio 1
	v_mfma_f32_16x16x32_bf16 v[20:23], v[178:181], v[220:223], v[20:23]
	v_mfma_f32_16x16x32_bf16 v[16:19], v[186:189], v[220:223], v[16:19]
	v_mfma_f32_16x16x32_bf16 v[4:7], v[178:181], v[228:231], v[4:7]
	v_mfma_f32_16x16x32_bf16 v[0:3], v[186:189], v[228:231], v[0:3]
	s_setprio 0
	s_setprio 1
	v_mfma_f32_16x16x32_bf16 v[52:55], v[182:185], v[208:211], v[52:55]
	v_mfma_f32_16x16x32_bf16 v[48:51], v[190:193], v[208:211], v[48:51]
	v_mfma_f32_16x16x32_bf16 v[36:39], v[182:185], v[216:219], v[36:39]
	v_mfma_f32_16x16x32_bf16 v[32:35], v[190:193], v[216:219], v[32:35]
	s_setprio 0
	s_setprio 1
	v_mfma_f32_16x16x32_bf16 v[20:23], v[182:185], v[224:227], v[20:23]
	v_mfma_f32_16x16x32_bf16 v[16:19], v[190:193], v[224:227], v[16:19]
	v_mfma_f32_16x16x32_bf16 v[4:7], v[182:185], v[232:235], v[4:7]
	v_mfma_f32_16x16x32_bf16 v[0:3], v[190:193], v[232:235], v[0:3]
	s_setprio 0
	s_barrier
	s_add_i32 s45, s45, 2
	s_add_u32 s0, s0, 0x100
	s_addc_u32 s1, s1, 0
	s_add_u32 s37, s37, 0x100
	s_addc_u32 s44, s44, 0
	s_cmp_gt_u32 s45, 29
	s_cbranch_scc0 .LBB0_1571
	s_mov_b64 s[50:51], 0x80
	s_and_b64 vcc, exec, s[4:5]
	s_cbranch_vccz .LBB0_1574
	s_barrier

; #define PG8_STAGE(bufoff, gbase, voff) do { _Pragma("unroll") for (int _i = 0; _i < 2; ++_i) \
;         __builtin_amdgcn_global_load_lds((const unsigned*)((const char*)(gbase) + (voff)[_i]), (PG8_LAS unsigned*)(lds + (bufoff) + ldsw + _i * 8192), 16, 0, 0); } while (0)
; #define PG8_LDA(dst, b, h) do { _Pragma("unroll") for (int m = 0; m < 4; ++m) _Pragma("unroll") for (int k = 0; k < 2; ++k) dst[m][k] = *(const PG8_LAS bf16x8*)(lds + PG8_SA(b, h) + aoff + m * 2048 + k * 1024); } while (0)
; #define PG8_LDB(dst, b, h) do { _Pragma("unroll") for (int n = 0; n < 2; ++n) _Pragma("unroll") for (int k = 0; k < 2; ++k) dst[n][k] = *(const PG8_LAS bf16x8*)(lds + PG8_SB(b, h) + boff + n * 2048 + k * 1024); } while (0)
; #define PG8_MMA(ai, bj, At, Bt) do { __builtin_amdgcn_s_setprio(1); _Pragma("unroll") for (int m = 0; m < 4; ++m) _Pragma("unroll") for (int n = 0; n < 2; ++n) _Pragma("unroll") for (int k = 0; k < 2; ++k) \
;         acc[ai][bj][m][n] = __builtin_amdgcn_mfma_f32_16x16x32_bf16(Bt[n][k], At[m][k], acc[ai][bj][m][n], 0, 0, 0); __builtin_amdgcn_s_setprio(0); } while (0)
; #define PG8_WAIT_V(n) asm volatile("s_waitcnt vmcnt(" #n ")" ::: "memory")
; #define PG8_BAR __builtin_amdgcn_s_barrier()
; template <class Epi, class Sched, bool ALIGN_EPI = false, bool SP2 = false>
; __device__ __forceinline__ void gemm_phase(PG8_LAS unsigned char* lds, const Gemm g, const Sched& S, const Epi& E, const int wave0) {
;     ...
;         for (int t = 0; t < nt; t += 2) {
;             const bool last = (t == nt - 2);
;             const char* a1 = cA + (size_t)(t + 1) * kstep;
;             const char* a2 = last ? nA : cA + (size_t)(t + 2) * kstep; const char* b2 = last ? nB : cB + (size_t)(t + 2) * kstep;
;             const char* a3 = a2 + kstep; const char* b3 = b2 + kstep;
;             if (last && has_next) S.a_ready(nxt);
;             if constexpr (SP2) {
;             PG8_LDB(B0, 0, 0); PG8_LDB(B1, 0, 1); PG8_SCHED; PG8_LDA(At, 0, 0); PG8_STAGE(PG8_SA(1, 1), a1 + hstepA, voffA);
;             PG8_WAIT_V(8); PG8_WAIT_L(0); PG8_BAR; PG8_MMA(0, 0, At, B0); PG8_MMA(0, 1, At, B1); PG8_BAR; PG8_SCHED;
;             PG8_LDA(At, 0, 1); PG8_STAGE(PG8_SB(0, 0), b2, voffB); PG8_STAGE(PG8_SB(0, 1), b2 + hstepB, voffB); PG8_STAGE(PG8_SA(0, 0), a2, voffA);
;             PG8_WAIT_V(8); PG8_WAIT_L(0); PG8_BAR; PG8_MMA(1, 0, At, B0); PG8_MMA(1, 1, At, B1); PG8_BAR; PG8_SCHED;
.LBB0_1685:
	s_add_u32 s16, s0, 0xffe00080
	s_addc_u32 s17, s1, -1
	s_add_i32 s43, 0, 0x10000
	s_cmpk_eq_i32 s42, 0x7c
	s_cselect_b32 s19, s11, s17
	s_cselect_b32 s18, s34, s16
	s_cselect_b32 s17, s9, s37
	s_cselect_b32 s16, s35, s36
	s_add_i32 s46, 0, 0x14000
	ds_read_b128 v[144:147], v252
	ds_read_b128 v[148:151], v252 offset:1024
	ds_read_b128 v[152:155], v252 offset:2048
	ds_read_b128 v[156:159], v252 offset:3072
	ds_read_b128 v[178:181], v253
	ds_read_b128 v[182:185], v253 offset:1024
	ds_read_b128 v[186:189], v253 offset:2048
	ds_read_b128 v[190:193], v253 offset:3072
	s_add_i32 m0, s21, 0xc000
	ds_read_b128 v[194:197], v143
	ds_read_b128 v[208:211], v143 offset:1024
	ds_read_b128 v[212:215], v143 offset:2048
	ds_read_b128 v[216:219], v143 offset:3072
	ds_read_b128 v[220:223], v143 offset:4096
	ds_read_b128 v[224:227], v143 offset:5120
	ds_read_b128 v[228:231], v143 offset:6144
	ds_read_b128 v[232:235], v143 offset:7168
	global_load_lds_dwordx4 v136, s[0:1]
	s_add_i32 m0, s21, 0xe000
	s_nop 0
	global_load_lds_dwordx4 v138, s[0:1]
	s_waitcnt vmcnt(8)
	s_waitcnt lgkmcnt(0)
	s_barrier
	s_setprio 1
	s_waitcnt lgkmcnt(0)
	v_mfma_f32_16x16x32_bf16 v[126:129], v[144:147], v[194:197], v[126:129]
	v_mfma_f32_16x16x32_bf16 v[122:125], v[152:155], v[194:197], v[122:125]
	v_mfma_f32_16x16x32_bf16 v[118:121], v[144:147], v[212:215], v[118:121]
	v_mfma_f32_16x16x32_bf16 v[114:117], v[152:155], v[212:215], v[114:117]
	s_setprio 0
	s_setprio 1
	v_mfma_f32_16x16x32_bf16 v[102:105], v[144:147], v[220:223], v[102:105]
	v_mfma_f32_16x16x32_bf16 v[98:101], v[152:155], v[220:223], v[98:101]
	v_mfma_f32_16x16x32_bf16 v[86:89], v[144:147], v[228:231], v[86:89]
	v_mfma_f32_16x16x32_bf16 v[82:85], v[152:155], v[228:231], v[82:85]
	s_setprio 0
	s_setprio 1
	v_mfma_f32_16x16x32_bf16 v[126:129], v[148:151], v[208:211], v[126:129]
	v_mfma_f32_16x16x32_bf16 v[122:125], v[156:159], v[208:211], v[122:125]
	v_mfma_f32_16x16x32_bf16 v[118:121], v[148:151], v[216:219], v[118:121]
	v_mfma_f32_16x16x32_bf16 v[114:117], v[156:159], v[216:219], v[114:117]
	s_setprio 0
	s_setprio 1
	v_mfma_f32_16x16x32_bf16 v[102:105], v[148:151], v[224:227], v[102:105]
	v_mfma_f32_16x16x32_bf16 v[98:101], v[156:159], v[224:227], v[98:101]
	v_mfma_f32_16x16x32_bf16 v[86:89], v[148:151], v[232:235], v[86:89]
	v_mfma_f32_16x16x32_bf16 v[82:85], v[156:159], v[232:235], v[82:85]
	s_setprio 0
	s_setprio 1
	v_mfma_f32_16x16x32_bf16 v[110:113], v[178:181], v[194:197], v[110:113]
	v_mfma_f32_16x16x32_bf16 v[106:109], v[186:189], v[194:197], v[106:109]
	v_mfma_f32_16x16x32_bf16 v[94:97], v[178:181], v[212:215], v[94:97]
	v_mfma_f32_16x16x32_bf16 v[90:93], v[186:189], v[212:215], v[90:93]
	s_setprio 0
	s_setprio 1
	v_mfma_f32_16x16x32_bf16 v[78:81], v[178:181], v[220:223], v[78:81]
	v_mfma_f32_16x16x32_bf16 v[74:77], v[186:189], v[220:223], v[74:77]
	v_mfma_f32_16x16x32_bf16 v[70:73], v[178:181], v[228:231], v[70:73]
	v_mfma_f32_16x16x32_bf16 v[66:69], v[186:189], v[228:231], v[66:69]
	s_setprio 0
	s_setprio 1
	v_mfma_f32_16x16x32_bf16 v[110:113], v[182:185], v[208:211], v[110:113]
	v_mfma_f32_16x16x32_bf16 v[106:109], v[190:193], v[208:211], v[106:109]
	v_mfma_f32_16x16x32_bf16 v[94:97], v[182:185], v[216:219], v[94:97]
	v_mfma_f32_16x16x32_bf16 v[90:93], v[190:193], v[216:219], v[90:93]
	s_setprio 0
	s_setprio 1
	v_mfma_f32_16x16x32_bf16 v[78:81], v[182:185], v[224:227], v[78:81]
	v_mfma_f32_16x16x32_bf16 v[74:77], v[190:193], v[224:227], v[74:77]
	v_mfma_f32_16x16x32_bf16 v[70:73], v[182:185], v[232:235], v[70:73]
	v_mfma_f32_16x16x32_bf16 v[66:69], v[190:193], v[232:235], v[66:69]
	s_setprio 0
	s_barrier
	s_add_i32 s43, s43, s20
	s_mov_b32 m0, s43
	ds_read_b128 v[194:197], v143 offset:16384
	ds_read_b128 v[208:211], v143 offset:17408
	ds_read_b128 v[212:215], v143 offset:18432
	ds_read_b128 v[216:219], v143 offset:19456
	ds_read_b128 v[220:223], v143 offset:20480
	ds_read_b128 v[224:227], v143 offset:21504
	ds_read_b128 v[228:231], v143 offset:22528
	ds_read_b128 v[232:235], v143 offset:23552
	global_load_lds_dwordx4 v64, s[16:17]
	s_add_i32 m0, s43, 0x2000
	s_add_u32 s44, s16, 0x200000
	s_addc_u32 s45, s17, 0
	s_add_i32 s43, s46, s20
	global_load_lds_dwordx4 v130, s[16:17]
	s_mov_b32 m0, s43
	s_mov_b64 s[100:101], s[18:19]
	global_load_lds_dwordx4 v64, s[44:45]
	s_add_i32 m0, s43, 0x2000
	s_nop 0
	global_load_lds_dwordx4 v130, s[44:45]
	s_mov_b32 m0, s21
	s_nop 0
	global_load_lds_dwordx4 v134, s[18:19]
	s_mov_b32 m0, s25
	s_nop 0
	global_load_lds_dwordx4 v132, s[18:19]
	s_waitcnt vmcnt(8)
	s_waitcnt lgkmcnt(0)
	s_barrier
; #define PG8_STAGE(bufoff, gbase, voff) do { _Pragma("unroll") for (int _i = 0; _i < 2; ++_i) \
;         __builtin_amdgcn_global_load_lds((const unsigned*)((const char*)(gbase) + (voff)[_i]), (PG8_LAS unsigned*)(lds + (bufoff) + ldsw + _i * 8192), 16, 0, 0); } while (0)
; #define PG8_LDA(dst, b, h) do { _Pragma("unroll") for (int m = 0; m < 4; ++m) _Pragma("unroll") for (int k = 0; k < 2; ++k) dst[m][k] = *(const PG8_LAS bf16x8*)(lds + PG8_SA(b, h) + aoff + m * 2048 + k * 1024); } while (0)
; #define PG8_LDB(dst, b, h) do { _Pragma("unroll") for (int n = 0; n < 2; ++n) _Pragma("unroll") for (int k = 0; k < 2; ++k) dst[n][k] = *(const PG8_LAS bf16x8*)(lds + PG8_SB(b, h) + boff + n * 2048 + k * 1024); } while (0)
; #define PG8_MMA(ai, bj, At, Bt) do { __builtin_amdgcn_s_setprio(1); _Pragma("unroll") for (int m = 0; m < 4; ++m) _Pragma("unroll") for (int n = 0; n < 2; ++n) _Pragma("unroll") for (int k = 0; k < 2; ++k) \
;         acc[ai][bj][m][n] = __builtin_amdgcn_mfma_f32_16x16x32_bf16(Bt[n][k], At[m][k], acc[ai][bj][m][n], 0, 0, 0); __builtin_amdgcn_s_setprio(0); } while (0)
; #define PG8_WAIT_V(n) asm volatile("s_waitcnt vmcnt(" #n ")" ::: "memory")
; #define PG8_WAIT_L(n) asm volatile("s_waitcnt lgkmcnt(" #n ")" ::: "memory")
; #define PG8_BAR __builtin_amdgcn_s_barrier()
; #define PG8_SCHED __builtin_amdgcn_sched_barrier(0)
; template <class Epi, class Sched, bool ALIGN_EPI = false, bool SP2 = false>
; __device__ __forceinline__ void gemm_phase(PG8_LAS unsigned char* lds, const Gemm g, const Sched& S, const Epi& E, const int wave0) {
;     ...
;             PG8_WAIT_V(8); PG8_WAIT_L(0); PG8_BAR; PG8_MMA(0, 0, At, B0); PG8_MMA(0, 1, At, B1); PG8_BAR; PG8_SCHED;
;             PG8_LDA(At, 0, 1); PG8_STAGE(PG8_SB(0, 0), b2, voffB); PG8_STAGE(PG8_SB(0, 1), b2 + hstepB, voffB); PG8_STAGE(PG8_SA(0, 0), a2, voffA);
;             PG8_WAIT_V(8); PG8_WAIT_L(0); PG8_BAR; PG8_MMA(1, 0, At, B0); PG8_MMA(1, 1, At, B1); PG8_BAR; PG8_SCHED;
;             PG8_LDB(B0, 1, 0); PG8_LDB(B1, 1, 1); PG8_SCHED; PG8_LDA(At, 1, 0); PG8_STAGE(PG8_SA(0, 1), a2 + hstepA, voffA);
;             PG8_WAIT_V(8); PG8_WAIT_L(0); PG8_BAR; PG8_MMA(0, 0, At, B0); PG8_MMA(0, 1, At, B1); PG8_BAR; PG8_SCHED;
	s_setprio 1
	s_waitcnt lgkmcnt(0)
	v_mfma_f32_16x16x32_bf16 v[60:63], v[144:147], v[194:197], v[60:63]
	v_mfma_f32_16x16x32_bf16 v[56:59], v[152:155], v[194:197], v[56:59]
	v_mfma_f32_16x16x32_bf16 v[52:55], v[144:147], v[212:215], v[52:55]
	v_mfma_f32_16x16x32_bf16 v[48:51], v[152:155], v[212:215], v[48:51]
	s_setprio 0
	s_setprio 1
	v_mfma_f32_16x16x32_bf16 v[36:39], v[144:147], v[220:223], v[36:39]
	v_mfma_f32_16x16x32_bf16 v[32:35], v[152:155], v[220:223], v[32:35]
	v_mfma_f32_16x16x32_bf16 v[20:23], v[144:147], v[228:231], v[20:23]
	v_mfma_f32_16x16x32_bf16 v[16:19], v[152:155], v[228:231], v[16:19]
	s_setprio 0
	s_setprio 1
	v_mfma_f32_16x16x32_bf16 v[60:63], v[148:151], v[208:211], v[60:63]
	v_mfma_f32_16x16x32_bf16 v[56:59], v[156:159], v[208:211], v[56:59]
	v_mfma_f32_16x16x32_bf16 v[52:55], v[148:151], v[216:219], v[52:55]
	v_mfma_f32_16x16x32_bf16 v[48:51], v[156:159], v[216:219], v[48:51]
	s_setprio 0
	s_setprio 1
	v_mfma_f32_16x16x32_bf16 v[36:39], v[148:151], v[224:227], v[36:39]
	v_mfma_f32_16x16x32_bf16 v[32:35], v[156:159], v[224:227], v[32:35]
	v_mfma_f32_16x16x32_bf16 v[20:23], v[148:151], v[232:235], v[20:23]
	v_mfma_f32_16x16x32_bf16 v[16:19], v[156:159], v[232:235], v[16:19]
	s_setprio 0
	s_setprio 1
	v_mfma_f32_16x16x32_bf16 v[44:47], v[178:181], v[194:197], v[44:47]
	v_mfma_f32_16x16x32_bf16 v[40:43], v[186:189], v[194:197], v[40:43]
	v_mfma_f32_16x16x32_bf16 v[28:31], v[178:181], v[212:215], v[28:31]
	v_mfma_f32_16x16x32_bf16 v[24:27], v[186:189], v[212:215], v[24:27]
	s_setprio 0
	s_setprio 1
	v_mfma_f32_16x16x32_bf16 v[12:15], v[178:181], v[220:223], v[12:15]
	v_mfma_f32_16x16x32_bf16 v[8:11], v[186:189], v[220:223], v[8:11]
	v_mfma_f32_16x16x32_bf16 v[4:7], v[178:181], v[228:231], v[4:7]
	v_mfma_f32_16x16x32_bf16 v[0:3], v[186:189], v[228:231], v[0:3]
	s_setprio 0
	s_setprio 1
	v_mfma_f32_16x16x32_bf16 v[44:47], v[182:185], v[208:211], v[44:47]
	v_mfma_f32_16x16x32_bf16 v[40:43], v[190:193], v[208:211], v[40:43]
	v_mfma_f32_16x16x32_bf16 v[28:31], v[182:185], v[216:219], v[28:31]
	v_mfma_f32_16x16x32_bf16 v[24:27], v[190:193], v[216:219], v[24:27]
	s_setprio 0
	s_setprio 1
	v_mfma_f32_16x16x32_bf16 v[12:15], v[182:185], v[224:227], v[12:15]
	v_mfma_f32_16x16x32_bf16 v[8:11], v[190:193], v[224:227], v[8:11]
	v_mfma_f32_16x16x32_bf16 v[4:7], v[182:185], v[232:235], v[4:7]
	v_mfma_f32_16x16x32_bf16 v[0:3], v[190:193], v[232:235], v[0:3]
	s_setprio 0
	s_barrier
	s_add_i32 s43, 0, 0x18000
	s_add_i32 s44, 0, 0x1c000
	ds_read_b128 v[144:147], v254
	ds_read_b128 v[148:151], v254 offset:1024
	ds_read_b128 v[152:155], v254 offset:2048
	ds_read_b128 v[156:159], v254 offset:3072
	ds_read_b128 v[178:181], v255
	ds_read_b128 v[182:185], v255 offset:1024
	ds_read_b128 v[186:189], v255 offset:2048
	ds_read_b128 v[190:193], v255 offset:3072
	s_add_u32 s18, s18, 0x200000
	s_addc_u32 s19, s19, 0
	s_mov_b32 m0, s26
	ds_read_b128 v[194:197], v143 offset:32768
	ds_read_b128 v[208:211], v143 offset:33792
	ds_read_b128 v[212:215], v143 offset:34816
	ds_read_b128 v[216:219], v143 offset:35840
	ds_read_b128 v[220:223], v143 offset:36864
	ds_read_b128 v[224:227], v143 offset:37888
	ds_read_b128 v[228:231], v143 offset:38912
	ds_read_b128 v[232:235], v143 offset:39936
	global_load_lds_dwordx4 v134, s[18:19]
	s_mov_b32 m0, s27
	s_nop 0
	global_load_lds_dwordx4 v132, s[18:19]
	s_waitcnt vmcnt(8)
	s_waitcnt lgkmcnt(0)
	s_barrier
	s_setprio 1
	s_waitcnt lgkmcnt(0)
	v_mfma_f32_16x16x32_bf16 v[126:129], v[144:147], v[194:197], v[126:129]
	v_mfma_f32_16x16x32_bf16 v[122:125], v[152:155], v[194:197], v[122:125]
	v_mfma_f32_16x16x32_bf16 v[118:121], v[144:147], v[212:215], v[118:121]
	v_mfma_f32_16x16x32_bf16 v[114:117], v[152:155], v[212:215], v[114:117]
	s_setprio 0
	s_setprio 1
	v_mfma_f32_16x16x32_bf16 v[102:105], v[144:147], v[220:223], v[102:105]
	v_mfma_f32_16x16x32_bf16 v[98:101], v[152:155], v[220:223], v[98:101]
	v_mfma_f32_16x16x32_bf16 v[86:89], v[144:147], v[228:231], v[86:89]
	v_mfma_f32_16x16x32_bf16 v[82:85], v[152:155], v[228:231], v[82:85]
	s_setprio 0
	s_setprio 1
	v_mfma_f32_16x16x32_bf16 v[126:129], v[148:151], v[208:211], v[126:129]
	v_mfma_f32_16x16x32_bf16 v[122:125], v[156:159], v[208:211], v[122:125]
	v_mfma_f32_16x16x32_bf16 v[118:121], v[148:151], v[216:219], v[118:121]
	v_mfma_f32_16x16x32_bf16 v[114:117], v[156:159], v[216:219], v[114:117]
	s_setprio 0
	s_setprio 1
	v_mfma_f32_16x16x32_bf16 v[102:105], v[148:151], v[224:227], v[102:105]
	v_mfma_f32_16x16x32_bf16 v[98:101], v[156:159], v[224:227], v[98:101]
	v_mfma_f32_16x16x32_bf16 v[86:89], v[148:151], v[232:235], v[86:89]
	v_mfma_f32_16x16x32_bf16 v[82:85], v[156:159], v[232:235], v[82:85]
	s_setprio 0
	s_setprio 1
	v_mfma_f32_16x16x32_bf16 v[110:113], v[178:181], v[194:197], v[110:113]
	v_mfma_f32_16x16x32_bf16 v[106:109], v[186:189], v[194:197], v[106:109]
	v_mfma_f32_16x16x32_bf16 v[94:97], v[178:181], v[212:215], v[94:97]
	v_mfma_f32_16x16x32_bf16 v[90:93], v[186:189], v[212:215], v[90:93]
	s_setprio 0
	s_setprio 1
	v_mfma_f32_16x16x32_bf16 v[78:81], v[178:181], v[220:223], v[78:81]
	v_mfma_f32_16x16x32_bf16 v[74:77], v[186:189], v[220:223], v[74:77]
	v_mfma_f32_16x16x32_bf16 v[70:73], v[178:181], v[228:231], v[70:73]
	v_mfma_f32_16x16x32_bf16 v[66:69], v[186:189], v[228:231], v[66:69]
	s_setprio 0
	s_setprio 1
	v_mfma_f32_16x16x32_bf16 v[110:113], v[182:185], v[208:211], v[110:113]
	v_mfma_f32_16x16x32_bf16 v[106:109], v[190:193], v[208:211], v[106:109]
	v_mfma_f32_16x16x32_bf16 v[94:97], v[182:185], v[216:219], v[94:97]
	v_mfma_f32_16x16x32_bf16 v[90:93], v[190:193], v[216:219], v[90:93]
	s_setprio 0
	s_setprio 1
	v_mfma_f32_16x16x32_bf16 v[78:81], v[182:185], v[224:227], v[78:81]
	v_mfma_f32_16x16x32_bf16 v[74:77], v[190:193], v[224:227], v[74:77]
	v_mfma_f32_16x16x32_bf16 v[70:73], v[182:185], v[232:235], v[70:73]
	v_mfma_f32_16x16x32_bf16 v[66:69], v[190:193], v[232:235], v[66:69]
	s_setprio 0
	s_barrier
; #define PG8_STAGE(bufoff, gbase, voff) do { _Pragma("unroll") for (int _i = 0; _i < 2; ++_i) \
;         __builtin_amdgcn_global_load_lds((const unsigned*)((const char*)(gbase) + (voff)[_i]), (PG8_LAS unsigned*)(lds + (bufoff) + ldsw + _i * 8192), 16, 0, 0); } while (0)
; #define PG8_LDA(dst, b, h) do { _Pragma("unroll") for (int m = 0; m < 4; ++m) _Pragma("unroll") for (int k = 0; k < 2; ++k) dst[m][k] = *(const PG8_LAS bf16x8*)(lds + PG8_SA(b, h) + aoff + m * 2048 + k * 1024); } while (0)
; #define PG8_MMA(ai, bj, At, Bt) do { __builtin_amdgcn_s_setprio(1); _Pragma("unroll") for (int m = 0; m < 4; ++m) _Pragma("unroll") for (int n = 0; n < 2; ++n) _Pragma("unroll") for (int k = 0; k < 2; ++k) \
;         acc[ai][bj][m][n] = __builtin_amdgcn_mfma_f32_16x16x32_bf16(Bt[n][k], At[m][k], acc[ai][bj][m][n], 0, 0, 0); __builtin_amdgcn_s_setprio(0); } while (0)
; #define PG8_WAIT_V(n) asm volatile("s_waitcnt vmcnt(" #n ")" ::: "memory")
; #define PG8_WAIT_L(n) asm volatile("s_waitcnt lgkmcnt(" #n ")" ::: "memory")
; #define PG8_BAR __builtin_amdgcn_s_barrier()
; #define PG8_SCHED __builtin_amdgcn_sched_barrier(0)
; template <class Epi, class Sched, bool ALIGN_EPI = false, bool SP2 = false>
; __device__ __forceinline__ void gemm_phase(PG8_LAS unsigned char* lds, const Gemm g, const Sched& S, const Epi& E, const int wave0) {
;     ...
;         for (int t = 0; t < nt; t += 2) {
;             const bool last = (t == nt - 2);
;     ...
;             PG8_LDA(At, 1, 1); PG8_STAGE(PG8_SB(1, 0), b3, voffB); PG8_STAGE(PG8_SB(1, 1), b3 + hstepB, voffB); PG8_STAGE(PG8_SA(1, 0), a3, voffA);
;             PG8_WAIT_V(8); PG8_WAIT_L(0); PG8_BAR; PG8_MMA(1, 0, At, B0); PG8_MMA(1, 1, At, B1); PG8_BAR; PG8_SCHED;
	s_add_i32 s18, s43, s20
	s_add_u32 s48, s16, 0x80
	s_addc_u32 s49, s17, 0
	s_mov_b32 m0, s18
	ds_read_b128 v[194:197], v143 offset:49152
	ds_read_b128 v[208:211], v143 offset:50176
	ds_read_b128 v[212:215], v143 offset:51200
	ds_read_b128 v[216:219], v143 offset:52224
	ds_read_b128 v[220:223], v143 offset:53248
	ds_read_b128 v[224:227], v143 offset:54272
	ds_read_b128 v[228:231], v143 offset:55296
	ds_read_b128 v[232:235], v143 offset:56320
	global_load_lds_dwordx4 v64, s[48:49]
	s_add_i32 m0, s18, 0x2000
	s_add_u32 s16, s16, 0x200080
	s_addc_u32 s17, s17, 0
	s_add_i32 s18, s44, s20
	global_load_lds_dwordx4 v130, s[48:49]
	s_mov_b32 m0, s18
	s_nop 0
	global_load_lds_dwordx4 v64, s[16:17]
	s_add_i32 m0, s18, 0x2000
	s_nop 0
	global_load_lds_dwordx4 v130, s[16:17]
	s_add_u32 s100, s100, 0x80
	s_addc_u32 s101, s101, 0
	s_mov_b32 m0, s28
	s_nop 0
	global_load_lds_dwordx4 v134, s[100:101]
	s_mov_b32 m0, s29
	s_nop 0
	global_load_lds_dwordx4 v132, s[100:101]
	s_waitcnt vmcnt(8)
	s_waitcnt lgkmcnt(0)
	s_barrier
	s_setprio 1
	s_waitcnt lgkmcnt(0)
	v_mfma_f32_16x16x32_bf16 v[60:63], v[144:147], v[194:197], v[60:63]
	v_mfma_f32_16x16x32_bf16 v[56:59], v[152:155], v[194:197], v[56:59]
	v_mfma_f32_16x16x32_bf16 v[52:55], v[144:147], v[212:215], v[52:55]
	v_mfma_f32_16x16x32_bf16 v[48:51], v[152:155], v[212:215], v[48:51]
	s_setprio 0
	s_setprio 1
	v_mfma_f32_16x16x32_bf16 v[36:39], v[144:147], v[220:223], v[36:39]
	v_mfma_f32_16x16x32_bf16 v[32:35], v[152:155], v[220:223], v[32:35]
	v_mfma_f32_16x16x32_bf16 v[20:23], v[144:147], v[228:231], v[20:23]
	v_mfma_f32_16x16x32_bf16 v[16:19], v[152:155], v[228:231], v[16:19]
	s_setprio 0
	s_setprio 1
	v_mfma_f32_16x16x32_bf16 v[60:63], v[148:151], v[208:211], v[60:63]
	v_mfma_f32_16x16x32_bf16 v[56:59], v[156:159], v[208:211], v[56:59]
	v_mfma_f32_16x16x32_bf16 v[52:55], v[148:151], v[216:219], v[52:55]
	v_mfma_f32_16x16x32_bf16 v[48:51], v[156:159], v[216:219], v[48:51]
	s_setprio 0
	s_setprio 1
	v_mfma_f32_16x16x32_bf16 v[36:39], v[148:151], v[224:227], v[36:39]
	v_mfma_f32_16x16x32_bf16 v[32:35], v[156:159], v[224:227], v[32:35]
	v_mfma_f32_16x16x32_bf16 v[20:23], v[148:151], v[232:235], v[20:23]
	v_mfma_f32_16x16x32_bf16 v[16:19], v[156:159], v[232:235], v[16:19]
	s_setprio 0
	s_setprio 1
	v_mfma_f32_16x16x32_bf16 v[44:47], v[178:181], v[194:197], v[44:47]
	v_mfma_f32_16x16x32_bf16 v[40:43], v[186:189], v[194:197], v[40:43]
	v_mfma_f32_16x16x32_bf16 v[28:31], v[178:181], v[212:215], v[28:31]
	v_mfma_f32_16x16x32_bf16 v[24:27], v[186:189], v[212:215], v[24:27]
	s_setprio 0
	s_setprio 1
	v_mfma_f32_16x16x32_bf16 v[12:15], v[178:181], v[220:223], v[12:15]
	v_mfma_f32_16x16x32_bf16 v[8:11], v[186:189], v[220:223], v[8:11]
	v_mfma_f32_16x16x32_bf16 v[4:7], v[178:181], v[228:231], v[4:7]
	v_mfma_f32_16x16x32_bf16 v[0:3], v[186:189], v[228:231], v[0:3]
	s_setprio 0
	s_setprio 1
	v_mfma_f32_16x16x32_bf16 v[44:47], v[182:185], v[208:211], v[44:47]
	v_mfma_f32_16x16x32_bf16 v[40:43], v[190:193], v[208:211], v[40:43]
	v_mfma_f32_16x16x32_bf16 v[28:31], v[182:185], v[216:219], v[28:31]
	v_mfma_f32_16x16x32_bf16 v[24:27], v[190:193], v[216:219], v[24:27]
	s_setprio 0
	s_setprio 1
	v_mfma_f32_16x16x32_bf16 v[12:15], v[182:185], v[224:227], v[12:15]
	v_mfma_f32_16x16x32_bf16 v[8:11], v[190:193], v[224:227], v[8:11]
	v_mfma_f32_16x16x32_bf16 v[4:7], v[182:185], v[232:235], v[4:7]
	v_mfma_f32_16x16x32_bf16 v[0:3], v[190:193], v[232:235], v[0:3]
	s_setprio 0
	s_barrier
	s_add_i32 s42, s42, 2
	s_add_u32 s0, s0, 0x100
	s_addc_u32 s1, s1, 0
	s_add_u32 s36, s36, 0x100
	s_addc_u32 s37, s37, 0
	s_cmpk_gt_u32 s42, 0x7d
	s_cbranch_scc0 .LBB0_1685
	s_mov_b64 s[48:49], 0x80
	s_and_b64 vcc, exec, s[6:7]
	s_mov_b64 s[34:35], 0x45000
	s_cbranch_vccz .LBB0_1688
	s_barrier

; #define PG8_STAGE(bufoff, gbase, voff) do { _Pragma("unroll") for (int _i = 0; _i < 2; ++_i) \
;         __builtin_amdgcn_global_load_lds((const unsigned*)((const char*)(gbase) + (voff)[_i]), (PG8_LAS unsigned*)(lds + (bufoff) + ldsw + _i * 8192), 16, 0, 0); } while (0)
; #define PG8_LDA(dst, b, h) do { _Pragma("unroll") for (int m = 0; m < 4; ++m) _Pragma("unroll") for (int k = 0; k < 2; ++k) dst[m][k] = *(const PG8_LAS bf16x8*)(lds + PG8_SA(b, h) + aoff + m * 2048 + k * 1024); } while (0)
; #define PG8_LDB(dst, b, h) do { _Pragma("unroll") for (int n = 0; n < 2; ++n) _Pragma("unroll") for (int k = 0; k < 2; ++k) dst[n][k] = *(const PG8_LAS bf16x8*)(lds + PG8_SB(b, h) + boff + n * 2048 + k * 1024); } while (0)
; #define PG8_MMA(ai, bj, At, Bt) do { __builtin_amdgcn_s_setprio(1); _Pragma("unroll") for (int m = 0; m < 4; ++m) _Pragma("unroll") for (int n = 0; n < 2; ++n) _Pragma("unroll") for (int k = 0; k < 2; ++k) \
;         acc[ai][bj][m][n] = __builtin_amdgcn_mfma_f32_16x16x32_bf16(Bt[n][k], At[m][k], acc[ai][bj][m][n], 0, 0, 0); __builtin_amdgcn_s_setprio(0); } while (0)
; #define PG8_WAIT_V(n) asm volatile("s_waitcnt vmcnt(" #n ")" ::: "memory")
; #define PG8_BAR __builtin_amdgcn_s_barrier()
; template <class Epi, class Sched, bool ALIGN_EPI = false, bool SP2 = false>
; __device__ __forceinline__ void gemm_phase(PG8_LAS unsigned char* lds, const Gemm g, const Sched& S, const Epi& E, const int wave0) {
;     ...
;         for (int t = 0; t < nt; t += 2) {
;             const bool last = (t == nt - 2);
;             const char* a1 = cA + (size_t)(t + 1) * kstep;
;             const char* a2 = last ? nA : cA + (size_t)(t + 2) * kstep; const char* b2 = last ? nB : cB + (size_t)(t + 2) * kstep;
;             const char* a3 = a2 + kstep; const char* b3 = b2 + kstep;
;             if (last && has_next) S.a_ready(nxt);
;             if constexpr (SP2) {
;             PG8_LDB(B0, 0, 0); PG8_LDB(B1, 0, 1); PG8_SCHED; PG8_LDA(At, 0, 0); PG8_STAGE(PG8_SA(1, 1), a1 + hstepA, voffA);
;             PG8_WAIT_V(8); PG8_WAIT_L(0); PG8_BAR; PG8_MMA(0, 0, At, B0); PG8_MMA(0, 1, At, B1); PG8_BAR; PG8_SCHED;
;             PG8_LDA(At, 0, 1); PG8_STAGE(PG8_SB(0, 0), b2, voffB); PG8_STAGE(PG8_SB(0, 1), b2 + hstepB, voffB); PG8_STAGE(PG8_SA(0, 0), a2, voffA);
;             PG8_WAIT_V(8); PG8_WAIT_L(0); PG8_BAR; PG8_MMA(1, 0, At, B0); PG8_MMA(1, 1, At, B1); PG8_BAR; PG8_SCHED;
.LBB0_1702:
	s_add_u32 s18, s16, 0xffe00080
	s_addc_u32 s19, s17, -1
	s_add_i32 s44, 0, 0x10000
	s_cmp_eq_u32 s43, 12
	s_cselect_b32 s21, s9, s19
	s_cselect_b32 s20, s11, s18
	s_cselect_b32 s19, s13, s42
	s_cselect_b32 s18, s38, s39
	s_add_i32 s46, 0, 0x14000
	ds_read_b128 v[144:147], v252
	ds_read_b128 v[148:151], v252 offset:1024
	ds_read_b128 v[152:155], v252 offset:2048
	ds_read_b128 v[156:159], v252 offset:3072
	ds_read_b128 v[178:181], v253
	ds_read_b128 v[182:185], v253 offset:1024
	ds_read_b128 v[186:189], v253 offset:2048
	ds_read_b128 v[190:193], v253 offset:3072
	s_add_i32 m0, s28, 0xc000
	ds_read_b128 v[194:197], v143
	ds_read_b128 v[208:211], v143 offset:1024
	ds_read_b128 v[212:215], v143 offset:2048
	ds_read_b128 v[216:219], v143 offset:3072
	ds_read_b128 v[220:223], v143 offset:4096
	ds_read_b128 v[224:227], v143 offset:5120
	ds_read_b128 v[228:231], v143 offset:6144
	ds_read_b128 v[232:235], v143 offset:7168
	global_load_lds_dwordx4 v136, s[16:17]
	s_add_i32 m0, s28, 0xe000
	s_nop 0
	global_load_lds_dwordx4 v138, s[16:17]
	s_waitcnt vmcnt(8)
	s_waitcnt lgkmcnt(0)
	s_barrier
	s_setprio 1
	s_waitcnt lgkmcnt(0)
	v_mfma_f32_16x16x32_bf16 v[126:129], v[144:147], v[194:197], v[126:129]
	v_mfma_f32_16x16x32_bf16 v[122:125], v[152:155], v[194:197], v[122:125]
	v_mfma_f32_16x16x32_bf16 v[118:121], v[144:147], v[212:215], v[118:121]
	v_mfma_f32_16x16x32_bf16 v[114:117], v[152:155], v[212:215], v[114:117]
	s_setprio 0
	s_setprio 1
	v_mfma_f32_16x16x32_bf16 v[102:105], v[144:147], v[220:223], v[102:105]
	v_mfma_f32_16x16x32_bf16 v[98:101], v[152:155], v[220:223], v[98:101]
	v_mfma_f32_16x16x32_bf16 v[86:89], v[144:147], v[228:231], v[86:89]
	v_mfma_f32_16x16x32_bf16 v[82:85], v[152:155], v[228:231], v[82:85]
	s_setprio 0
	s_setprio 1
	v_mfma_f32_16x16x32_bf16 v[126:129], v[148:151], v[208:211], v[126:129]
	v_mfma_f32_16x16x32_bf16 v[122:125], v[156:159], v[208:211], v[122:125]
	v_mfma_f32_16x16x32_bf16 v[118:121], v[148:151], v[216:219], v[118:121]
	v_mfma_f32_16x16x32_bf16 v[114:117], v[156:159], v[216:219], v[114:117]
	s_setprio 0
	s_setprio 1
	v_mfma_f32_16x16x32_bf16 v[102:105], v[148:151], v[224:227], v[102:105]
	v_mfma_f32_16x16x32_bf16 v[98:101], v[156:159], v[224:227], v[98:101]
	v_mfma_f32_16x16x32_bf16 v[86:89], v[148:151], v[232:235], v[86:89]
	v_mfma_f32_16x16x32_bf16 v[82:85], v[156:159], v[232:235], v[82:85]
	s_setprio 0
	s_setprio 1
	v_mfma_f32_16x16x32_bf16 v[110:113], v[178:181], v[194:197], v[110:113]
	v_mfma_f32_16x16x32_bf16 v[106:109], v[186:189], v[194:197], v[106:109]
	v_mfma_f32_16x16x32_bf16 v[94:97], v[178:181], v[212:215], v[94:97]
	v_mfma_f32_16x16x32_bf16 v[90:93], v[186:189], v[212:215], v[90:93]
	s_setprio 0
	s_setprio 1
	v_mfma_f32_16x16x32_bf16 v[78:81], v[178:181], v[220:223], v[78:81]
	v_mfma_f32_16x16x32_bf16 v[74:77], v[186:189], v[220:223], v[74:77]
	v_mfma_f32_16x16x32_bf16 v[70:73], v[178:181], v[228:231], v[70:73]
	v_mfma_f32_16x16x32_bf16 v[66:69], v[186:189], v[228:231], v[66:69]
	s_setprio 0
	s_setprio 1
	v_mfma_f32_16x16x32_bf16 v[110:113], v[182:185], v[208:211], v[110:113]
	v_mfma_f32_16x16x32_bf16 v[106:109], v[190:193], v[208:211], v[106:109]
	v_mfma_f32_16x16x32_bf16 v[94:97], v[182:185], v[216:219], v[94:97]
	v_mfma_f32_16x16x32_bf16 v[90:93], v[190:193], v[216:219], v[90:93]
	s_setprio 0
	s_setprio 1
	v_mfma_f32_16x16x32_bf16 v[78:81], v[182:185], v[224:227], v[78:81]
	v_mfma_f32_16x16x32_bf16 v[74:77], v[190:193], v[224:227], v[74:77]
	v_mfma_f32_16x16x32_bf16 v[70:73], v[182:185], v[232:235], v[70:73]
	v_mfma_f32_16x16x32_bf16 v[66:69], v[190:193], v[232:235], v[66:69]
	s_setprio 0
	s_barrier
	s_add_i32 s44, s44, s25
	s_mov_b32 m0, s44
	ds_read_b128 v[194:197], v143 offset:16384
	ds_read_b128 v[208:211], v143 offset:17408
	ds_read_b128 v[212:215], v143 offset:18432
	ds_read_b128 v[216:219], v143 offset:19456
	ds_read_b128 v[220:223], v143 offset:20480
	ds_read_b128 v[224:227], v143 offset:21504
	ds_read_b128 v[228:231], v143 offset:22528
	ds_read_b128 v[232:235], v143 offset:23552
	global_load_lds_dwordx4 v64, s[18:19]
	s_add_i32 m0, s44, 0x2000
	s_add_u32 s44, s18, 0x200000
	s_addc_u32 s45, s19, 0
	s_add_i32 s46, s46, s25
	global_load_lds_dwordx4 v130, s[18:19]
	s_mov_b32 m0, s46
	s_mov_b64 s[100:101], s[20:21]
	global_load_lds_dwordx4 v64, s[44:45]
	s_add_i32 m0, s46, 0x2000
	s_nop 0
	global_load_lds_dwordx4 v130, s[44:45]
	s_mov_b32 m0, s28
	s_nop 0
	global_load_lds_dwordx4 v134, s[20:21]
	s_mov_b32 m0, s29
	s_nop 0
	global_load_lds_dwordx4 v132, s[20:21]
	s_waitcnt vmcnt(8)
	s_waitcnt lgkmcnt(0)
	s_barrier
; #define PG8_STAGE(bufoff, gbase, voff) do { _Pragma("unroll") for (int _i = 0; _i < 2; ++_i) \
;         __builtin_amdgcn_global_load_lds((const unsigned*)((const char*)(gbase) + (voff)[_i]), (PG8_LAS unsigned*)(lds + (bufoff) + ldsw + _i * 8192), 16, 0, 0); } while (0)
; #define PG8_LDA(dst, b, h) do { _Pragma("unroll") for (int m = 0; m < 4; ++m) _Pragma("unroll") for (int k = 0; k < 2; ++k) dst[m][k] = *(const PG8_LAS bf16x8*)(lds + PG8_SA(b, h) + aoff + m * 2048 + k * 1024); } while (0)
; #define PG8_LDB(dst, b, h) do { _Pragma("unroll") for (int n = 0; n < 2; ++n) _Pragma("unroll") for (int k = 0; k < 2; ++k) dst[n][k] = *(const PG8_LAS bf16x8*)(lds + PG8_SB(b, h) + boff + n * 2048 + k * 1024); } while (0)
; #define PG8_MMA(ai, bj, At, Bt) do { __builtin_amdgcn_s_setprio(1); _Pragma("unroll") for (int m = 0; m < 4; ++m) _Pragma("unroll") for (int n = 0; n < 2; ++n) _Pragma("unroll") for (int k = 0; k < 2; ++k) \
;         acc[ai][bj][m][n] = __builtin_amdgcn_mfma_f32_16x16x32_bf16(Bt[n][k], At[m][k], acc[ai][bj][m][n], 0, 0, 0); __builtin_amdgcn_s_setprio(0); } while (0)
; #define PG8_WAIT_V(n) asm volatile("s_waitcnt vmcnt(" #n ")" ::: "memory")
; #define PG8_WAIT_L(n) asm volatile("s_waitcnt lgkmcnt(" #n ")" ::: "memory")
; #define PG8_BAR __builtin_amdgcn_s_barrier()
; #define PG8_SCHED __builtin_amdgcn_sched_barrier(0)
; template <class Epi, class Sched, bool ALIGN_EPI = false, bool SP2 = false>
; __device__ __forceinline__ void gemm_phase(PG8_LAS unsigned char* lds, const Gemm g, const Sched& S, const Epi& E, const int wave0) {
;     ...
;             PG8_WAIT_V(8); PG8_WAIT_L(0); PG8_BAR; PG8_MMA(0, 0, At, B0); PG8_MMA(0, 1, At, B1); PG8_BAR; PG8_SCHED;
;             PG8_LDA(At, 0, 1); PG8_STAGE(PG8_SB(0, 0), b2, voffB); PG8_STAGE(PG8_SB(0, 1), b2 + hstepB, voffB); PG8_STAGE(PG8_SA(0, 0), a2, voffA);
;             PG8_WAIT_V(8); PG8_WAIT_L(0); PG8_BAR; PG8_MMA(1, 0, At, B0); PG8_MMA(1, 1, At, B1); PG8_BAR; PG8_SCHED;
;             PG8_LDB(B0, 1, 0); PG8_LDB(B1, 1, 1); PG8_SCHED; PG8_LDA(At, 1, 0); PG8_STAGE(PG8_SA(0, 1), a2 + hstepA, voffA);
;             PG8_WAIT_V(8); PG8_WAIT_L(0); PG8_BAR; PG8_MMA(0, 0, At, B0); PG8_MMA(0, 1, At, B1); PG8_BAR; PG8_SCHED;
	s_setprio 1
	s_waitcnt lgkmcnt(0)
	v_mfma_f32_16x16x32_bf16 v[60:63], v[144:147], v[194:197], v[60:63]
	v_mfma_f32_16x16x32_bf16 v[56:59], v[152:155], v[194:197], v[56:59]
	v_mfma_f32_16x16x32_bf16 v[52:55], v[144:147], v[212:215], v[52:55]
	v_mfma_f32_16x16x32_bf16 v[48:51], v[152:155], v[212:215], v[48:51]
	s_setprio 0
	s_setprio 1
	v_mfma_f32_16x16x32_bf16 v[36:39], v[144:147], v[220:223], v[36:39]
	v_mfma_f32_16x16x32_bf16 v[32:35], v[152:155], v[220:223], v[32:35]
	v_mfma_f32_16x16x32_bf16 v[20:23], v[144:147], v[228:231], v[20:23]
	v_mfma_f32_16x16x32_bf16 v[16:19], v[152:155], v[228:231], v[16:19]
	s_setprio 0
	s_setprio 1
	v_mfma_f32_16x16x32_bf16 v[60:63], v[148:151], v[208:211], v[60:63]
	v_mfma_f32_16x16x32_bf16 v[56:59], v[156:159], v[208:211], v[56:59]
	v_mfma_f32_16x16x32_bf16 v[52:55], v[148:151], v[216:219], v[52:55]
	v_mfma_f32_16x16x32_bf16 v[48:51], v[156:159], v[216:219], v[48:51]
	s_setprio 0
	s_setprio 1
	v_mfma_f32_16x16x32_bf16 v[36:39], v[148:151], v[224:227], v[36:39]
	v_mfma_f32_16x16x32_bf16 v[32:35], v[156:159], v[224:227], v[32:35]
	v_mfma_f32_16x16x32_bf16 v[20:23], v[148:151], v[232:235], v[20:23]
	v_mfma_f32_16x16x32_bf16 v[16:19], v[156:159], v[232:235], v[16:19]
	s_setprio 0
	s_setprio 1
	v_mfma_f32_16x16x32_bf16 v[44:47], v[178:181], v[194:197], v[44:47]
	v_mfma_f32_16x16x32_bf16 v[40:43], v[186:189], v[194:197], v[40:43]
	v_mfma_f32_16x16x32_bf16 v[28:31], v[178:181], v[212:215], v[28:31]
	v_mfma_f32_16x16x32_bf16 v[24:27], v[186:189], v[212:215], v[24:27]
	s_setprio 0
	s_setprio 1
	v_mfma_f32_16x16x32_bf16 v[12:15], v[178:181], v[220:223], v[12:15]
	v_mfma_f32_16x16x32_bf16 v[8:11], v[186:189], v[220:223], v[8:11]
	v_mfma_f32_16x16x32_bf16 v[4:7], v[178:181], v[228:231], v[4:7]
	v_mfma_f32_16x16x32_bf16 v[0:3], v[186:189], v[228:231], v[0:3]
	s_setprio 0
	s_setprio 1
	v_mfma_f32_16x16x32_bf16 v[44:47], v[182:185], v[208:211], v[44:47]
	v_mfma_f32_16x16x32_bf16 v[40:43], v[190:193], v[208:211], v[40:43]
	v_mfma_f32_16x16x32_bf16 v[28:31], v[182:185], v[216:219], v[28:31]
	v_mfma_f32_16x16x32_bf16 v[24:27], v[190:193], v[216:219], v[24:27]
	s_setprio 0
	s_setprio 1
	v_mfma_f32_16x16x32_bf16 v[12:15], v[182:185], v[224:227], v[12:15]
	v_mfma_f32_16x16x32_bf16 v[8:11], v[190:193], v[224:227], v[8:11]
	v_mfma_f32_16x16x32_bf16 v[4:7], v[182:185], v[232:235], v[4:7]
	v_mfma_f32_16x16x32_bf16 v[0:3], v[190:193], v[232:235], v[0:3]
	s_setprio 0
	s_barrier
	s_add_i32 s44, 0, 0x18000
	s_add_i32 s45, 0, 0x1c000
	ds_read_b128 v[144:147], v254
	ds_read_b128 v[148:151], v254 offset:1024
	ds_read_b128 v[152:155], v254 offset:2048
	ds_read_b128 v[156:159], v254 offset:3072
	ds_read_b128 v[178:181], v255
	ds_read_b128 v[182:185], v255 offset:1024
	ds_read_b128 v[186:189], v255 offset:2048
	ds_read_b128 v[190:193], v255 offset:3072
	s_add_u32 s20, s20, 0x200000
	s_addc_u32 s21, s21, 0
	s_mov_b32 m0, s30
	ds_read_b128 v[194:197], v143 offset:32768
	ds_read_b128 v[208:211], v143 offset:33792
	ds_read_b128 v[212:215], v143 offset:34816
	ds_read_b128 v[216:219], v143 offset:35840
	ds_read_b128 v[220:223], v143 offset:36864
	ds_read_b128 v[224:227], v143 offset:37888
	ds_read_b128 v[228:231], v143 offset:38912
	ds_read_b128 v[232:235], v143 offset:39936
	global_load_lds_dwordx4 v134, s[20:21]
	s_mov_b32 m0, s31
	s_nop 0
	global_load_lds_dwordx4 v132, s[20:21]
	s_waitcnt vmcnt(8)
	s_waitcnt lgkmcnt(0)
	s_barrier
	s_setprio 1
	s_waitcnt lgkmcnt(0)
	v_mfma_f32_16x16x32_bf16 v[126:129], v[144:147], v[194:197], v[126:129]
	v_mfma_f32_16x16x32_bf16 v[122:125], v[152:155], v[194:197], v[122:125]
	v_mfma_f32_16x16x32_bf16 v[118:121], v[144:147], v[212:215], v[118:121]
	v_mfma_f32_16x16x32_bf16 v[114:117], v[152:155], v[212:215], v[114:117]
	s_setprio 0
	s_setprio 1
	v_mfma_f32_16x16x32_bf16 v[102:105], v[144:147], v[220:223], v[102:105]
	v_mfma_f32_16x16x32_bf16 v[98:101], v[152:155], v[220:223], v[98:101]
	v_mfma_f32_16x16x32_bf16 v[86:89], v[144:147], v[228:231], v[86:89]
	v_mfma_f32_16x16x32_bf16 v[82:85], v[152:155], v[228:231], v[82:85]
	s_setprio 0
	s_setprio 1
	v_mfma_f32_16x16x32_bf16 v[126:129], v[148:151], v[208:211], v[126:129]
	v_mfma_f32_16x16x32_bf16 v[122:125], v[156:159], v[208:211], v[122:125]
	v_mfma_f32_16x16x32_bf16 v[118:121], v[148:151], v[216:219], v[118:121]
	v_mfma_f32_16x16x32_bf16 v[114:117], v[156:159], v[216:219], v[114:117]
	s_setprio 0
	s_setprio 1
	v_mfma_f32_16x16x32_bf16 v[102:105], v[148:151], v[224:227], v[102:105]
	v_mfma_f32_16x16x32_bf16 v[98:101], v[156:159], v[224:227], v[98:101]
	v_mfma_f32_16x16x32_bf16 v[86:89], v[148:151], v[232:235], v[86:89]
	v_mfma_f32_16x16x32_bf16 v[82:85], v[156:159], v[232:235], v[82:85]
	s_setprio 0
	s_setprio 1
	v_mfma_f32_16x16x32_bf16 v[110:113], v[178:181], v[194:197], v[110:113]
	v_mfma_f32_16x16x32_bf16 v[106:109], v[186:189], v[194:197], v[106:109]
	v_mfma_f32_16x16x32_bf16 v[94:97], v[178:181], v[212:215], v[94:97]
	v_mfma_f32_16x16x32_bf16 v[90:93], v[186:189], v[212:215], v[90:93]
	s_setprio 0
	s_setprio 1
	v_mfma_f32_16x16x32_bf16 v[78:81], v[178:181], v[220:223], v[78:81]
	v_mfma_f32_16x16x32_bf16 v[74:77], v[186:189], v[220:223], v[74:77]
	v_mfma_f32_16x16x32_bf16 v[70:73], v[178:181], v[228:231], v[70:73]
	v_mfma_f32_16x16x32_bf16 v[66:69], v[186:189], v[228:231], v[66:69]
	s_setprio 0
	s_setprio 1
	v_mfma_f32_16x16x32_bf16 v[110:113], v[182:185], v[208:211], v[110:113]
	v_mfma_f32_16x16x32_bf16 v[106:109], v[190:193], v[208:211], v[106:109]
	v_mfma_f32_16x16x32_bf16 v[94:97], v[182:185], v[216:219], v[94:97]
	v_mfma_f32_16x16x32_bf16 v[90:93], v[190:193], v[216:219], v[90:93]
	s_setprio 0
	s_setprio 1
	v_mfma_f32_16x16x32_bf16 v[78:81], v[182:185], v[224:227], v[78:81]
	v_mfma_f32_16x16x32_bf16 v[74:77], v[190:193], v[224:227], v[74:77]
	v_mfma_f32_16x16x32_bf16 v[70:73], v[182:185], v[232:235], v[70:73]
	v_mfma_f32_16x16x32_bf16 v[66:69], v[190:193], v[232:235], v[66:69]
	s_setprio 0
	s_barrier
; #define PG8_STAGE(bufoff, gbase, voff) do { _Pragma("unroll") for (int _i = 0; _i < 2; ++_i) \
;         __builtin_amdgcn_global_load_lds((const unsigned*)((const char*)(gbase) + (voff)[_i]), (PG8_LAS unsigned*)(lds + (bufoff) + ldsw + _i * 8192), 16, 0, 0); } while (0)
; #define PG8_LDA(dst, b, h) do { _Pragma("unroll") for (int m = 0; m < 4; ++m) _Pragma("unroll") for (int k = 0; k < 2; ++k) dst[m][k] = *(const PG8_LAS bf16x8*)(lds + PG8_SA(b, h) + aoff + m * 2048 + k * 1024); } while (0)
; #define PG8_MMA(ai, bj, At, Bt) do { __builtin_amdgcn_s_setprio(1); _Pragma("unroll") for (int m = 0; m < 4; ++m) _Pragma("unroll") for (int n = 0; n < 2; ++n) _Pragma("unroll") for (int k = 0; k < 2; ++k) \
;         acc[ai][bj][m][n] = __builtin_amdgcn_mfma_f32_16x16x32_bf16(Bt[n][k], At[m][k], acc[ai][bj][m][n], 0, 0, 0); __builtin_amdgcn_s_setprio(0); } while (0)
; #define PG8_WAIT_V(n) asm volatile("s_waitcnt vmcnt(" #n ")" ::: "memory")
; #define PG8_WAIT_L(n) asm volatile("s_waitcnt lgkmcnt(" #n ")" ::: "memory")
; #define PG8_BAR __builtin_amdgcn_s_barrier()
; #define PG8_SCHED __builtin_amdgcn_sched_barrier(0)
; template <class Epi, class Sched, bool ALIGN_EPI = false, bool SP2 = false>
; __device__ __forceinline__ void gemm_phase(PG8_LAS unsigned char* lds, const Gemm g, const Sched& S, const Epi& E, const int wave0) {
;     ...
;         for (int t = 0; t < nt; t += 2) {
;             const bool last = (t == nt - 2);
;     ...
;             PG8_LDA(At, 1, 1); PG8_STAGE(PG8_SB(1, 0), b3, voffB); PG8_STAGE(PG8_SB(1, 1), b3 + hstepB, voffB); PG8_STAGE(PG8_SA(1, 0), a3, voffA);
;             PG8_WAIT_V(8); PG8_WAIT_L(0); PG8_BAR; PG8_MMA(1, 0, At, B0); PG8_MMA(1, 1, At, B1); PG8_BAR; PG8_SCHED;
	s_add_i32 s20, s44, s25
	s_add_u32 s48, s18, 0x80
	s_addc_u32 s49, s19, 0
	s_mov_b32 m0, s20
	ds_read_b128 v[194:197], v143 offset:49152
	ds_read_b128 v[208:211], v143 offset:50176
	ds_read_b128 v[212:215], v143 offset:51200
	ds_read_b128 v[216:219], v143 offset:52224
	ds_read_b128 v[220:223], v143 offset:53248
	ds_read_b128 v[224:227], v143 offset:54272
	ds_read_b128 v[228:231], v143 offset:55296
	ds_read_b128 v[232:235], v143 offset:56320
	global_load_lds_dwordx4 v64, s[48:49]
	s_add_i32 m0, s20, 0x2000
	s_add_u32 s18, s18, 0x200080
	s_addc_u32 s19, s19, 0
	s_add_i32 s20, s45, s25
	global_load_lds_dwordx4 v130, s[48:49]
	s_mov_b32 m0, s20
	s_nop 0
	global_load_lds_dwordx4 v64, s[18:19]
	s_add_i32 m0, s20, 0x2000
	s_nop 0
	global_load_lds_dwordx4 v130, s[18:19]
	s_add_u32 s100, s100, 0x80
	s_addc_u32 s101, s101, 0
	s_mov_b32 m0, s33
	s_nop 0
	global_load_lds_dwordx4 v134, s[100:101]
	s_mov_b32 m0, s34
	s_nop 0
	global_load_lds_dwordx4 v132, s[100:101]
	s_waitcnt vmcnt(8)
	s_waitcnt lgkmcnt(0)
	s_barrier
	s_setprio 1
	s_waitcnt lgkmcnt(0)
	v_mfma_f32_16x16x32_bf16 v[60:63], v[144:147], v[194:197], v[60:63]
	v_mfma_f32_16x16x32_bf16 v[56:59], v[152:155], v[194:197], v[56:59]
	v_mfma_f32_16x16x32_bf16 v[52:55], v[144:147], v[212:215], v[52:55]
	v_mfma_f32_16x16x32_bf16 v[48:51], v[152:155], v[212:215], v[48:51]
	s_setprio 0
	s_setprio 1
	v_mfma_f32_16x16x32_bf16 v[36:39], v[144:147], v[220:223], v[36:39]
	v_mfma_f32_16x16x32_bf16 v[32:35], v[152:155], v[220:223], v[32:35]
	v_mfma_f32_16x16x32_bf16 v[20:23], v[144:147], v[228:231], v[20:23]
	v_mfma_f32_16x16x32_bf16 v[16:19], v[152:155], v[228:231], v[16:19]
	s_setprio 0
	s_setprio 1
	v_mfma_f32_16x16x32_bf16 v[60:63], v[148:151], v[208:211], v[60:63]
	v_mfma_f32_16x16x32_bf16 v[56:59], v[156:159], v[208:211], v[56:59]
	v_mfma_f32_16x16x32_bf16 v[52:55], v[148:151], v[216:219], v[52:55]
	v_mfma_f32_16x16x32_bf16 v[48:51], v[156:159], v[216:219], v[48:51]
	s_setprio 0
	s_setprio 1
	v_mfma_f32_16x16x32_bf16 v[36:39], v[148:151], v[224:227], v[36:39]
	v_mfma_f32_16x16x32_bf16 v[32:35], v[156:159], v[224:227], v[32:35]
	v_mfma_f32_16x16x32_bf16 v[20:23], v[148:151], v[232:235], v[20:23]
	v_mfma_f32_16x16x32_bf16 v[16:19], v[156:159], v[232:235], v[16:19]
	s_setprio 0
	s_setprio 1
	v_mfma_f32_16x16x32_bf16 v[44:47], v[178:181], v[194:197], v[44:47]
	v_mfma_f32_16x16x32_bf16 v[40:43], v[186:189], v[194:197], v[40:43]
	v_mfma_f32_16x16x32_bf16 v[28:31], v[178:181], v[212:215], v[28:31]
	v_mfma_f32_16x16x32_bf16 v[24:27], v[186:189], v[212:215], v[24:27]
	s_setprio 0
	s_setprio 1
	v_mfma_f32_16x16x32_bf16 v[12:15], v[178:181], v[220:223], v[12:15]
	v_mfma_f32_16x16x32_bf16 v[8:11], v[186:189], v[220:223], v[8:11]
	v_mfma_f32_16x16x32_bf16 v[4:7], v[178:181], v[228:231], v[4:7]
	v_mfma_f32_16x16x32_bf16 v[0:3], v[186:189], v[228:231], v[0:3]
	s_setprio 0
	s_setprio 1
	v_mfma_f32_16x16x32_bf16 v[44:47], v[182:185], v[208:211], v[44:47]
	v_mfma_f32_16x16x32_bf16 v[40:43], v[190:193], v[208:211], v[40:43]
	v_mfma_f32_16x16x32_bf16 v[28:31], v[182:185], v[216:219], v[28:31]
	v_mfma_f32_16x16x32_bf16 v[24:27], v[190:193], v[216:219], v[24:27]
	s_setprio 0
	s_setprio 1
	v_mfma_f32_16x16x32_bf16 v[12:15], v[182:185], v[224:227], v[12:15]
	v_mfma_f32_16x16x32_bf16 v[8:11], v[190:193], v[224:227], v[8:11]
	v_mfma_f32_16x16x32_bf16 v[4:7], v[182:185], v[232:235], v[4:7]
	v_mfma_f32_16x16x32_bf16 v[0:3], v[190:193], v[232:235], v[0:3]
	s_setprio 0
	s_barrier
	s_add_i32 s43, s43, 2
	s_add_u32 s16, s16, 0x100
	s_addc_u32 s17, s17, 0
	s_add_u32 s39, s39, 0x100
	s_addc_u32 s42, s42, 0
	s_cmp_gt_u32 s43, 13
	s_cbranch_scc0 .LBB0_1702
	s_mov_b64 s[48:49], 0x80
	s_and_b64 vcc, exec, s[6:7]
	s_cbranch_vccz .LBB0_1705
	s_barrier
